# back-edge rotation in the six 64-MFMA K-loops: counter/pointer advance and next-iteration selects moved in front of the closing wait+barrier, per-half loop heads
# baseline (speedup 1.0000x reference)
.Lk64_lead_p1:
	s_sub_u32 vcc_lo, s20, 0x80
	s_subb_u32 vcc_hi, s21, 0
	s_add_i32 m0, s23, 0x18000
	s_nop 0
	global_load_lds_dwordx4 v130, vcc
	s_add_i32 m0, s23, 0x1a000
	s_nop 0
	global_load_lds_dwordx4 v134, vcc
	s_add_u32 vcc_lo, vcc_lo, 0x20000
	s_addc_u32 vcc_hi, vcc_hi, 0
	s_add_i32 m0, s23, 0x19000
	s_nop 0
	global_load_lds_dwordx4 v130, vcc
	s_add_i32 m0, s23, 0x1b000
	s_nop 0
	global_load_lds_dwordx4 v134, vcc
	s_add_u32 vcc_lo, vcc_lo, 0x60000
	s_addc_u32 vcc_hi, vcc_hi, 0
	s_add_i32 m0, s23, 0x1c000
	s_nop 0
	global_load_lds_dwordx4 v130, vcc
	s_add_i32 m0, s23, 0x1e000
	s_nop 0
	global_load_lds_dwordx4 v134, vcc
	s_add_u32 vcc_lo, vcc_lo, 0x20000
	s_addc_u32 vcc_hi, vcc_hi, 0
	s_add_i32 m0, s23, 0x1d000
	s_nop 0
	global_load_lds_dwordx4 v130, vcc
	s_add_i32 m0, s23, 0x1f000
	s_nop 0
	global_load_lds_dwordx4 v134, vcc
	ds_read_b128 v[148:151], v168 offset:0
	ds_read_b128 v[152:155], v168 offset:1024
	ds_read_b128 v[156:159], v168 offset:2048
	ds_read_b128 v[172:175], v168 offset:3072
	ds_read_b128 v[176:179], v169 offset:0
	ds_read_b128 v[180:183], v169 offset:1024
	ds_read_b128 v[184:187], v169 offset:2048
	ds_read_b128 v[188:191], v169 offset:3072
	ds_read_b128 v[192:195], v170 offset:0
	ds_read_b128 v[196:199], v170 offset:1024
	ds_read_b128 v[200:203], v170 offset:2048
	ds_read_b128 v[204:207], v170 offset:3072
	ds_read_b128 v[208:211], v170 offset:4096
	ds_read_b128 v[212:215], v170 offset:5120
	ds_read_b128 v[216:219], v170 offset:6144
	ds_read_b128 v[220:223], v170 offset:7168
	ds_read_b128 v[142:145], v170 offset:16384
	ds_read_b128 v[224:227], v170 offset:17408
	ds_read_b128 v[228:231], v170 offset:18432
	ds_read_b128 v[232:235], v170 offset:19456
	ds_read_b128 v[236:239], v170 offset:20480
	ds_read_b128 v[240:243], v170 offset:21504
	ds_read_b128 v[244:247], v170 offset:22528
	ds_read_b128 v[248:251], v170 offset:23552
	s_nop 15
	s_nop 15
	s_waitcnt lgkmcnt(0)
	s_barrier
	s_setprio 1
	v_mfma_f32_16x16x32_bf16 v[124:127], v[148:151], v[192:195], v[124:127]
	v_mfma_f32_16x16x32_bf16 v[120:123], v[156:159], v[192:195], v[120:123]
	v_mfma_f32_16x16x32_bf16 v[116:119], v[148:151], v[200:203], v[116:119]
	v_mfma_f32_16x16x32_bf16 v[112:115], v[156:159], v[200:203], v[112:115]
	v_mfma_f32_16x16x32_bf16 v[100:103], v[148:151], v[208:211], v[100:103]
	v_mfma_f32_16x16x32_bf16 v[96:99], v[156:159], v[208:211], v[96:99]
	v_mfma_f32_16x16x32_bf16 v[84:87], v[148:151], v[216:219], v[84:87]
	v_mfma_f32_16x16x32_bf16 v[80:83], v[156:159], v[216:219], v[80:83]
	v_mfma_f32_16x16x32_bf16 v[124:127], v[152:155], v[196:199], v[124:127]
	v_mfma_f32_16x16x32_bf16 v[120:123], v[172:175], v[196:199], v[120:123]
	v_mfma_f32_16x16x32_bf16 v[116:119], v[152:155], v[204:207], v[116:119]
	v_mfma_f32_16x16x32_bf16 v[112:115], v[172:175], v[204:207], v[112:115]
	v_mfma_f32_16x16x32_bf16 v[100:103], v[152:155], v[212:215], v[100:103]
	v_mfma_f32_16x16x32_bf16 v[96:99], v[172:175], v[212:215], v[96:99]
	v_mfma_f32_16x16x32_bf16 v[84:87], v[152:155], v[220:223], v[84:87]
	v_mfma_f32_16x16x32_bf16 v[80:83], v[172:175], v[220:223], v[80:83]
	s_setprio 0
	s_setprio 1
	v_mfma_f32_16x16x32_bf16 v[108:111], v[176:179], v[192:195], v[108:111]
	v_mfma_f32_16x16x32_bf16 v[104:107], v[184:187], v[192:195], v[104:107]
	v_mfma_f32_16x16x32_bf16 v[92:95], v[176:179], v[200:203], v[92:95]
	v_mfma_f32_16x16x32_bf16 v[88:91], v[184:187], v[200:203], v[88:91]
	v_mfma_f32_16x16x32_bf16 v[76:79], v[176:179], v[208:211], v[76:79]
	v_mfma_f32_16x16x32_bf16 v[72:75], v[184:187], v[208:211], v[72:75]
	v_mfma_f32_16x16x32_bf16 v[68:71], v[176:179], v[216:219], v[68:71]
	v_mfma_f32_16x16x32_bf16 v[64:67], v[184:187], v[216:219], v[64:67]
	v_mfma_f32_16x16x32_bf16 v[108:111], v[180:183], v[196:199], v[108:111]
	v_mfma_f32_16x16x32_bf16 v[104:107], v[188:191], v[196:199], v[104:107]
	v_mfma_f32_16x16x32_bf16 v[92:95], v[180:183], v[204:207], v[92:95]
	v_mfma_f32_16x16x32_bf16 v[88:91], v[188:191], v[204:207], v[88:91]
	v_mfma_f32_16x16x32_bf16 v[76:79], v[180:183], v[212:215], v[76:79]
	v_mfma_f32_16x16x32_bf16 v[72:75], v[188:191], v[212:215], v[72:75]
	v_mfma_f32_16x16x32_bf16 v[68:71], v[180:183], v[220:223], v[68:71]
	v_mfma_f32_16x16x32_bf16 v[64:67], v[188:191], v[220:223], v[64:67]
	s_setprio 0
	s_setprio 1
	v_mfma_f32_16x16x32_bf16 v[60:63], v[148:151], v[142:145], v[60:63]
	v_mfma_f32_16x16x32_bf16 v[56:59], v[156:159], v[142:145], v[56:59]
	v_mfma_f32_16x16x32_bf16 v[52:55], v[148:151], v[228:231], v[52:55]
	v_mfma_f32_16x16x32_bf16 v[48:51], v[156:159], v[228:231], v[48:51]
	v_mfma_f32_16x16x32_bf16 v[36:39], v[148:151], v[236:239], v[36:39]
	v_mfma_f32_16x16x32_bf16 v[32:35], v[156:159], v[236:239], v[32:35]
	v_mfma_f32_16x16x32_bf16 v[20:23], v[148:151], v[244:247], v[20:23]
	v_mfma_f32_16x16x32_bf16 v[16:19], v[156:159], v[244:247], v[16:19]
	v_mfma_f32_16x16x32_bf16 v[60:63], v[152:155], v[224:227], v[60:63]
	v_mfma_f32_16x16x32_bf16 v[56:59], v[172:175], v[224:227], v[56:59]
	v_mfma_f32_16x16x32_bf16 v[52:55], v[152:155], v[232:235], v[52:55]
	v_mfma_f32_16x16x32_bf16 v[48:51], v[172:175], v[232:235], v[48:51]
	v_mfma_f32_16x16x32_bf16 v[36:39], v[152:155], v[240:243], v[36:39]
	v_mfma_f32_16x16x32_bf16 v[32:35], v[172:175], v[240:243], v[32:35]
	v_mfma_f32_16x16x32_bf16 v[20:23], v[152:155], v[248:251], v[20:23]
	v_mfma_f32_16x16x32_bf16 v[16:19], v[172:175], v[248:251], v[16:19]
	s_setprio 0
	s_setprio 1
	v_mfma_f32_16x16x32_bf16 v[44:47], v[176:179], v[142:145], v[44:47]
	v_mfma_f32_16x16x32_bf16 v[40:43], v[184:187], v[142:145], v[40:43]
	v_mfma_f32_16x16x32_bf16 v[28:31], v[176:179], v[228:231], v[28:31]
	v_mfma_f32_16x16x32_bf16 v[24:27], v[184:187], v[228:231], v[24:27]
	v_mfma_f32_16x16x32_bf16 v[12:15], v[176:179], v[236:239], v[12:15]
	v_mfma_f32_16x16x32_bf16 v[8:11], v[184:187], v[236:239], v[8:11]
	v_mfma_f32_16x16x32_bf16 v[4:7], v[176:179], v[244:247], v[4:7]
	v_mfma_f32_16x16x32_bf16 v[0:3], v[184:187], v[244:247], v[0:3]
	v_mfma_f32_16x16x32_bf16 v[44:47], v[180:183], v[224:227], v[44:47]
	v_mfma_f32_16x16x32_bf16 v[40:43], v[188:191], v[224:227], v[40:43]
	v_mfma_f32_16x16x32_bf16 v[28:31], v[180:183], v[232:235], v[28:31]
	v_mfma_f32_16x16x32_bf16 v[24:27], v[188:191], v[232:235], v[24:27]
	v_mfma_f32_16x16x32_bf16 v[12:15], v[180:183], v[240:243], v[12:15]
	v_mfma_f32_16x16x32_bf16 v[8:11], v[188:191], v[240:243], v[8:11]
	v_mfma_f32_16x16x32_bf16 v[4:7], v[180:183], v[248:251], v[4:7]
	v_mfma_f32_16x16x32_bf16 v[0:3], v[188:191], v[248:251], v[0:3]
	s_setprio 0
	s_waitcnt vmcnt(0)
	s_barrier
	s_add_u32 vcc_lo, s16, 0x0
	s_addc_u32 vcc_hi, s17, 0
	s_add_i32 m0, s23, 0x10000
	s_nop 0
	global_load_lds_dwordx4 v130, vcc
	s_add_i32 m0, s23, 0x12000
	s_nop 0
	global_load_lds_dwordx4 v134, vcc
	s_add_u32 vcc_lo, vcc_lo, 0x20000
	s_addc_u32 vcc_hi, vcc_hi, 0
	s_add_i32 m0, s23, 0x11000
	s_nop 0
	global_load_lds_dwordx4 v130, vcc
	s_add_i32 m0, s23, 0x13000
	s_nop 0
	global_load_lds_dwordx4 v134, vcc
	s_add_u32 vcc_lo, vcc_lo, 0x60000
	s_addc_u32 vcc_hi, vcc_hi, 0
	s_add_i32 m0, s23, 0x14000
	s_nop 0
	global_load_lds_dwordx4 v130, vcc
	s_add_i32 m0, s23, 0x16000
	s_nop 0
	global_load_lds_dwordx4 v134, vcc
	s_add_u32 vcc_lo, vcc_lo, 0x20000
	s_addc_u32 vcc_hi, vcc_hi, 0
	s_add_i32 m0, s23, 0x15000
	s_nop 0
	global_load_lds_dwordx4 v130, vcc
	s_add_i32 m0, s23, 0x17000
	s_nop 0
	global_load_lds_dwordx4 v134, vcc
	ds_read_b128 v[148:151], v168 offset:32768
	ds_read_b128 v[152:155], v168 offset:33792
	ds_read_b128 v[156:159], v168 offset:34816
	ds_read_b128 v[172:175], v168 offset:35840
	ds_read_b128 v[176:179], v169 offset:32768
	ds_read_b128 v[180:183], v169 offset:33792
	ds_read_b128 v[184:187], v169 offset:34816
	ds_read_b128 v[188:191], v169 offset:35840
	ds_read_b128 v[192:195], v170 offset:32768
	ds_read_b128 v[196:199], v170 offset:33792
	ds_read_b128 v[200:203], v170 offset:34816
	ds_read_b128 v[204:207], v170 offset:35840
	ds_read_b128 v[208:211], v170 offset:36864
	ds_read_b128 v[212:215], v170 offset:37888
	ds_read_b128 v[216:219], v170 offset:38912
	ds_read_b128 v[220:223], v170 offset:39936
	ds_read_b128 v[142:145], v170 offset:49152
	ds_read_b128 v[224:227], v170 offset:50176
	ds_read_b128 v[228:231], v170 offset:51200
	ds_read_b128 v[232:235], v170 offset:52224
	ds_read_b128 v[236:239], v170 offset:53248
	ds_read_b128 v[240:243], v170 offset:54272
	ds_read_b128 v[244:247], v170 offset:55296
	ds_read_b128 v[248:251], v170 offset:56320
	s_nop 15
	s_nop 15
	s_waitcnt lgkmcnt(0)
	s_barrier
	s_setprio 1
	v_mfma_f32_16x16x32_bf16 v[124:127], v[148:151], v[192:195], v[124:127]
	v_mfma_f32_16x16x32_bf16 v[120:123], v[156:159], v[192:195], v[120:123]
	v_mfma_f32_16x16x32_bf16 v[116:119], v[148:151], v[200:203], v[116:119]
	v_mfma_f32_16x16x32_bf16 v[112:115], v[156:159], v[200:203], v[112:115]
	v_mfma_f32_16x16x32_bf16 v[100:103], v[148:151], v[208:211], v[100:103]
	v_mfma_f32_16x16x32_bf16 v[96:99], v[156:159], v[208:211], v[96:99]
	v_mfma_f32_16x16x32_bf16 v[84:87], v[148:151], v[216:219], v[84:87]
	v_mfma_f32_16x16x32_bf16 v[80:83], v[156:159], v[216:219], v[80:83]
	v_mfma_f32_16x16x32_bf16 v[124:127], v[152:155], v[196:199], v[124:127]
	v_mfma_f32_16x16x32_bf16 v[120:123], v[172:175], v[196:199], v[120:123]
	v_mfma_f32_16x16x32_bf16 v[116:119], v[152:155], v[204:207], v[116:119]
	v_mfma_f32_16x16x32_bf16 v[112:115], v[172:175], v[204:207], v[112:115]
	v_mfma_f32_16x16x32_bf16 v[100:103], v[152:155], v[212:215], v[100:103]
	v_mfma_f32_16x16x32_bf16 v[96:99], v[172:175], v[212:215], v[96:99]
	v_mfma_f32_16x16x32_bf16 v[84:87], v[152:155], v[220:223], v[84:87]
	v_mfma_f32_16x16x32_bf16 v[80:83], v[172:175], v[220:223], v[80:83]
	s_setprio 0
	s_setprio 1
	v_mfma_f32_16x16x32_bf16 v[108:111], v[176:179], v[192:195], v[108:111]
	v_mfma_f32_16x16x32_bf16 v[104:107], v[184:187], v[192:195], v[104:107]
	v_mfma_f32_16x16x32_bf16 v[92:95], v[176:179], v[200:203], v[92:95]
	v_mfma_f32_16x16x32_bf16 v[88:91], v[184:187], v[200:203], v[88:91]
	v_mfma_f32_16x16x32_bf16 v[76:79], v[176:179], v[208:211], v[76:79]
	v_mfma_f32_16x16x32_bf16 v[72:75], v[184:187], v[208:211], v[72:75]
	v_mfma_f32_16x16x32_bf16 v[68:71], v[176:179], v[216:219], v[68:71]
	v_mfma_f32_16x16x32_bf16 v[64:67], v[184:187], v[216:219], v[64:67]
	v_mfma_f32_16x16x32_bf16 v[108:111], v[180:183], v[196:199], v[108:111]
	v_mfma_f32_16x16x32_bf16 v[104:107], v[188:191], v[196:199], v[104:107]
	v_mfma_f32_16x16x32_bf16 v[92:95], v[180:183], v[204:207], v[92:95]
	v_mfma_f32_16x16x32_bf16 v[88:91], v[188:191], v[204:207], v[88:91]
	v_mfma_f32_16x16x32_bf16 v[76:79], v[180:183], v[212:215], v[76:79]
	v_mfma_f32_16x16x32_bf16 v[72:75], v[188:191], v[212:215], v[72:75]
	v_mfma_f32_16x16x32_bf16 v[68:71], v[180:183], v[220:223], v[68:71]
	v_mfma_f32_16x16x32_bf16 v[64:67], v[188:191], v[220:223], v[64:67]
	s_setprio 0
	s_setprio 1
	v_mfma_f32_16x16x32_bf16 v[60:63], v[148:151], v[142:145], v[60:63]
	v_mfma_f32_16x16x32_bf16 v[56:59], v[156:159], v[142:145], v[56:59]
	v_mfma_f32_16x16x32_bf16 v[52:55], v[148:151], v[228:231], v[52:55]
	v_mfma_f32_16x16x32_bf16 v[48:51], v[156:159], v[228:231], v[48:51]
	v_mfma_f32_16x16x32_bf16 v[36:39], v[148:151], v[236:239], v[36:39]
	v_mfma_f32_16x16x32_bf16 v[32:35], v[156:159], v[236:239], v[32:35]
	v_mfma_f32_16x16x32_bf16 v[20:23], v[148:151], v[244:247], v[20:23]
	v_mfma_f32_16x16x32_bf16 v[16:19], v[156:159], v[244:247], v[16:19]
	v_mfma_f32_16x16x32_bf16 v[60:63], v[152:155], v[224:227], v[60:63]
	v_mfma_f32_16x16x32_bf16 v[56:59], v[172:175], v[224:227], v[56:59]
	v_mfma_f32_16x16x32_bf16 v[52:55], v[152:155], v[232:235], v[52:55]
	v_mfma_f32_16x16x32_bf16 v[48:51], v[172:175], v[232:235], v[48:51]
	v_mfma_f32_16x16x32_bf16 v[36:39], v[152:155], v[240:243], v[36:39]
	v_mfma_f32_16x16x32_bf16 v[32:35], v[172:175], v[240:243], v[32:35]
	v_mfma_f32_16x16x32_bf16 v[20:23], v[152:155], v[248:251], v[20:23]
	v_mfma_f32_16x16x32_bf16 v[16:19], v[172:175], v[248:251], v[16:19]
	s_setprio 0
	s_setprio 1
	v_mfma_f32_16x16x32_bf16 v[44:47], v[176:179], v[142:145], v[44:47]
	v_mfma_f32_16x16x32_bf16 v[40:43], v[184:187], v[142:145], v[40:43]
	v_mfma_f32_16x16x32_bf16 v[28:31], v[176:179], v[228:231], v[28:31]
	v_mfma_f32_16x16x32_bf16 v[24:27], v[184:187], v[228:231], v[24:27]
	v_mfma_f32_16x16x32_bf16 v[12:15], v[176:179], v[236:239], v[12:15]
	v_mfma_f32_16x16x32_bf16 v[8:11], v[184:187], v[236:239], v[8:11]
	v_mfma_f32_16x16x32_bf16 v[4:7], v[176:179], v[244:247], v[4:7]
	v_mfma_f32_16x16x32_bf16 v[0:3], v[184:187], v[244:247], v[0:3]
	v_mfma_f32_16x16x32_bf16 v[44:47], v[180:183], v[224:227], v[44:47]
	v_mfma_f32_16x16x32_bf16 v[40:43], v[188:191], v[224:227], v[40:43]
	v_mfma_f32_16x16x32_bf16 v[28:31], v[180:183], v[232:235], v[28:31]
	v_mfma_f32_16x16x32_bf16 v[24:27], v[188:191], v[232:235], v[24:27]
	v_mfma_f32_16x16x32_bf16 v[12:15], v[180:183], v[240:243], v[12:15]
	v_mfma_f32_16x16x32_bf16 v[8:11], v[188:191], v[240:243], v[8:11]
	v_mfma_f32_16x16x32_bf16 v[4:7], v[180:183], v[248:251], v[4:7]
	v_mfma_f32_16x16x32_bf16 v[0:3], v[188:191], v[248:251], v[0:3]
	s_setprio 0
	s_add_i32 s64, s64, 2
	s_add_u32 s14, s14, 0x100
	s_addc_u32 s15, s15, 0
	s_add_u32 s20, s20, 0x100
	s_addc_u32 s21, s21, 0
	s_add_u32 s16, s14, 0xfff80080
	s_addc_u32 s17, s15, -1
	s_cmp_eq_u32 s64, 28
	s_cselect_b32 s19, s1, s17
	s_cselect_b32 s18, s4, s16
	s_cselect_b32 s17, s11, s21
	s_cselect_b32 s16, s13, s20
	s_cmp_gt_u32 s64, 29
	s_waitcnt vmcnt(0)
	s_barrier
	s_cbranch_scc0 .Lk64_lead_p1
	s_branch .Lk64_done_p1
.Lk64_trail_p1:
	s_sub_u32 vcc_lo, s14, 0x80000
	s_subb_u32 vcc_hi, s15, 0
	s_add_i32 m0, s23, 0xa000
	s_nop 0
	global_load_lds_dwordx4 v132, vcc
	s_add_u32 vcc_lo, vcc_lo, 0x20000
	s_addc_u32 vcc_hi, vcc_hi, 0
	s_add_i32 m0, s23, 0x9000
	s_nop 0
	global_load_lds_dwordx4 v128, vcc
	s_add_u32 vcc_lo, vcc_lo, 0x60000
	s_addc_u32 vcc_hi, vcc_hi, 0
	s_add_i32 m0, s23, 0xe000
	s_nop 0
	global_load_lds_dwordx4 v132, vcc
	s_add_u32 vcc_lo, vcc_lo, 0x20000
	s_addc_u32 vcc_hi, vcc_hi, 0
	s_add_i32 m0, s23, 0xd000
	s_nop 0
	global_load_lds_dwordx4 v128, vcc
	s_add_u32 vcc_lo, s18, 0x0
	s_addc_u32 vcc_hi, s19, 0
	s_mov_b32 m0, s23
	s_nop 0
	global_load_lds_dwordx4 v128, vcc
	s_sub_u32 vcc_lo, vcc_lo, 0x20000
	s_subb_u32 vcc_hi, vcc_hi, 0
	s_sub_i32 m0, s23, 0x1000
	s_nop 0
	global_load_lds_dwordx4 v128, vcc
	s_add_u32 vcc_lo, vcc_lo, 0xa0000
	s_addc_u32 vcc_hi, vcc_hi, 0
	s_add_i32 m0, s23, 0x4000
	s_nop 0
	global_load_lds_dwordx4 v128, vcc
	s_sub_u32 vcc_lo, vcc_lo, 0x20000
	s_subb_u32 vcc_hi, vcc_hi, 0
	s_add_i32 m0, s23, 0x3000
	s_nop 0
	global_load_lds_dwordx4 v128, vcc
	ds_read_b128 v[148:151], v168 offset:0
	ds_read_b128 v[152:155], v168 offset:1024
	ds_read_b128 v[156:159], v168 offset:2048
	ds_read_b128 v[172:175], v168 offset:3072
	ds_read_b128 v[176:179], v169 offset:0
	ds_read_b128 v[180:183], v169 offset:1024
	ds_read_b128 v[184:187], v169 offset:2048
	ds_read_b128 v[188:191], v169 offset:3072
	ds_read_b128 v[192:195], v170 offset:0
	ds_read_b128 v[196:199], v170 offset:1024
	ds_read_b128 v[200:203], v170 offset:2048
	ds_read_b128 v[204:207], v170 offset:3072
	ds_read_b128 v[208:211], v170 offset:4096
	ds_read_b128 v[212:215], v170 offset:5120
	ds_read_b128 v[216:219], v170 offset:6144
	ds_read_b128 v[220:223], v170 offset:7168
	ds_read_b128 v[142:145], v170 offset:16384
	ds_read_b128 v[224:227], v170 offset:17408
	ds_read_b128 v[228:231], v170 offset:18432
	ds_read_b128 v[232:235], v170 offset:19456
	ds_read_b128 v[236:239], v170 offset:20480
	ds_read_b128 v[240:243], v170 offset:21504
	ds_read_b128 v[244:247], v170 offset:22528
	ds_read_b128 v[248:251], v170 offset:23552
	s_nop 15
	s_nop 15
	s_waitcnt lgkmcnt(0)
	s_barrier
	s_setprio 1
	v_mfma_f32_16x16x32_bf16 v[124:127], v[148:151], v[192:195], v[124:127]
	v_mfma_f32_16x16x32_bf16 v[120:123], v[156:159], v[192:195], v[120:123]
	v_mfma_f32_16x16x32_bf16 v[116:119], v[148:151], v[200:203], v[116:119]
	v_mfma_f32_16x16x32_bf16 v[112:115], v[156:159], v[200:203], v[112:115]
	v_mfma_f32_16x16x32_bf16 v[100:103], v[148:151], v[208:211], v[100:103]
	v_mfma_f32_16x16x32_bf16 v[96:99], v[156:159], v[208:211], v[96:99]
	v_mfma_f32_16x16x32_bf16 v[84:87], v[148:151], v[216:219], v[84:87]
	v_mfma_f32_16x16x32_bf16 v[80:83], v[156:159], v[216:219], v[80:83]
	v_mfma_f32_16x16x32_bf16 v[124:127], v[152:155], v[196:199], v[124:127]
	v_mfma_f32_16x16x32_bf16 v[120:123], v[172:175], v[196:199], v[120:123]
	v_mfma_f32_16x16x32_bf16 v[116:119], v[152:155], v[204:207], v[116:119]
	v_mfma_f32_16x16x32_bf16 v[112:115], v[172:175], v[204:207], v[112:115]
	v_mfma_f32_16x16x32_bf16 v[100:103], v[152:155], v[212:215], v[100:103]
	v_mfma_f32_16x16x32_bf16 v[96:99], v[172:175], v[212:215], v[96:99]
	v_mfma_f32_16x16x32_bf16 v[84:87], v[152:155], v[220:223], v[84:87]
	v_mfma_f32_16x16x32_bf16 v[80:83], v[172:175], v[220:223], v[80:83]
	s_setprio 0
	s_setprio 1
	v_mfma_f32_16x16x32_bf16 v[108:111], v[176:179], v[192:195], v[108:111]
	v_mfma_f32_16x16x32_bf16 v[104:107], v[184:187], v[192:195], v[104:107]
	v_mfma_f32_16x16x32_bf16 v[92:95], v[176:179], v[200:203], v[92:95]
	v_mfma_f32_16x16x32_bf16 v[88:91], v[184:187], v[200:203], v[88:91]
	v_mfma_f32_16x16x32_bf16 v[76:79], v[176:179], v[208:211], v[76:79]
	v_mfma_f32_16x16x32_bf16 v[72:75], v[184:187], v[208:211], v[72:75]
	v_mfma_f32_16x16x32_bf16 v[68:71], v[176:179], v[216:219], v[68:71]
	v_mfma_f32_16x16x32_bf16 v[64:67], v[184:187], v[216:219], v[64:67]
	v_mfma_f32_16x16x32_bf16 v[108:111], v[180:183], v[196:199], v[108:111]
	v_mfma_f32_16x16x32_bf16 v[104:107], v[188:191], v[196:199], v[104:107]
	v_mfma_f32_16x16x32_bf16 v[92:95], v[180:183], v[204:207], v[92:95]
	v_mfma_f32_16x16x32_bf16 v[88:91], v[188:191], v[204:207], v[88:91]
	v_mfma_f32_16x16x32_bf16 v[76:79], v[180:183], v[212:215], v[76:79]
	v_mfma_f32_16x16x32_bf16 v[72:75], v[188:191], v[212:215], v[72:75]
	v_mfma_f32_16x16x32_bf16 v[68:71], v[180:183], v[220:223], v[68:71]
	v_mfma_f32_16x16x32_bf16 v[64:67], v[188:191], v[220:223], v[64:67]
	s_setprio 0
	s_setprio 1
	v_mfma_f32_16x16x32_bf16 v[60:63], v[148:151], v[142:145], v[60:63]
	v_mfma_f32_16x16x32_bf16 v[56:59], v[156:159], v[142:145], v[56:59]
	v_mfma_f32_16x16x32_bf16 v[52:55], v[148:151], v[228:231], v[52:55]
	v_mfma_f32_16x16x32_bf16 v[48:51], v[156:159], v[228:231], v[48:51]
	v_mfma_f32_16x16x32_bf16 v[36:39], v[148:151], v[236:239], v[36:39]
	v_mfma_f32_16x16x32_bf16 v[32:35], v[156:159], v[236:239], v[32:35]
	v_mfma_f32_16x16x32_bf16 v[20:23], v[148:151], v[244:247], v[20:23]
	v_mfma_f32_16x16x32_bf16 v[16:19], v[156:159], v[244:247], v[16:19]
	v_mfma_f32_16x16x32_bf16 v[60:63], v[152:155], v[224:227], v[60:63]
	v_mfma_f32_16x16x32_bf16 v[56:59], v[172:175], v[224:227], v[56:59]
	v_mfma_f32_16x16x32_bf16 v[52:55], v[152:155], v[232:235], v[52:55]
	v_mfma_f32_16x16x32_bf16 v[48:51], v[172:175], v[232:235], v[48:51]
	v_mfma_f32_16x16x32_bf16 v[36:39], v[152:155], v[240:243], v[36:39]
	v_mfma_f32_16x16x32_bf16 v[32:35], v[172:175], v[240:243], v[32:35]
	v_mfma_f32_16x16x32_bf16 v[20:23], v[152:155], v[248:251], v[20:23]
	v_mfma_f32_16x16x32_bf16 v[16:19], v[172:175], v[248:251], v[16:19]
	s_setprio 0
	s_setprio 1
	v_mfma_f32_16x16x32_bf16 v[44:47], v[176:179], v[142:145], v[44:47]
	v_mfma_f32_16x16x32_bf16 v[40:43], v[184:187], v[142:145], v[40:43]
	v_mfma_f32_16x16x32_bf16 v[28:31], v[176:179], v[228:231], v[28:31]
	v_mfma_f32_16x16x32_bf16 v[24:27], v[184:187], v[228:231], v[24:27]
	v_mfma_f32_16x16x32_bf16 v[12:15], v[176:179], v[236:239], v[12:15]
	v_mfma_f32_16x16x32_bf16 v[8:11], v[184:187], v[236:239], v[8:11]
	v_mfma_f32_16x16x32_bf16 v[4:7], v[176:179], v[244:247], v[4:7]
	v_mfma_f32_16x16x32_bf16 v[0:3], v[184:187], v[244:247], v[0:3]
	v_mfma_f32_16x16x32_bf16 v[44:47], v[180:183], v[224:227], v[44:47]
	v_mfma_f32_16x16x32_bf16 v[40:43], v[188:191], v[224:227], v[40:43]
	v_mfma_f32_16x16x32_bf16 v[28:31], v[180:183], v[232:235], v[28:31]
	v_mfma_f32_16x16x32_bf16 v[24:27], v[188:191], v[232:235], v[24:27]
	v_mfma_f32_16x16x32_bf16 v[12:15], v[180:183], v[240:243], v[12:15]
	v_mfma_f32_16x16x32_bf16 v[8:11], v[188:191], v[240:243], v[8:11]
	v_mfma_f32_16x16x32_bf16 v[4:7], v[180:183], v[248:251], v[4:7]
	v_mfma_f32_16x16x32_bf16 v[0:3], v[188:191], v[248:251], v[0:3]
	s_setprio 0
	s_waitcnt vmcnt(0)
	s_barrier
	s_add_u32 vcc_lo, s18, 0x0
	s_addc_u32 vcc_hi, s19, 0
	s_add_i32 m0, s23, 0x2000
	s_nop 0
	global_load_lds_dwordx4 v132, vcc
	s_add_u32 vcc_lo, vcc_lo, 0x20000
	s_addc_u32 vcc_hi, vcc_hi, 0
	s_add_i32 m0, s23, 0x1000
	s_nop 0
	global_load_lds_dwordx4 v128, vcc
	s_add_u32 vcc_lo, vcc_lo, 0x60000
	s_addc_u32 vcc_hi, vcc_hi, 0
	s_add_i32 m0, s23, 0x6000
	s_nop 0
	global_load_lds_dwordx4 v132, vcc
	s_add_u32 vcc_lo, vcc_lo, 0x20000
	s_addc_u32 vcc_hi, vcc_hi, 0
	s_add_i32 m0, s23, 0x5000
	s_nop 0
	global_load_lds_dwordx4 v128, vcc
	s_add_u32 vcc_lo, s18, 0x80
	s_addc_u32 vcc_hi, s19, 0
	s_add_i32 m0, s23, 0x8000
	s_nop 0
	global_load_lds_dwordx4 v128, vcc
	s_sub_u32 vcc_lo, vcc_lo, 0x20000
	s_subb_u32 vcc_hi, vcc_hi, 0
	s_add_i32 m0, s23, 0x7000
	s_nop 0
	global_load_lds_dwordx4 v128, vcc
	s_add_u32 vcc_lo, vcc_lo, 0xa0000
	s_addc_u32 vcc_hi, vcc_hi, 0
	s_add_i32 m0, s23, 0xc000
	s_nop 0
	global_load_lds_dwordx4 v128, vcc
	s_sub_u32 vcc_lo, vcc_lo, 0x20000
	s_subb_u32 vcc_hi, vcc_hi, 0
	s_add_i32 m0, s23, 0xb000
	s_nop 0
	global_load_lds_dwordx4 v128, vcc
	ds_read_b128 v[148:151], v168 offset:32768
	ds_read_b128 v[152:155], v168 offset:33792
	ds_read_b128 v[156:159], v168 offset:34816
	ds_read_b128 v[172:175], v168 offset:35840
	ds_read_b128 v[176:179], v169 offset:32768
	ds_read_b128 v[180:183], v169 offset:33792
	ds_read_b128 v[184:187], v169 offset:34816
	ds_read_b128 v[188:191], v169 offset:35840
	ds_read_b128 v[192:195], v170 offset:32768
	ds_read_b128 v[196:199], v170 offset:33792
	ds_read_b128 v[200:203], v170 offset:34816
	ds_read_b128 v[204:207], v170 offset:35840
	ds_read_b128 v[208:211], v170 offset:36864
	ds_read_b128 v[212:215], v170 offset:37888
	ds_read_b128 v[216:219], v170 offset:38912
	ds_read_b128 v[220:223], v170 offset:39936
	ds_read_b128 v[142:145], v170 offset:49152
	ds_read_b128 v[224:227], v170 offset:50176
	ds_read_b128 v[228:231], v170 offset:51200
	ds_read_b128 v[232:235], v170 offset:52224
	ds_read_b128 v[236:239], v170 offset:53248
	ds_read_b128 v[240:243], v170 offset:54272
	ds_read_b128 v[244:247], v170 offset:55296
	ds_read_b128 v[248:251], v170 offset:56320
	s_nop 15
	s_nop 15
	s_waitcnt lgkmcnt(0)
	s_barrier
	s_setprio 1
	v_mfma_f32_16x16x32_bf16 v[124:127], v[148:151], v[192:195], v[124:127]
	v_mfma_f32_16x16x32_bf16 v[120:123], v[156:159], v[192:195], v[120:123]
	v_mfma_f32_16x16x32_bf16 v[116:119], v[148:151], v[200:203], v[116:119]
	v_mfma_f32_16x16x32_bf16 v[112:115], v[156:159], v[200:203], v[112:115]
	v_mfma_f32_16x16x32_bf16 v[100:103], v[148:151], v[208:211], v[100:103]
	v_mfma_f32_16x16x32_bf16 v[96:99], v[156:159], v[208:211], v[96:99]
	v_mfma_f32_16x16x32_bf16 v[84:87], v[148:151], v[216:219], v[84:87]
	v_mfma_f32_16x16x32_bf16 v[80:83], v[156:159], v[216:219], v[80:83]
	v_mfma_f32_16x16x32_bf16 v[124:127], v[152:155], v[196:199], v[124:127]
	v_mfma_f32_16x16x32_bf16 v[120:123], v[172:175], v[196:199], v[120:123]
	v_mfma_f32_16x16x32_bf16 v[116:119], v[152:155], v[204:207], v[116:119]
	v_mfma_f32_16x16x32_bf16 v[112:115], v[172:175], v[204:207], v[112:115]
	v_mfma_f32_16x16x32_bf16 v[100:103], v[152:155], v[212:215], v[100:103]
	v_mfma_f32_16x16x32_bf16 v[96:99], v[172:175], v[212:215], v[96:99]
	v_mfma_f32_16x16x32_bf16 v[84:87], v[152:155], v[220:223], v[84:87]
	v_mfma_f32_16x16x32_bf16 v[80:83], v[172:175], v[220:223], v[80:83]
	s_setprio 0
	s_setprio 1
	v_mfma_f32_16x16x32_bf16 v[108:111], v[176:179], v[192:195], v[108:111]
	v_mfma_f32_16x16x32_bf16 v[104:107], v[184:187], v[192:195], v[104:107]
	v_mfma_f32_16x16x32_bf16 v[92:95], v[176:179], v[200:203], v[92:95]
	v_mfma_f32_16x16x32_bf16 v[88:91], v[184:187], v[200:203], v[88:91]
	v_mfma_f32_16x16x32_bf16 v[76:79], v[176:179], v[208:211], v[76:79]
	v_mfma_f32_16x16x32_bf16 v[72:75], v[184:187], v[208:211], v[72:75]
	v_mfma_f32_16x16x32_bf16 v[68:71], v[176:179], v[216:219], v[68:71]
	v_mfma_f32_16x16x32_bf16 v[64:67], v[184:187], v[216:219], v[64:67]
	v_mfma_f32_16x16x32_bf16 v[108:111], v[180:183], v[196:199], v[108:111]
	v_mfma_f32_16x16x32_bf16 v[104:107], v[188:191], v[196:199], v[104:107]
	v_mfma_f32_16x16x32_bf16 v[92:95], v[180:183], v[204:207], v[92:95]
	v_mfma_f32_16x16x32_bf16 v[88:91], v[188:191], v[204:207], v[88:91]
	v_mfma_f32_16x16x32_bf16 v[76:79], v[180:183], v[212:215], v[76:79]
	v_mfma_f32_16x16x32_bf16 v[72:75], v[188:191], v[212:215], v[72:75]
	v_mfma_f32_16x16x32_bf16 v[68:71], v[180:183], v[220:223], v[68:71]
	v_mfma_f32_16x16x32_bf16 v[64:67], v[188:191], v[220:223], v[64:67]
	s_setprio 0
	s_setprio 1
	v_mfma_f32_16x16x32_bf16 v[60:63], v[148:151], v[142:145], v[60:63]
	v_mfma_f32_16x16x32_bf16 v[56:59], v[156:159], v[142:145], v[56:59]
	v_mfma_f32_16x16x32_bf16 v[52:55], v[148:151], v[228:231], v[52:55]
	v_mfma_f32_16x16x32_bf16 v[48:51], v[156:159], v[228:231], v[48:51]
	v_mfma_f32_16x16x32_bf16 v[36:39], v[148:151], v[236:239], v[36:39]
	v_mfma_f32_16x16x32_bf16 v[32:35], v[156:159], v[236:239], v[32:35]
	v_mfma_f32_16x16x32_bf16 v[20:23], v[148:151], v[244:247], v[20:23]
	v_mfma_f32_16x16x32_bf16 v[16:19], v[156:159], v[244:247], v[16:19]
	v_mfma_f32_16x16x32_bf16 v[60:63], v[152:155], v[224:227], v[60:63]
	v_mfma_f32_16x16x32_bf16 v[56:59], v[172:175], v[224:227], v[56:59]
	v_mfma_f32_16x16x32_bf16 v[52:55], v[152:155], v[232:235], v[52:55]
	v_mfma_f32_16x16x32_bf16 v[48:51], v[172:175], v[232:235], v[48:51]
	v_mfma_f32_16x16x32_bf16 v[36:39], v[152:155], v[240:243], v[36:39]
	v_mfma_f32_16x16x32_bf16 v[32:35], v[172:175], v[240:243], v[32:35]
	v_mfma_f32_16x16x32_bf16 v[20:23], v[152:155], v[248:251], v[20:23]
	v_mfma_f32_16x16x32_bf16 v[16:19], v[172:175], v[248:251], v[16:19]
	s_setprio 0
	s_setprio 1
	v_mfma_f32_16x16x32_bf16 v[44:47], v[176:179], v[142:145], v[44:47]
	v_mfma_f32_16x16x32_bf16 v[40:43], v[184:187], v[142:145], v[40:43]
	v_mfma_f32_16x16x32_bf16 v[28:31], v[176:179], v[228:231], v[28:31]
	v_mfma_f32_16x16x32_bf16 v[24:27], v[184:187], v[228:231], v[24:27]
	v_mfma_f32_16x16x32_bf16 v[12:15], v[176:179], v[236:239], v[12:15]
	v_mfma_f32_16x16x32_bf16 v[8:11], v[184:187], v[236:239], v[8:11]
	v_mfma_f32_16x16x32_bf16 v[4:7], v[176:179], v[244:247], v[4:7]
	v_mfma_f32_16x16x32_bf16 v[0:3], v[184:187], v[244:247], v[0:3]
	v_mfma_f32_16x16x32_bf16 v[44:47], v[180:183], v[224:227], v[44:47]
	v_mfma_f32_16x16x32_bf16 v[40:43], v[188:191], v[224:227], v[40:43]
	v_mfma_f32_16x16x32_bf16 v[28:31], v[180:183], v[232:235], v[28:31]
	v_mfma_f32_16x16x32_bf16 v[24:27], v[188:191], v[232:235], v[24:27]
	v_mfma_f32_16x16x32_bf16 v[12:15], v[180:183], v[240:243], v[12:15]
	v_mfma_f32_16x16x32_bf16 v[8:11], v[188:191], v[240:243], v[8:11]
	v_mfma_f32_16x16x32_bf16 v[4:7], v[180:183], v[248:251], v[4:7]
	v_mfma_f32_16x16x32_bf16 v[0:3], v[188:191], v[248:251], v[0:3]
	s_setprio 0
	s_add_i32 s64, s64, 2
	s_add_u32 s14, s14, 0x100
	s_addc_u32 s15, s15, 0
	s_add_u32 s20, s20, 0x100
	s_addc_u32 s21, s21, 0
	s_add_u32 s16, s14, 0xfff80080
	s_addc_u32 s17, s15, -1
	s_cmp_eq_u32 s64, 28
	s_cselect_b32 s19, s1, s17
	s_cselect_b32 s18, s4, s16
	s_cselect_b32 s17, s11, s21
	s_cselect_b32 s16, s13, s20
	s_cmp_gt_u32 s64, 29
	s_waitcnt vmcnt(0)
	s_barrier
	s_cbranch_scc0 .Lk64_trail_p1

.Lk64_lead_glu:
	s_sub_u32 vcc_lo, s47, 0x80
	s_subb_u32 vcc_hi, s48, 0
	s_add_i32 m0, s28, 0x18000
	s_nop 0
	global_load_lds_dwordx4 v132, vcc
	s_add_i32 m0, s28, 0x1a000
	s_nop 0
	global_load_lds_dwordx4 v128, vcc
	s_add_u32 vcc_lo, vcc_lo, 0x10000
	s_addc_u32 vcc_hi, vcc_hi, 0
	s_add_i32 m0, s28, 0x19000
	s_nop 0
	global_load_lds_dwordx4 v132, vcc
	s_add_i32 m0, s28, 0x1b000
	s_nop 0
	global_load_lds_dwordx4 v128, vcc
	s_add_u32 vcc_lo, vcc_lo, 0x30000
	s_addc_u32 vcc_hi, vcc_hi, 0
	s_add_i32 m0, s28, 0x1c000
	s_nop 0
	global_load_lds_dwordx4 v132, vcc
	s_add_i32 m0, s28, 0x1e000
	s_nop 0
	global_load_lds_dwordx4 v128, vcc
	s_add_u32 vcc_lo, vcc_lo, 0x10000
	s_addc_u32 vcc_hi, vcc_hi, 0
	s_add_i32 m0, s28, 0x1d000
	s_nop 0
	global_load_lds_dwordx4 v132, vcc
	s_add_i32 m0, s28, 0x1f000
	s_nop 0
	global_load_lds_dwordx4 v128, vcc
	ds_read_b128 v[144:147], v151 offset:0
	ds_read_b128 v[154:157], v151 offset:1024
	ds_read_b128 v[158:161], v151 offset:2048
	ds_read_b128 v[162:165], v151 offset:3072
	ds_read_b128 v[166:169], v152 offset:0
	ds_read_b128 v[170:173], v152 offset:1024
	ds_read_b128 v[174:177], v152 offset:2048
	ds_read_b128 v[178:181], v152 offset:3072
	ds_read_b128 v[182:185], v153 offset:0
	ds_read_b128 v[186:189], v153 offset:1024
	ds_read_b128 v[190:193], v153 offset:2048
	ds_read_b128 v[194:197], v153 offset:3072
	ds_read_b128 v[198:201], v153 offset:4096
	ds_read_b128 v[202:205], v153 offset:5120
	ds_read_b128 v[206:209], v153 offset:6144
	ds_read_b128 v[210:213], v153 offset:7168
	ds_read_b128 v[220:223], v153 offset:16384
	ds_read_b128 v[224:227], v153 offset:17408
	ds_read_b128 v[228:231], v153 offset:18432
	ds_read_b128 v[232:235], v153 offset:19456
	ds_read_b128 v[236:239], v153 offset:20480
	ds_read_b128 v[240:243], v153 offset:21504
	ds_read_b128 v[244:247], v153 offset:22528
	ds_read_b128 v[248:251], v153 offset:23552
	s_nop 15
	s_nop 15
	s_waitcnt lgkmcnt(0)
	s_barrier
	s_setprio 1
	v_mfma_f32_16x16x32_bf16 v[124:127], v[144:147], v[182:185], v[124:127]
	v_mfma_f32_16x16x32_bf16 v[120:123], v[158:161], v[182:185], v[120:123]
	v_mfma_f32_16x16x32_bf16 v[108:111], v[144:147], v[190:193], v[108:111]
	v_mfma_f32_16x16x32_bf16 v[104:107], v[158:161], v[190:193], v[104:107]
	v_mfma_f32_16x16x32_bf16 v[92:95], v[144:147], v[198:201], v[92:95]
	v_mfma_f32_16x16x32_bf16 v[88:91], v[158:161], v[198:201], v[88:91]
	v_mfma_f32_16x16x32_bf16 v[76:79], v[144:147], v[206:209], v[76:79]
	v_mfma_f32_16x16x32_bf16 v[72:75], v[158:161], v[206:209], v[72:75]
	v_mfma_f32_16x16x32_bf16 v[124:127], v[154:157], v[186:189], v[124:127]
	v_mfma_f32_16x16x32_bf16 v[120:123], v[162:165], v[186:189], v[120:123]
	v_mfma_f32_16x16x32_bf16 v[108:111], v[154:157], v[194:197], v[108:111]
	v_mfma_f32_16x16x32_bf16 v[104:107], v[162:165], v[194:197], v[104:107]
	v_mfma_f32_16x16x32_bf16 v[92:95], v[154:157], v[202:205], v[92:95]
	v_mfma_f32_16x16x32_bf16 v[88:91], v[162:165], v[202:205], v[88:91]
	v_mfma_f32_16x16x32_bf16 v[76:79], v[154:157], v[210:213], v[76:79]
	v_mfma_f32_16x16x32_bf16 v[72:75], v[162:165], v[210:213], v[72:75]
	s_setprio 0
	s_setprio 1
	v_mfma_f32_16x16x32_bf16 v[116:119], v[166:169], v[182:185], v[116:119]
	v_mfma_f32_16x16x32_bf16 v[112:115], v[174:177], v[182:185], v[112:115]
	v_mfma_f32_16x16x32_bf16 v[100:103], v[166:169], v[190:193], v[100:103]
	v_mfma_f32_16x16x32_bf16 v[96:99], v[174:177], v[190:193], v[96:99]
	v_mfma_f32_16x16x32_bf16 v[84:87], v[166:169], v[198:201], v[84:87]
	v_mfma_f32_16x16x32_bf16 v[80:83], v[174:177], v[198:201], v[80:83]
	v_mfma_f32_16x16x32_bf16 v[68:71], v[166:169], v[206:209], v[68:71]
	v_mfma_f32_16x16x32_bf16 v[64:67], v[174:177], v[206:209], v[64:67]
	v_mfma_f32_16x16x32_bf16 v[116:119], v[170:173], v[186:189], v[116:119]
	v_mfma_f32_16x16x32_bf16 v[112:115], v[178:181], v[186:189], v[112:115]
	v_mfma_f32_16x16x32_bf16 v[100:103], v[170:173], v[194:197], v[100:103]
	v_mfma_f32_16x16x32_bf16 v[96:99], v[178:181], v[194:197], v[96:99]
	v_mfma_f32_16x16x32_bf16 v[84:87], v[170:173], v[202:205], v[84:87]
	v_mfma_f32_16x16x32_bf16 v[80:83], v[178:181], v[202:205], v[80:83]
	v_mfma_f32_16x16x32_bf16 v[68:71], v[170:173], v[210:213], v[68:71]
	v_mfma_f32_16x16x32_bf16 v[64:67], v[178:181], v[210:213], v[64:67]
	s_setprio 0
	s_setprio 1
	v_mfma_f32_16x16x32_bf16 v[60:63], v[144:147], v[220:223], v[60:63]
	v_mfma_f32_16x16x32_bf16 v[56:59], v[158:161], v[220:223], v[56:59]
	v_mfma_f32_16x16x32_bf16 v[44:47], v[144:147], v[228:231], v[44:47]
	v_mfma_f32_16x16x32_bf16 v[40:43], v[158:161], v[228:231], v[40:43]
	v_mfma_f32_16x16x32_bf16 v[28:31], v[144:147], v[236:239], v[28:31]
	v_mfma_f32_16x16x32_bf16 v[24:27], v[158:161], v[236:239], v[24:27]
	v_mfma_f32_16x16x32_bf16 v[12:15], v[144:147], v[244:247], v[12:15]
	v_mfma_f32_16x16x32_bf16 v[8:11], v[158:161], v[244:247], v[8:11]
	v_mfma_f32_16x16x32_bf16 v[60:63], v[154:157], v[224:227], v[60:63]
	v_mfma_f32_16x16x32_bf16 v[56:59], v[162:165], v[224:227], v[56:59]
	v_mfma_f32_16x16x32_bf16 v[44:47], v[154:157], v[232:235], v[44:47]
	v_mfma_f32_16x16x32_bf16 v[40:43], v[162:165], v[232:235], v[40:43]
	v_mfma_f32_16x16x32_bf16 v[28:31], v[154:157], v[240:243], v[28:31]
	v_mfma_f32_16x16x32_bf16 v[24:27], v[162:165], v[240:243], v[24:27]
	v_mfma_f32_16x16x32_bf16 v[12:15], v[154:157], v[248:251], v[12:15]
	v_mfma_f32_16x16x32_bf16 v[8:11], v[162:165], v[248:251], v[8:11]
	s_setprio 0
	s_setprio 1
	v_mfma_f32_16x16x32_bf16 v[52:55], v[166:169], v[220:223], v[52:55]
	v_mfma_f32_16x16x32_bf16 v[48:51], v[174:177], v[220:223], v[48:51]
	v_mfma_f32_16x16x32_bf16 v[36:39], v[166:169], v[228:231], v[36:39]
	v_mfma_f32_16x16x32_bf16 v[32:35], v[174:177], v[228:231], v[32:35]
	v_mfma_f32_16x16x32_bf16 v[20:23], v[166:169], v[236:239], v[20:23]
	v_mfma_f32_16x16x32_bf16 v[16:19], v[174:177], v[236:239], v[16:19]
	v_mfma_f32_16x16x32_bf16 v[4:7], v[166:169], v[244:247], v[4:7]
	v_mfma_f32_16x16x32_bf16 v[0:3], v[174:177], v[244:247], v[0:3]
	v_mfma_f32_16x16x32_bf16 v[52:55], v[170:173], v[224:227], v[52:55]
	v_mfma_f32_16x16x32_bf16 v[48:51], v[178:181], v[224:227], v[48:51]
	v_mfma_f32_16x16x32_bf16 v[36:39], v[170:173], v[232:235], v[36:39]
	v_mfma_f32_16x16x32_bf16 v[32:35], v[178:181], v[232:235], v[32:35]
	v_mfma_f32_16x16x32_bf16 v[20:23], v[170:173], v[240:243], v[20:23]
	v_mfma_f32_16x16x32_bf16 v[16:19], v[178:181], v[240:243], v[16:19]
	v_mfma_f32_16x16x32_bf16 v[4:7], v[170:173], v[248:251], v[4:7]
	v_mfma_f32_16x16x32_bf16 v[0:3], v[178:181], v[248:251], v[0:3]
	s_setprio 0
	s_waitcnt vmcnt(0)
	s_barrier
	s_add_u32 vcc_lo, s24, 0x0
	s_addc_u32 vcc_hi, s25, 0
	s_add_i32 m0, s28, 0x10000
	s_nop 0
	global_load_lds_dwordx4 v132, vcc
	s_add_i32 m0, s28, 0x12000
	s_nop 0
	global_load_lds_dwordx4 v128, vcc
	s_add_u32 vcc_lo, vcc_lo, 0x10000
	s_addc_u32 vcc_hi, vcc_hi, 0
	s_add_i32 m0, s28, 0x11000
	s_nop 0
	global_load_lds_dwordx4 v132, vcc
	s_add_i32 m0, s28, 0x13000
	s_nop 0
	global_load_lds_dwordx4 v128, vcc
	s_add_u32 vcc_lo, vcc_lo, 0x30000
	s_addc_u32 vcc_hi, vcc_hi, 0
	s_add_i32 m0, s28, 0x14000
	s_nop 0
	global_load_lds_dwordx4 v132, vcc
	s_add_i32 m0, s28, 0x16000
	s_nop 0
	global_load_lds_dwordx4 v128, vcc
	s_add_u32 vcc_lo, vcc_lo, 0x10000
	s_addc_u32 vcc_hi, vcc_hi, 0
	s_add_i32 m0, s28, 0x15000
	s_nop 0
	global_load_lds_dwordx4 v132, vcc
	s_add_i32 m0, s28, 0x17000
	s_nop 0
	global_load_lds_dwordx4 v128, vcc
	ds_read_b128 v[144:147], v151 offset:32768
	ds_read_b128 v[154:157], v151 offset:33792
	ds_read_b128 v[158:161], v151 offset:34816
	ds_read_b128 v[162:165], v151 offset:35840
	ds_read_b128 v[166:169], v152 offset:32768
	ds_read_b128 v[170:173], v152 offset:33792
	ds_read_b128 v[174:177], v152 offset:34816
	ds_read_b128 v[178:181], v152 offset:35840
	ds_read_b128 v[182:185], v153 offset:32768
	ds_read_b128 v[186:189], v153 offset:33792
	ds_read_b128 v[190:193], v153 offset:34816
	ds_read_b128 v[194:197], v153 offset:35840
	ds_read_b128 v[198:201], v153 offset:36864
	ds_read_b128 v[202:205], v153 offset:37888
	ds_read_b128 v[206:209], v153 offset:38912
	ds_read_b128 v[210:213], v153 offset:39936
	ds_read_b128 v[220:223], v153 offset:49152
	ds_read_b128 v[224:227], v153 offset:50176
	ds_read_b128 v[228:231], v153 offset:51200
	ds_read_b128 v[232:235], v153 offset:52224
	ds_read_b128 v[236:239], v153 offset:53248
	ds_read_b128 v[240:243], v153 offset:54272
	ds_read_b128 v[244:247], v153 offset:55296
	ds_read_b128 v[248:251], v153 offset:56320
	s_nop 15
	s_nop 15
	s_waitcnt lgkmcnt(0)
	s_barrier
	s_setprio 1
	v_mfma_f32_16x16x32_bf16 v[124:127], v[144:147], v[182:185], v[124:127]
	v_mfma_f32_16x16x32_bf16 v[120:123], v[158:161], v[182:185], v[120:123]
	v_mfma_f32_16x16x32_bf16 v[108:111], v[144:147], v[190:193], v[108:111]
	v_mfma_f32_16x16x32_bf16 v[104:107], v[158:161], v[190:193], v[104:107]
	v_mfma_f32_16x16x32_bf16 v[92:95], v[144:147], v[198:201], v[92:95]
	v_mfma_f32_16x16x32_bf16 v[88:91], v[158:161], v[198:201], v[88:91]
	v_mfma_f32_16x16x32_bf16 v[76:79], v[144:147], v[206:209], v[76:79]
	v_mfma_f32_16x16x32_bf16 v[72:75], v[158:161], v[206:209], v[72:75]
	v_mfma_f32_16x16x32_bf16 v[124:127], v[154:157], v[186:189], v[124:127]
	v_mfma_f32_16x16x32_bf16 v[120:123], v[162:165], v[186:189], v[120:123]
	v_mfma_f32_16x16x32_bf16 v[108:111], v[154:157], v[194:197], v[108:111]
	v_mfma_f32_16x16x32_bf16 v[104:107], v[162:165], v[194:197], v[104:107]
	v_mfma_f32_16x16x32_bf16 v[92:95], v[154:157], v[202:205], v[92:95]
	v_mfma_f32_16x16x32_bf16 v[88:91], v[162:165], v[202:205], v[88:91]
	v_mfma_f32_16x16x32_bf16 v[76:79], v[154:157], v[210:213], v[76:79]
	v_mfma_f32_16x16x32_bf16 v[72:75], v[162:165], v[210:213], v[72:75]
	s_setprio 0
	s_setprio 1
	v_mfma_f32_16x16x32_bf16 v[116:119], v[166:169], v[182:185], v[116:119]
	v_mfma_f32_16x16x32_bf16 v[112:115], v[174:177], v[182:185], v[112:115]
	v_mfma_f32_16x16x32_bf16 v[100:103], v[166:169], v[190:193], v[100:103]
	v_mfma_f32_16x16x32_bf16 v[96:99], v[174:177], v[190:193], v[96:99]
	v_mfma_f32_16x16x32_bf16 v[84:87], v[166:169], v[198:201], v[84:87]
	v_mfma_f32_16x16x32_bf16 v[80:83], v[174:177], v[198:201], v[80:83]
	v_mfma_f32_16x16x32_bf16 v[68:71], v[166:169], v[206:209], v[68:71]
	v_mfma_f32_16x16x32_bf16 v[64:67], v[174:177], v[206:209], v[64:67]
	v_mfma_f32_16x16x32_bf16 v[116:119], v[170:173], v[186:189], v[116:119]
	v_mfma_f32_16x16x32_bf16 v[112:115], v[178:181], v[186:189], v[112:115]
	v_mfma_f32_16x16x32_bf16 v[100:103], v[170:173], v[194:197], v[100:103]
	v_mfma_f32_16x16x32_bf16 v[96:99], v[178:181], v[194:197], v[96:99]
	v_mfma_f32_16x16x32_bf16 v[84:87], v[170:173], v[202:205], v[84:87]
	v_mfma_f32_16x16x32_bf16 v[80:83], v[178:181], v[202:205], v[80:83]
	v_mfma_f32_16x16x32_bf16 v[68:71], v[170:173], v[210:213], v[68:71]
	v_mfma_f32_16x16x32_bf16 v[64:67], v[178:181], v[210:213], v[64:67]
	s_setprio 0
	s_setprio 1
	v_mfma_f32_16x16x32_bf16 v[60:63], v[144:147], v[220:223], v[60:63]
	v_mfma_f32_16x16x32_bf16 v[56:59], v[158:161], v[220:223], v[56:59]
	v_mfma_f32_16x16x32_bf16 v[44:47], v[144:147], v[228:231], v[44:47]
	v_mfma_f32_16x16x32_bf16 v[40:43], v[158:161], v[228:231], v[40:43]
	v_mfma_f32_16x16x32_bf16 v[28:31], v[144:147], v[236:239], v[28:31]
	v_mfma_f32_16x16x32_bf16 v[24:27], v[158:161], v[236:239], v[24:27]
	v_mfma_f32_16x16x32_bf16 v[12:15], v[144:147], v[244:247], v[12:15]
	v_mfma_f32_16x16x32_bf16 v[8:11], v[158:161], v[244:247], v[8:11]
	v_mfma_f32_16x16x32_bf16 v[60:63], v[154:157], v[224:227], v[60:63]
	v_mfma_f32_16x16x32_bf16 v[56:59], v[162:165], v[224:227], v[56:59]
	v_mfma_f32_16x16x32_bf16 v[44:47], v[154:157], v[232:235], v[44:47]
	v_mfma_f32_16x16x32_bf16 v[40:43], v[162:165], v[232:235], v[40:43]
	v_mfma_f32_16x16x32_bf16 v[28:31], v[154:157], v[240:243], v[28:31]
	v_mfma_f32_16x16x32_bf16 v[24:27], v[162:165], v[240:243], v[24:27]
	v_mfma_f32_16x16x32_bf16 v[12:15], v[154:157], v[248:251], v[12:15]
	v_mfma_f32_16x16x32_bf16 v[8:11], v[162:165], v[248:251], v[8:11]
	s_setprio 0
	s_setprio 1
	v_mfma_f32_16x16x32_bf16 v[52:55], v[166:169], v[220:223], v[52:55]
	v_mfma_f32_16x16x32_bf16 v[48:51], v[174:177], v[220:223], v[48:51]
	v_mfma_f32_16x16x32_bf16 v[36:39], v[166:169], v[228:231], v[36:39]
	v_mfma_f32_16x16x32_bf16 v[32:35], v[174:177], v[228:231], v[32:35]
	v_mfma_f32_16x16x32_bf16 v[20:23], v[166:169], v[236:239], v[20:23]
	v_mfma_f32_16x16x32_bf16 v[16:19], v[174:177], v[236:239], v[16:19]
	v_mfma_f32_16x16x32_bf16 v[4:7], v[166:169], v[244:247], v[4:7]
	v_mfma_f32_16x16x32_bf16 v[0:3], v[174:177], v[244:247], v[0:3]
	v_mfma_f32_16x16x32_bf16 v[52:55], v[170:173], v[224:227], v[52:55]
	v_mfma_f32_16x16x32_bf16 v[48:51], v[178:181], v[224:227], v[48:51]
	v_mfma_f32_16x16x32_bf16 v[36:39], v[170:173], v[232:235], v[36:39]
	v_mfma_f32_16x16x32_bf16 v[32:35], v[178:181], v[232:235], v[32:35]
	v_mfma_f32_16x16x32_bf16 v[20:23], v[170:173], v[240:243], v[20:23]
	v_mfma_f32_16x16x32_bf16 v[16:19], v[178:181], v[240:243], v[16:19]
	v_mfma_f32_16x16x32_bf16 v[4:7], v[170:173], v[248:251], v[4:7]
	v_mfma_f32_16x16x32_bf16 v[0:3], v[178:181], v[248:251], v[0:3]
	s_setprio 0
	s_add_i32 s49, s49, 2
	s_add_u32 s22, s22, 0x100
	s_addc_u32 s23, s23, 0
	s_add_u32 s47, s47, 0x100
	s_addc_u32 s48, s48, 0
	s_add_u32 s24, s22, 0xfffc0080
	s_addc_u32 s25, s23, -1
	s_cmp_eq_u32 s49, 12
	s_cselect_b32 s27, s13, s25
	s_cselect_b32 s26, s41, s24
	s_cselect_b32 s25, s11, s48
	s_cselect_b32 s24, s46, s47
	s_cmp_gt_u32 s49, 13
	s_waitcnt vmcnt(0)
	s_barrier
	s_cbranch_scc0 .Lk64_lead_glu
	s_branch .Lk64_done_glu
.Lk64_trail_glu:
	s_sub_u32 vcc_lo, s22, 0x40000
	s_subb_u32 vcc_hi, s23, 0
	s_add_i32 m0, s28, 0xa000
	s_nop 0
	global_load_lds_dwordx4 v130, vcc
	s_add_u32 vcc_lo, vcc_lo, 0x10000
	s_addc_u32 vcc_hi, vcc_hi, 0
	s_add_i32 m0, s28, 0x9000
	s_nop 0
	global_load_lds_dwordx4 v134, vcc
	s_add_u32 vcc_lo, vcc_lo, 0x30000
	s_addc_u32 vcc_hi, vcc_hi, 0
	s_add_i32 m0, s28, 0xe000
	s_nop 0
	global_load_lds_dwordx4 v130, vcc
	s_add_u32 vcc_lo, vcc_lo, 0x10000
	s_addc_u32 vcc_hi, vcc_hi, 0
	s_add_i32 m0, s28, 0xd000
	s_nop 0
	global_load_lds_dwordx4 v134, vcc
	s_add_u32 vcc_lo, s26, 0x0
	s_addc_u32 vcc_hi, s27, 0
	s_mov_b32 m0, s28
	s_nop 0
	global_load_lds_dwordx4 v134, vcc
	s_sub_u32 vcc_lo, vcc_lo, 0x10000
	s_subb_u32 vcc_hi, vcc_hi, 0
	s_sub_i32 m0, s28, 0x1000
	s_nop 0
	global_load_lds_dwordx4 v134, vcc
	s_add_u32 vcc_lo, vcc_lo, 0x50000
	s_addc_u32 vcc_hi, vcc_hi, 0
	s_add_i32 m0, s28, 0x4000
	s_nop 0
	global_load_lds_dwordx4 v134, vcc
	s_sub_u32 vcc_lo, vcc_lo, 0x10000
	s_subb_u32 vcc_hi, vcc_hi, 0
	s_add_i32 m0, s28, 0x3000
	s_nop 0
	global_load_lds_dwordx4 v134, vcc
	ds_read_b128 v[144:147], v151 offset:0
	ds_read_b128 v[154:157], v151 offset:1024
	ds_read_b128 v[158:161], v151 offset:2048
	ds_read_b128 v[162:165], v151 offset:3072
	ds_read_b128 v[166:169], v152 offset:0
	ds_read_b128 v[170:173], v152 offset:1024
	ds_read_b128 v[174:177], v152 offset:2048
	ds_read_b128 v[178:181], v152 offset:3072
	ds_read_b128 v[182:185], v153 offset:0
	ds_read_b128 v[186:189], v153 offset:1024
	ds_read_b128 v[190:193], v153 offset:2048
	ds_read_b128 v[194:197], v153 offset:3072
	ds_read_b128 v[198:201], v153 offset:4096
	ds_read_b128 v[202:205], v153 offset:5120
	ds_read_b128 v[206:209], v153 offset:6144
	ds_read_b128 v[210:213], v153 offset:7168
	ds_read_b128 v[220:223], v153 offset:16384
	ds_read_b128 v[224:227], v153 offset:17408
	ds_read_b128 v[228:231], v153 offset:18432
	ds_read_b128 v[232:235], v153 offset:19456
	ds_read_b128 v[236:239], v153 offset:20480
	ds_read_b128 v[240:243], v153 offset:21504
	ds_read_b128 v[244:247], v153 offset:22528
	ds_read_b128 v[248:251], v153 offset:23552
	s_nop 15
	s_nop 15
	s_waitcnt lgkmcnt(0)
	s_barrier
	s_setprio 1
	v_mfma_f32_16x16x32_bf16 v[124:127], v[144:147], v[182:185], v[124:127]
	v_mfma_f32_16x16x32_bf16 v[120:123], v[158:161], v[182:185], v[120:123]
	v_mfma_f32_16x16x32_bf16 v[108:111], v[144:147], v[190:193], v[108:111]
	v_mfma_f32_16x16x32_bf16 v[104:107], v[158:161], v[190:193], v[104:107]
	v_mfma_f32_16x16x32_bf16 v[92:95], v[144:147], v[198:201], v[92:95]
	v_mfma_f32_16x16x32_bf16 v[88:91], v[158:161], v[198:201], v[88:91]
	v_mfma_f32_16x16x32_bf16 v[76:79], v[144:147], v[206:209], v[76:79]
	v_mfma_f32_16x16x32_bf16 v[72:75], v[158:161], v[206:209], v[72:75]
	v_mfma_f32_16x16x32_bf16 v[124:127], v[154:157], v[186:189], v[124:127]
	v_mfma_f32_16x16x32_bf16 v[120:123], v[162:165], v[186:189], v[120:123]
	v_mfma_f32_16x16x32_bf16 v[108:111], v[154:157], v[194:197], v[108:111]
	v_mfma_f32_16x16x32_bf16 v[104:107], v[162:165], v[194:197], v[104:107]
	v_mfma_f32_16x16x32_bf16 v[92:95], v[154:157], v[202:205], v[92:95]
	v_mfma_f32_16x16x32_bf16 v[88:91], v[162:165], v[202:205], v[88:91]
	v_mfma_f32_16x16x32_bf16 v[76:79], v[154:157], v[210:213], v[76:79]
	v_mfma_f32_16x16x32_bf16 v[72:75], v[162:165], v[210:213], v[72:75]
	s_setprio 0
	s_setprio 1
	v_mfma_f32_16x16x32_bf16 v[116:119], v[166:169], v[182:185], v[116:119]
	v_mfma_f32_16x16x32_bf16 v[112:115], v[174:177], v[182:185], v[112:115]
	v_mfma_f32_16x16x32_bf16 v[100:103], v[166:169], v[190:193], v[100:103]
	v_mfma_f32_16x16x32_bf16 v[96:99], v[174:177], v[190:193], v[96:99]
	v_mfma_f32_16x16x32_bf16 v[84:87], v[166:169], v[198:201], v[84:87]
	v_mfma_f32_16x16x32_bf16 v[80:83], v[174:177], v[198:201], v[80:83]
	v_mfma_f32_16x16x32_bf16 v[68:71], v[166:169], v[206:209], v[68:71]
	v_mfma_f32_16x16x32_bf16 v[64:67], v[174:177], v[206:209], v[64:67]
	v_mfma_f32_16x16x32_bf16 v[116:119], v[170:173], v[186:189], v[116:119]
	v_mfma_f32_16x16x32_bf16 v[112:115], v[178:181], v[186:189], v[112:115]
	v_mfma_f32_16x16x32_bf16 v[100:103], v[170:173], v[194:197], v[100:103]
	v_mfma_f32_16x16x32_bf16 v[96:99], v[178:181], v[194:197], v[96:99]
	v_mfma_f32_16x16x32_bf16 v[84:87], v[170:173], v[202:205], v[84:87]
	v_mfma_f32_16x16x32_bf16 v[80:83], v[178:181], v[202:205], v[80:83]
	v_mfma_f32_16x16x32_bf16 v[68:71], v[170:173], v[210:213], v[68:71]
	v_mfma_f32_16x16x32_bf16 v[64:67], v[178:181], v[210:213], v[64:67]
	s_setprio 0
	s_setprio 1
	v_mfma_f32_16x16x32_bf16 v[60:63], v[144:147], v[220:223], v[60:63]
	v_mfma_f32_16x16x32_bf16 v[56:59], v[158:161], v[220:223], v[56:59]
	v_mfma_f32_16x16x32_bf16 v[44:47], v[144:147], v[228:231], v[44:47]
	v_mfma_f32_16x16x32_bf16 v[40:43], v[158:161], v[228:231], v[40:43]
	v_mfma_f32_16x16x32_bf16 v[28:31], v[144:147], v[236:239], v[28:31]
	v_mfma_f32_16x16x32_bf16 v[24:27], v[158:161], v[236:239], v[24:27]
	v_mfma_f32_16x16x32_bf16 v[12:15], v[144:147], v[244:247], v[12:15]
	v_mfma_f32_16x16x32_bf16 v[8:11], v[158:161], v[244:247], v[8:11]
	v_mfma_f32_16x16x32_bf16 v[60:63], v[154:157], v[224:227], v[60:63]
	v_mfma_f32_16x16x32_bf16 v[56:59], v[162:165], v[224:227], v[56:59]
	v_mfma_f32_16x16x32_bf16 v[44:47], v[154:157], v[232:235], v[44:47]
	v_mfma_f32_16x16x32_bf16 v[40:43], v[162:165], v[232:235], v[40:43]
	v_mfma_f32_16x16x32_bf16 v[28:31], v[154:157], v[240:243], v[28:31]
	v_mfma_f32_16x16x32_bf16 v[24:27], v[162:165], v[240:243], v[24:27]
	v_mfma_f32_16x16x32_bf16 v[12:15], v[154:157], v[248:251], v[12:15]
	v_mfma_f32_16x16x32_bf16 v[8:11], v[162:165], v[248:251], v[8:11]
	s_setprio 0
	s_setprio 1
	v_mfma_f32_16x16x32_bf16 v[52:55], v[166:169], v[220:223], v[52:55]
	v_mfma_f32_16x16x32_bf16 v[48:51], v[174:177], v[220:223], v[48:51]
	v_mfma_f32_16x16x32_bf16 v[36:39], v[166:169], v[228:231], v[36:39]
	v_mfma_f32_16x16x32_bf16 v[32:35], v[174:177], v[228:231], v[32:35]
	v_mfma_f32_16x16x32_bf16 v[20:23], v[166:169], v[236:239], v[20:23]
	v_mfma_f32_16x16x32_bf16 v[16:19], v[174:177], v[236:239], v[16:19]
	v_mfma_f32_16x16x32_bf16 v[4:7], v[166:169], v[244:247], v[4:7]
	v_mfma_f32_16x16x32_bf16 v[0:3], v[174:177], v[244:247], v[0:3]
	v_mfma_f32_16x16x32_bf16 v[52:55], v[170:173], v[224:227], v[52:55]
	v_mfma_f32_16x16x32_bf16 v[48:51], v[178:181], v[224:227], v[48:51]
	v_mfma_f32_16x16x32_bf16 v[36:39], v[170:173], v[232:235], v[36:39]
	v_mfma_f32_16x16x32_bf16 v[32:35], v[178:181], v[232:235], v[32:35]
	v_mfma_f32_16x16x32_bf16 v[20:23], v[170:173], v[240:243], v[20:23]
	v_mfma_f32_16x16x32_bf16 v[16:19], v[178:181], v[240:243], v[16:19]
	v_mfma_f32_16x16x32_bf16 v[4:7], v[170:173], v[248:251], v[4:7]
	v_mfma_f32_16x16x32_bf16 v[0:3], v[178:181], v[248:251], v[0:3]
	s_setprio 0
	s_waitcnt vmcnt(0)
	s_barrier
	s_add_u32 vcc_lo, s26, 0x0
	s_addc_u32 vcc_hi, s27, 0
	s_add_i32 m0, s28, 0x2000
	s_nop 0
	global_load_lds_dwordx4 v130, vcc
	s_add_u32 vcc_lo, vcc_lo, 0x10000
	s_addc_u32 vcc_hi, vcc_hi, 0
	s_add_i32 m0, s28, 0x1000
	s_nop 0
	global_load_lds_dwordx4 v134, vcc
	s_add_u32 vcc_lo, vcc_lo, 0x30000
	s_addc_u32 vcc_hi, vcc_hi, 0
	s_add_i32 m0, s28, 0x6000
	s_nop 0
	global_load_lds_dwordx4 v130, vcc
	s_add_u32 vcc_lo, vcc_lo, 0x10000
	s_addc_u32 vcc_hi, vcc_hi, 0
	s_add_i32 m0, s28, 0x5000
	s_nop 0
	global_load_lds_dwordx4 v134, vcc
	s_add_u32 vcc_lo, s26, 0x80
	s_addc_u32 vcc_hi, s27, 0
	s_add_i32 m0, s28, 0x8000
	s_nop 0
	global_load_lds_dwordx4 v134, vcc
	s_sub_u32 vcc_lo, vcc_lo, 0x10000
	s_subb_u32 vcc_hi, vcc_hi, 0
	s_add_i32 m0, s28, 0x7000
	s_nop 0
	global_load_lds_dwordx4 v134, vcc
	s_add_u32 vcc_lo, vcc_lo, 0x50000
	s_addc_u32 vcc_hi, vcc_hi, 0
	s_add_i32 m0, s28, 0xc000
	s_nop 0
	global_load_lds_dwordx4 v134, vcc
	s_sub_u32 vcc_lo, vcc_lo, 0x10000
	s_subb_u32 vcc_hi, vcc_hi, 0
	s_add_i32 m0, s28, 0xb000
	s_nop 0
	global_load_lds_dwordx4 v134, vcc
	ds_read_b128 v[144:147], v151 offset:32768
	ds_read_b128 v[154:157], v151 offset:33792
	ds_read_b128 v[158:161], v151 offset:34816
	ds_read_b128 v[162:165], v151 offset:35840
	ds_read_b128 v[166:169], v152 offset:32768
	ds_read_b128 v[170:173], v152 offset:33792
	ds_read_b128 v[174:177], v152 offset:34816
	ds_read_b128 v[178:181], v152 offset:35840
	ds_read_b128 v[182:185], v153 offset:32768
	ds_read_b128 v[186:189], v153 offset:33792
	ds_read_b128 v[190:193], v153 offset:34816
	ds_read_b128 v[194:197], v153 offset:35840
	ds_read_b128 v[198:201], v153 offset:36864
	ds_read_b128 v[202:205], v153 offset:37888
	ds_read_b128 v[206:209], v153 offset:38912
	ds_read_b128 v[210:213], v153 offset:39936
	ds_read_b128 v[220:223], v153 offset:49152
	ds_read_b128 v[224:227], v153 offset:50176
	ds_read_b128 v[228:231], v153 offset:51200
	ds_read_b128 v[232:235], v153 offset:52224
	ds_read_b128 v[236:239], v153 offset:53248
	ds_read_b128 v[240:243], v153 offset:54272
	ds_read_b128 v[244:247], v153 offset:55296
	ds_read_b128 v[248:251], v153 offset:56320
	s_nop 15
	s_nop 15
	s_waitcnt lgkmcnt(0)
	s_barrier
	s_setprio 1
	v_mfma_f32_16x16x32_bf16 v[124:127], v[144:147], v[182:185], v[124:127]
	v_mfma_f32_16x16x32_bf16 v[120:123], v[158:161], v[182:185], v[120:123]
	v_mfma_f32_16x16x32_bf16 v[108:111], v[144:147], v[190:193], v[108:111]
	v_mfma_f32_16x16x32_bf16 v[104:107], v[158:161], v[190:193], v[104:107]
	v_mfma_f32_16x16x32_bf16 v[92:95], v[144:147], v[198:201], v[92:95]
	v_mfma_f32_16x16x32_bf16 v[88:91], v[158:161], v[198:201], v[88:91]
	v_mfma_f32_16x16x32_bf16 v[76:79], v[144:147], v[206:209], v[76:79]
	v_mfma_f32_16x16x32_bf16 v[72:75], v[158:161], v[206:209], v[72:75]
	v_mfma_f32_16x16x32_bf16 v[124:127], v[154:157], v[186:189], v[124:127]
	v_mfma_f32_16x16x32_bf16 v[120:123], v[162:165], v[186:189], v[120:123]
	v_mfma_f32_16x16x32_bf16 v[108:111], v[154:157], v[194:197], v[108:111]
	v_mfma_f32_16x16x32_bf16 v[104:107], v[162:165], v[194:197], v[104:107]
	v_mfma_f32_16x16x32_bf16 v[92:95], v[154:157], v[202:205], v[92:95]
	v_mfma_f32_16x16x32_bf16 v[88:91], v[162:165], v[202:205], v[88:91]
	v_mfma_f32_16x16x32_bf16 v[76:79], v[154:157], v[210:213], v[76:79]
	v_mfma_f32_16x16x32_bf16 v[72:75], v[162:165], v[210:213], v[72:75]
	s_setprio 0
	s_setprio 1
	v_mfma_f32_16x16x32_bf16 v[116:119], v[166:169], v[182:185], v[116:119]
	v_mfma_f32_16x16x32_bf16 v[112:115], v[174:177], v[182:185], v[112:115]
	v_mfma_f32_16x16x32_bf16 v[100:103], v[166:169], v[190:193], v[100:103]
	v_mfma_f32_16x16x32_bf16 v[96:99], v[174:177], v[190:193], v[96:99]
	v_mfma_f32_16x16x32_bf16 v[84:87], v[166:169], v[198:201], v[84:87]
	v_mfma_f32_16x16x32_bf16 v[80:83], v[174:177], v[198:201], v[80:83]
	v_mfma_f32_16x16x32_bf16 v[68:71], v[166:169], v[206:209], v[68:71]
	v_mfma_f32_16x16x32_bf16 v[64:67], v[174:177], v[206:209], v[64:67]
	v_mfma_f32_16x16x32_bf16 v[116:119], v[170:173], v[186:189], v[116:119]
	v_mfma_f32_16x16x32_bf16 v[112:115], v[178:181], v[186:189], v[112:115]
	v_mfma_f32_16x16x32_bf16 v[100:103], v[170:173], v[194:197], v[100:103]
	v_mfma_f32_16x16x32_bf16 v[96:99], v[178:181], v[194:197], v[96:99]
	v_mfma_f32_16x16x32_bf16 v[84:87], v[170:173], v[202:205], v[84:87]
	v_mfma_f32_16x16x32_bf16 v[80:83], v[178:181], v[202:205], v[80:83]
	v_mfma_f32_16x16x32_bf16 v[68:71], v[170:173], v[210:213], v[68:71]
	v_mfma_f32_16x16x32_bf16 v[64:67], v[178:181], v[210:213], v[64:67]
	s_setprio 0
	s_setprio 1
	v_mfma_f32_16x16x32_bf16 v[60:63], v[144:147], v[220:223], v[60:63]
	v_mfma_f32_16x16x32_bf16 v[56:59], v[158:161], v[220:223], v[56:59]
	v_mfma_f32_16x16x32_bf16 v[44:47], v[144:147], v[228:231], v[44:47]
	v_mfma_f32_16x16x32_bf16 v[40:43], v[158:161], v[228:231], v[40:43]
	v_mfma_f32_16x16x32_bf16 v[28:31], v[144:147], v[236:239], v[28:31]
	v_mfma_f32_16x16x32_bf16 v[24:27], v[158:161], v[236:239], v[24:27]
	v_mfma_f32_16x16x32_bf16 v[12:15], v[144:147], v[244:247], v[12:15]
	v_mfma_f32_16x16x32_bf16 v[8:11], v[158:161], v[244:247], v[8:11]
	v_mfma_f32_16x16x32_bf16 v[60:63], v[154:157], v[224:227], v[60:63]
	v_mfma_f32_16x16x32_bf16 v[56:59], v[162:165], v[224:227], v[56:59]
	v_mfma_f32_16x16x32_bf16 v[44:47], v[154:157], v[232:235], v[44:47]
	v_mfma_f32_16x16x32_bf16 v[40:43], v[162:165], v[232:235], v[40:43]
	v_mfma_f32_16x16x32_bf16 v[28:31], v[154:157], v[240:243], v[28:31]
	v_mfma_f32_16x16x32_bf16 v[24:27], v[162:165], v[240:243], v[24:27]
	v_mfma_f32_16x16x32_bf16 v[12:15], v[154:157], v[248:251], v[12:15]
	v_mfma_f32_16x16x32_bf16 v[8:11], v[162:165], v[248:251], v[8:11]
	s_setprio 0
	s_setprio 1
	v_mfma_f32_16x16x32_bf16 v[52:55], v[166:169], v[220:223], v[52:55]
	v_mfma_f32_16x16x32_bf16 v[48:51], v[174:177], v[220:223], v[48:51]
	v_mfma_f32_16x16x32_bf16 v[36:39], v[166:169], v[228:231], v[36:39]
	v_mfma_f32_16x16x32_bf16 v[32:35], v[174:177], v[228:231], v[32:35]
	v_mfma_f32_16x16x32_bf16 v[20:23], v[166:169], v[236:239], v[20:23]
	v_mfma_f32_16x16x32_bf16 v[16:19], v[174:177], v[236:239], v[16:19]
	v_mfma_f32_16x16x32_bf16 v[4:7], v[166:169], v[244:247], v[4:7]
	v_mfma_f32_16x16x32_bf16 v[0:3], v[174:177], v[244:247], v[0:3]
	v_mfma_f32_16x16x32_bf16 v[52:55], v[170:173], v[224:227], v[52:55]
	v_mfma_f32_16x16x32_bf16 v[48:51], v[178:181], v[224:227], v[48:51]
	v_mfma_f32_16x16x32_bf16 v[36:39], v[170:173], v[232:235], v[36:39]
	v_mfma_f32_16x16x32_bf16 v[32:35], v[178:181], v[232:235], v[32:35]
	v_mfma_f32_16x16x32_bf16 v[20:23], v[170:173], v[240:243], v[20:23]
	v_mfma_f32_16x16x32_bf16 v[16:19], v[178:181], v[240:243], v[16:19]
	v_mfma_f32_16x16x32_bf16 v[4:7], v[170:173], v[248:251], v[4:7]
	v_mfma_f32_16x16x32_bf16 v[0:3], v[178:181], v[248:251], v[0:3]
	s_setprio 0
	s_add_i32 s49, s49, 2
	s_add_u32 s22, s22, 0x100
	s_addc_u32 s23, s23, 0
	s_add_u32 s47, s47, 0x100
	s_addc_u32 s48, s48, 0
	s_add_u32 s24, s22, 0xfffc0080
	s_addc_u32 s25, s23, -1
	s_cmp_eq_u32 s49, 12
	s_cselect_b32 s27, s13, s25
	s_cselect_b32 s26, s41, s24
	s_cselect_b32 s25, s11, s48
	s_cselect_b32 s24, s46, s47
	s_cmp_gt_u32 s49, 13
	s_waitcnt vmcnt(0)
	s_barrier
	s_cbranch_scc0 .Lk64_trail_glu

.Lk64_lead_p4:
	s_sub_u32 vcc_lo, s54, 0x80
	s_subb_u32 vcc_hi, s55, 0
	s_add_i32 m0, s36, 0x18000
	s_nop 0
	global_load_lds_dwordx4 v132, vcc
	s_add_i32 m0, s36, 0x1a000
	s_nop 0
	global_load_lds_dwordx4 v128, vcc
	s_add_u32 vcc_lo, vcc_lo, 0x10000
	s_addc_u32 vcc_hi, vcc_hi, 0
	s_add_i32 m0, s36, 0x19000
	s_nop 0
	global_load_lds_dwordx4 v132, vcc
	s_add_i32 m0, s36, 0x1b000
	s_nop 0
	global_load_lds_dwordx4 v128, vcc
	s_add_u32 vcc_lo, vcc_lo, 0x30000
	s_addc_u32 vcc_hi, vcc_hi, 0
	s_add_i32 m0, s36, 0x1c000
	s_nop 0
	global_load_lds_dwordx4 v132, vcc
	s_add_i32 m0, s36, 0x1e000
	s_nop 0
	global_load_lds_dwordx4 v128, vcc
	s_add_u32 vcc_lo, vcc_lo, 0x10000
	s_addc_u32 vcc_hi, vcc_hi, 0
	s_add_i32 m0, s36, 0x1d000
	s_nop 0
	global_load_lds_dwordx4 v132, vcc
	s_add_i32 m0, s36, 0x1f000
	s_nop 0
	global_load_lds_dwordx4 v128, vcc
	ds_read_b128 v[144:147], v151 offset:0
	ds_read_b128 v[154:157], v151 offset:1024
	ds_read_b128 v[158:161], v151 offset:2048
	ds_read_b128 v[162:165], v151 offset:3072
	ds_read_b128 v[166:169], v152 offset:0
	ds_read_b128 v[170:173], v152 offset:1024
	ds_read_b128 v[174:177], v152 offset:2048
	ds_read_b128 v[178:181], v152 offset:3072
	ds_read_b128 v[182:185], v153 offset:0
	ds_read_b128 v[186:189], v153 offset:1024
	ds_read_b128 v[190:193], v153 offset:2048
	ds_read_b128 v[194:197], v153 offset:3072
	ds_read_b128 v[198:201], v153 offset:4096
	ds_read_b128 v[202:205], v153 offset:5120
	ds_read_b128 v[206:209], v153 offset:6144
	ds_read_b128 v[210:213], v153 offset:7168
	ds_read_b128 v[220:223], v153 offset:16384
	ds_read_b128 v[224:227], v153 offset:17408
	ds_read_b128 v[228:231], v153 offset:18432
	ds_read_b128 v[232:235], v153 offset:19456
	ds_read_b128 v[236:239], v153 offset:20480
	ds_read_b128 v[240:243], v153 offset:21504
	ds_read_b128 v[244:247], v153 offset:22528
	ds_read_b128 v[248:251], v153 offset:23552
	s_nop 15
	s_nop 15
	s_waitcnt lgkmcnt(0)
	s_barrier
	s_setprio 1
	v_mfma_f32_16x16x32_bf16 v[124:127], v[144:147], v[182:185], v[124:127]
	v_mfma_f32_16x16x32_bf16 v[120:123], v[158:161], v[182:185], v[120:123]
	v_mfma_f32_16x16x32_bf16 v[108:111], v[144:147], v[190:193], v[108:111]
	v_mfma_f32_16x16x32_bf16 v[104:107], v[158:161], v[190:193], v[104:107]
	v_mfma_f32_16x16x32_bf16 v[92:95], v[144:147], v[198:201], v[92:95]
	v_mfma_f32_16x16x32_bf16 v[88:91], v[158:161], v[198:201], v[88:91]
	v_mfma_f32_16x16x32_bf16 v[76:79], v[144:147], v[206:209], v[76:79]
	v_mfma_f32_16x16x32_bf16 v[72:75], v[158:161], v[206:209], v[72:75]
	v_mfma_f32_16x16x32_bf16 v[124:127], v[154:157], v[186:189], v[124:127]
	v_mfma_f32_16x16x32_bf16 v[120:123], v[162:165], v[186:189], v[120:123]
	v_mfma_f32_16x16x32_bf16 v[108:111], v[154:157], v[194:197], v[108:111]
	v_mfma_f32_16x16x32_bf16 v[104:107], v[162:165], v[194:197], v[104:107]
	v_mfma_f32_16x16x32_bf16 v[92:95], v[154:157], v[202:205], v[92:95]
	v_mfma_f32_16x16x32_bf16 v[88:91], v[162:165], v[202:205], v[88:91]
	v_mfma_f32_16x16x32_bf16 v[76:79], v[154:157], v[210:213], v[76:79]
	v_mfma_f32_16x16x32_bf16 v[72:75], v[162:165], v[210:213], v[72:75]
	s_setprio 0
	s_setprio 1
	v_mfma_f32_16x16x32_bf16 v[116:119], v[166:169], v[182:185], v[116:119]
	v_mfma_f32_16x16x32_bf16 v[112:115], v[174:177], v[182:185], v[112:115]
	v_mfma_f32_16x16x32_bf16 v[100:103], v[166:169], v[190:193], v[100:103]
	v_mfma_f32_16x16x32_bf16 v[96:99], v[174:177], v[190:193], v[96:99]
	v_mfma_f32_16x16x32_bf16 v[84:87], v[166:169], v[198:201], v[84:87]
	v_mfma_f32_16x16x32_bf16 v[80:83], v[174:177], v[198:201], v[80:83]
	v_mfma_f32_16x16x32_bf16 v[68:71], v[166:169], v[206:209], v[68:71]
	v_mfma_f32_16x16x32_bf16 v[64:67], v[174:177], v[206:209], v[64:67]
	v_mfma_f32_16x16x32_bf16 v[116:119], v[170:173], v[186:189], v[116:119]
	v_mfma_f32_16x16x32_bf16 v[112:115], v[178:181], v[186:189], v[112:115]
	v_mfma_f32_16x16x32_bf16 v[100:103], v[170:173], v[194:197], v[100:103]
	v_mfma_f32_16x16x32_bf16 v[96:99], v[178:181], v[194:197], v[96:99]
	v_mfma_f32_16x16x32_bf16 v[84:87], v[170:173], v[202:205], v[84:87]
	v_mfma_f32_16x16x32_bf16 v[80:83], v[178:181], v[202:205], v[80:83]
	v_mfma_f32_16x16x32_bf16 v[68:71], v[170:173], v[210:213], v[68:71]
	v_mfma_f32_16x16x32_bf16 v[64:67], v[178:181], v[210:213], v[64:67]
	s_setprio 0
	s_setprio 1
	v_mfma_f32_16x16x32_bf16 v[60:63], v[144:147], v[220:223], v[60:63]
	v_mfma_f32_16x16x32_bf16 v[56:59], v[158:161], v[220:223], v[56:59]
	v_mfma_f32_16x16x32_bf16 v[44:47], v[144:147], v[228:231], v[44:47]
	v_mfma_f32_16x16x32_bf16 v[40:43], v[158:161], v[228:231], v[40:43]
	v_mfma_f32_16x16x32_bf16 v[28:31], v[144:147], v[236:239], v[28:31]
	v_mfma_f32_16x16x32_bf16 v[24:27], v[158:161], v[236:239], v[24:27]
	v_mfma_f32_16x16x32_bf16 v[12:15], v[144:147], v[244:247], v[12:15]
	v_mfma_f32_16x16x32_bf16 v[8:11], v[158:161], v[244:247], v[8:11]
	v_mfma_f32_16x16x32_bf16 v[60:63], v[154:157], v[224:227], v[60:63]
	v_mfma_f32_16x16x32_bf16 v[56:59], v[162:165], v[224:227], v[56:59]
	v_mfma_f32_16x16x32_bf16 v[44:47], v[154:157], v[232:235], v[44:47]
	v_mfma_f32_16x16x32_bf16 v[40:43], v[162:165], v[232:235], v[40:43]
	v_mfma_f32_16x16x32_bf16 v[28:31], v[154:157], v[240:243], v[28:31]
	v_mfma_f32_16x16x32_bf16 v[24:27], v[162:165], v[240:243], v[24:27]
	v_mfma_f32_16x16x32_bf16 v[12:15], v[154:157], v[248:251], v[12:15]
	v_mfma_f32_16x16x32_bf16 v[8:11], v[162:165], v[248:251], v[8:11]
	s_setprio 0
	s_setprio 1
	v_mfma_f32_16x16x32_bf16 v[52:55], v[166:169], v[220:223], v[52:55]
	v_mfma_f32_16x16x32_bf16 v[48:51], v[174:177], v[220:223], v[48:51]
	v_mfma_f32_16x16x32_bf16 v[36:39], v[166:169], v[228:231], v[36:39]
	v_mfma_f32_16x16x32_bf16 v[32:35], v[174:177], v[228:231], v[32:35]
	v_mfma_f32_16x16x32_bf16 v[20:23], v[166:169], v[236:239], v[20:23]
	v_mfma_f32_16x16x32_bf16 v[16:19], v[174:177], v[236:239], v[16:19]
	v_mfma_f32_16x16x32_bf16 v[4:7], v[166:169], v[244:247], v[4:7]
	v_mfma_f32_16x16x32_bf16 v[0:3], v[174:177], v[244:247], v[0:3]
	v_mfma_f32_16x16x32_bf16 v[52:55], v[170:173], v[224:227], v[52:55]
	v_mfma_f32_16x16x32_bf16 v[48:51], v[178:181], v[224:227], v[48:51]
	v_mfma_f32_16x16x32_bf16 v[36:39], v[170:173], v[232:235], v[36:39]
	v_mfma_f32_16x16x32_bf16 v[32:35], v[178:181], v[232:235], v[32:35]
	v_mfma_f32_16x16x32_bf16 v[20:23], v[170:173], v[240:243], v[20:23]
	v_mfma_f32_16x16x32_bf16 v[16:19], v[178:181], v[240:243], v[16:19]
	v_mfma_f32_16x16x32_bf16 v[4:7], v[170:173], v[248:251], v[4:7]
	v_mfma_f32_16x16x32_bf16 v[0:3], v[178:181], v[248:251], v[0:3]
	s_setprio 0
	s_waitcnt vmcnt(0)
	s_barrier
	s_add_u32 vcc_lo, s30, 0x0
	s_addc_u32 vcc_hi, s31, 0
	s_add_i32 m0, s36, 0x10000
	s_nop 0
	global_load_lds_dwordx4 v132, vcc
	s_add_i32 m0, s36, 0x12000
	s_nop 0
	global_load_lds_dwordx4 v128, vcc
	s_add_u32 vcc_lo, vcc_lo, 0x10000
	s_addc_u32 vcc_hi, vcc_hi, 0
	s_add_i32 m0, s36, 0x11000
	s_nop 0
	global_load_lds_dwordx4 v132, vcc
	s_add_i32 m0, s36, 0x13000
	s_nop 0
	global_load_lds_dwordx4 v128, vcc
	s_add_u32 vcc_lo, vcc_lo, 0x30000
	s_addc_u32 vcc_hi, vcc_hi, 0
	s_add_i32 m0, s36, 0x14000
	s_nop 0
	global_load_lds_dwordx4 v132, vcc
	s_add_i32 m0, s36, 0x16000
	s_nop 0
	global_load_lds_dwordx4 v128, vcc
	s_add_u32 vcc_lo, vcc_lo, 0x10000
	s_addc_u32 vcc_hi, vcc_hi, 0
	s_add_i32 m0, s36, 0x15000
	s_nop 0
	global_load_lds_dwordx4 v132, vcc
	s_add_i32 m0, s36, 0x17000
	s_nop 0
	global_load_lds_dwordx4 v128, vcc
	ds_read_b128 v[144:147], v151 offset:32768
	ds_read_b128 v[154:157], v151 offset:33792
	ds_read_b128 v[158:161], v151 offset:34816
	ds_read_b128 v[162:165], v151 offset:35840
	ds_read_b128 v[166:169], v152 offset:32768
	ds_read_b128 v[170:173], v152 offset:33792
	ds_read_b128 v[174:177], v152 offset:34816
	ds_read_b128 v[178:181], v152 offset:35840
	ds_read_b128 v[182:185], v153 offset:32768
	ds_read_b128 v[186:189], v153 offset:33792
	ds_read_b128 v[190:193], v153 offset:34816
	ds_read_b128 v[194:197], v153 offset:35840
	ds_read_b128 v[198:201], v153 offset:36864
	ds_read_b128 v[202:205], v153 offset:37888
	ds_read_b128 v[206:209], v153 offset:38912
	ds_read_b128 v[210:213], v153 offset:39936
	ds_read_b128 v[220:223], v153 offset:49152
	ds_read_b128 v[224:227], v153 offset:50176
	ds_read_b128 v[228:231], v153 offset:51200
	ds_read_b128 v[232:235], v153 offset:52224
	ds_read_b128 v[236:239], v153 offset:53248
	ds_read_b128 v[240:243], v153 offset:54272
	ds_read_b128 v[244:247], v153 offset:55296
	ds_read_b128 v[248:251], v153 offset:56320
	s_nop 15
	s_nop 15
	s_waitcnt lgkmcnt(0)
	s_barrier
	s_setprio 1
	v_mfma_f32_16x16x32_bf16 v[124:127], v[144:147], v[182:185], v[124:127]
	v_mfma_f32_16x16x32_bf16 v[120:123], v[158:161], v[182:185], v[120:123]
	v_mfma_f32_16x16x32_bf16 v[108:111], v[144:147], v[190:193], v[108:111]
	v_mfma_f32_16x16x32_bf16 v[104:107], v[158:161], v[190:193], v[104:107]
	v_mfma_f32_16x16x32_bf16 v[92:95], v[144:147], v[198:201], v[92:95]
	v_mfma_f32_16x16x32_bf16 v[88:91], v[158:161], v[198:201], v[88:91]
	v_mfma_f32_16x16x32_bf16 v[76:79], v[144:147], v[206:209], v[76:79]
	v_mfma_f32_16x16x32_bf16 v[72:75], v[158:161], v[206:209], v[72:75]
	v_mfma_f32_16x16x32_bf16 v[124:127], v[154:157], v[186:189], v[124:127]
	v_mfma_f32_16x16x32_bf16 v[120:123], v[162:165], v[186:189], v[120:123]
	v_mfma_f32_16x16x32_bf16 v[108:111], v[154:157], v[194:197], v[108:111]
	v_mfma_f32_16x16x32_bf16 v[104:107], v[162:165], v[194:197], v[104:107]
	v_mfma_f32_16x16x32_bf16 v[92:95], v[154:157], v[202:205], v[92:95]
	v_mfma_f32_16x16x32_bf16 v[88:91], v[162:165], v[202:205], v[88:91]
	v_mfma_f32_16x16x32_bf16 v[76:79], v[154:157], v[210:213], v[76:79]
	v_mfma_f32_16x16x32_bf16 v[72:75], v[162:165], v[210:213], v[72:75]
	s_setprio 0
	s_setprio 1
	v_mfma_f32_16x16x32_bf16 v[116:119], v[166:169], v[182:185], v[116:119]
	v_mfma_f32_16x16x32_bf16 v[112:115], v[174:177], v[182:185], v[112:115]
	v_mfma_f32_16x16x32_bf16 v[100:103], v[166:169], v[190:193], v[100:103]
	v_mfma_f32_16x16x32_bf16 v[96:99], v[174:177], v[190:193], v[96:99]
	v_mfma_f32_16x16x32_bf16 v[84:87], v[166:169], v[198:201], v[84:87]
	v_mfma_f32_16x16x32_bf16 v[80:83], v[174:177], v[198:201], v[80:83]
	v_mfma_f32_16x16x32_bf16 v[68:71], v[166:169], v[206:209], v[68:71]
	v_mfma_f32_16x16x32_bf16 v[64:67], v[174:177], v[206:209], v[64:67]
	v_mfma_f32_16x16x32_bf16 v[116:119], v[170:173], v[186:189], v[116:119]
	v_mfma_f32_16x16x32_bf16 v[112:115], v[178:181], v[186:189], v[112:115]
	v_mfma_f32_16x16x32_bf16 v[100:103], v[170:173], v[194:197], v[100:103]
	v_mfma_f32_16x16x32_bf16 v[96:99], v[178:181], v[194:197], v[96:99]
	v_mfma_f32_16x16x32_bf16 v[84:87], v[170:173], v[202:205], v[84:87]
	v_mfma_f32_16x16x32_bf16 v[80:83], v[178:181], v[202:205], v[80:83]
	v_mfma_f32_16x16x32_bf16 v[68:71], v[170:173], v[210:213], v[68:71]
	v_mfma_f32_16x16x32_bf16 v[64:67], v[178:181], v[210:213], v[64:67]
	s_setprio 0
	s_setprio 1
	v_mfma_f32_16x16x32_bf16 v[60:63], v[144:147], v[220:223], v[60:63]
	v_mfma_f32_16x16x32_bf16 v[56:59], v[158:161], v[220:223], v[56:59]
	v_mfma_f32_16x16x32_bf16 v[44:47], v[144:147], v[228:231], v[44:47]
	v_mfma_f32_16x16x32_bf16 v[40:43], v[158:161], v[228:231], v[40:43]
	v_mfma_f32_16x16x32_bf16 v[28:31], v[144:147], v[236:239], v[28:31]
	v_mfma_f32_16x16x32_bf16 v[24:27], v[158:161], v[236:239], v[24:27]
	v_mfma_f32_16x16x32_bf16 v[12:15], v[144:147], v[244:247], v[12:15]
	v_mfma_f32_16x16x32_bf16 v[8:11], v[158:161], v[244:247], v[8:11]
	v_mfma_f32_16x16x32_bf16 v[60:63], v[154:157], v[224:227], v[60:63]
	v_mfma_f32_16x16x32_bf16 v[56:59], v[162:165], v[224:227], v[56:59]
	v_mfma_f32_16x16x32_bf16 v[44:47], v[154:157], v[232:235], v[44:47]
	v_mfma_f32_16x16x32_bf16 v[40:43], v[162:165], v[232:235], v[40:43]
	v_mfma_f32_16x16x32_bf16 v[28:31], v[154:157], v[240:243], v[28:31]
	v_mfma_f32_16x16x32_bf16 v[24:27], v[162:165], v[240:243], v[24:27]
	v_mfma_f32_16x16x32_bf16 v[12:15], v[154:157], v[248:251], v[12:15]
	v_mfma_f32_16x16x32_bf16 v[8:11], v[162:165], v[248:251], v[8:11]
	s_setprio 0
	s_setprio 1
	v_mfma_f32_16x16x32_bf16 v[52:55], v[166:169], v[220:223], v[52:55]
	v_mfma_f32_16x16x32_bf16 v[48:51], v[174:177], v[220:223], v[48:51]
	v_mfma_f32_16x16x32_bf16 v[36:39], v[166:169], v[228:231], v[36:39]
	v_mfma_f32_16x16x32_bf16 v[32:35], v[174:177], v[228:231], v[32:35]
	v_mfma_f32_16x16x32_bf16 v[20:23], v[166:169], v[236:239], v[20:23]
	v_mfma_f32_16x16x32_bf16 v[16:19], v[174:177], v[236:239], v[16:19]
	v_mfma_f32_16x16x32_bf16 v[4:7], v[166:169], v[244:247], v[4:7]
	v_mfma_f32_16x16x32_bf16 v[0:3], v[174:177], v[244:247], v[0:3]
	v_mfma_f32_16x16x32_bf16 v[52:55], v[170:173], v[224:227], v[52:55]
	v_mfma_f32_16x16x32_bf16 v[48:51], v[178:181], v[224:227], v[48:51]
	v_mfma_f32_16x16x32_bf16 v[36:39], v[170:173], v[232:235], v[36:39]
	v_mfma_f32_16x16x32_bf16 v[32:35], v[178:181], v[232:235], v[32:35]
	v_mfma_f32_16x16x32_bf16 v[20:23], v[170:173], v[240:243], v[20:23]
	v_mfma_f32_16x16x32_bf16 v[16:19], v[178:181], v[240:243], v[16:19]
	v_mfma_f32_16x16x32_bf16 v[4:7], v[170:173], v[248:251], v[4:7]
	v_mfma_f32_16x16x32_bf16 v[0:3], v[178:181], v[248:251], v[0:3]
	s_setprio 0
	s_add_i32 s56, s56, 2
	s_add_u32 s12, s12, 0x100
	s_addc_u32 s13, s13, 0
	s_add_u32 s54, s54, 0x100
	s_addc_u32 s55, s55, 0
	s_add_u32 s30, s12, 0xfffc0080
	s_addc_u32 s31, s13, -1
	s_cmp_eq_u32 s56, 12
	s_cselect_b32 s35, s25, s31
	s_cselect_b32 s34, s49, s30
	s_cselect_b32 s31, s23, s55
	s_cselect_b32 s30, s51, s54
	s_cmp_gt_u32 s56, 13
	s_waitcnt vmcnt(0)
	s_barrier
	s_cbranch_scc0 .Lk64_lead_p4
	s_branch .Lk64_done_p4
.Lk64_trail_p4:
	s_sub_u32 vcc_lo, s12, 0x40000
	s_subb_u32 vcc_hi, s13, 0
	s_add_i32 m0, s36, 0xa000
	s_nop 0
	global_load_lds_dwordx4 v130, vcc
	s_add_u32 vcc_lo, vcc_lo, 0x10000
	s_addc_u32 vcc_hi, vcc_hi, 0
	s_add_i32 m0, s36, 0x9000
	s_nop 0
	global_load_lds_dwordx4 v134, vcc
	s_add_u32 vcc_lo, vcc_lo, 0x30000
	s_addc_u32 vcc_hi, vcc_hi, 0
	s_add_i32 m0, s36, 0xe000
	s_nop 0
	global_load_lds_dwordx4 v130, vcc
	s_add_u32 vcc_lo, vcc_lo, 0x10000
	s_addc_u32 vcc_hi, vcc_hi, 0
	s_add_i32 m0, s36, 0xd000
	s_nop 0
	global_load_lds_dwordx4 v134, vcc
	s_add_u32 vcc_lo, s34, 0x0
	s_addc_u32 vcc_hi, s35, 0
	s_mov_b32 m0, s36
	s_nop 0
	global_load_lds_dwordx4 v134, vcc
	s_sub_u32 vcc_lo, vcc_lo, 0x10000
	s_subb_u32 vcc_hi, vcc_hi, 0
	s_sub_i32 m0, s36, 0x1000
	s_nop 0
	global_load_lds_dwordx4 v134, vcc
	s_add_u32 vcc_lo, vcc_lo, 0x50000
	s_addc_u32 vcc_hi, vcc_hi, 0
	s_add_i32 m0, s36, 0x4000
	s_nop 0
	global_load_lds_dwordx4 v134, vcc
	s_sub_u32 vcc_lo, vcc_lo, 0x10000
	s_subb_u32 vcc_hi, vcc_hi, 0
	s_add_i32 m0, s36, 0x3000
	s_nop 0
	global_load_lds_dwordx4 v134, vcc
	ds_read_b128 v[144:147], v151 offset:0
	ds_read_b128 v[154:157], v151 offset:1024
	ds_read_b128 v[158:161], v151 offset:2048
	ds_read_b128 v[162:165], v151 offset:3072
	ds_read_b128 v[166:169], v152 offset:0
	ds_read_b128 v[170:173], v152 offset:1024
	ds_read_b128 v[174:177], v152 offset:2048
	ds_read_b128 v[178:181], v152 offset:3072
	ds_read_b128 v[182:185], v153 offset:0
	ds_read_b128 v[186:189], v153 offset:1024
	ds_read_b128 v[190:193], v153 offset:2048
	ds_read_b128 v[194:197], v153 offset:3072
	ds_read_b128 v[198:201], v153 offset:4096
	ds_read_b128 v[202:205], v153 offset:5120
	ds_read_b128 v[206:209], v153 offset:6144
	ds_read_b128 v[210:213], v153 offset:7168
	ds_read_b128 v[220:223], v153 offset:16384
	ds_read_b128 v[224:227], v153 offset:17408
	ds_read_b128 v[228:231], v153 offset:18432
	ds_read_b128 v[232:235], v153 offset:19456
	ds_read_b128 v[236:239], v153 offset:20480
	ds_read_b128 v[240:243], v153 offset:21504
	ds_read_b128 v[244:247], v153 offset:22528
	ds_read_b128 v[248:251], v153 offset:23552
	s_nop 15
	s_nop 15
	s_waitcnt lgkmcnt(0)
	s_barrier
	s_setprio 1
	v_mfma_f32_16x16x32_bf16 v[124:127], v[144:147], v[182:185], v[124:127]
	v_mfma_f32_16x16x32_bf16 v[120:123], v[158:161], v[182:185], v[120:123]
	v_mfma_f32_16x16x32_bf16 v[108:111], v[144:147], v[190:193], v[108:111]
	v_mfma_f32_16x16x32_bf16 v[104:107], v[158:161], v[190:193], v[104:107]
	v_mfma_f32_16x16x32_bf16 v[92:95], v[144:147], v[198:201], v[92:95]
	v_mfma_f32_16x16x32_bf16 v[88:91], v[158:161], v[198:201], v[88:91]
	v_mfma_f32_16x16x32_bf16 v[76:79], v[144:147], v[206:209], v[76:79]
	v_mfma_f32_16x16x32_bf16 v[72:75], v[158:161], v[206:209], v[72:75]
	v_mfma_f32_16x16x32_bf16 v[124:127], v[154:157], v[186:189], v[124:127]
	v_mfma_f32_16x16x32_bf16 v[120:123], v[162:165], v[186:189], v[120:123]
	v_mfma_f32_16x16x32_bf16 v[108:111], v[154:157], v[194:197], v[108:111]
	v_mfma_f32_16x16x32_bf16 v[104:107], v[162:165], v[194:197], v[104:107]
	v_mfma_f32_16x16x32_bf16 v[92:95], v[154:157], v[202:205], v[92:95]
	v_mfma_f32_16x16x32_bf16 v[88:91], v[162:165], v[202:205], v[88:91]
	v_mfma_f32_16x16x32_bf16 v[76:79], v[154:157], v[210:213], v[76:79]
	v_mfma_f32_16x16x32_bf16 v[72:75], v[162:165], v[210:213], v[72:75]
	s_setprio 0
	s_setprio 1
	v_mfma_f32_16x16x32_bf16 v[116:119], v[166:169], v[182:185], v[116:119]
	v_mfma_f32_16x16x32_bf16 v[112:115], v[174:177], v[182:185], v[112:115]
	v_mfma_f32_16x16x32_bf16 v[100:103], v[166:169], v[190:193], v[100:103]
	v_mfma_f32_16x16x32_bf16 v[96:99], v[174:177], v[190:193], v[96:99]
	v_mfma_f32_16x16x32_bf16 v[84:87], v[166:169], v[198:201], v[84:87]
	v_mfma_f32_16x16x32_bf16 v[80:83], v[174:177], v[198:201], v[80:83]
	v_mfma_f32_16x16x32_bf16 v[68:71], v[166:169], v[206:209], v[68:71]
	v_mfma_f32_16x16x32_bf16 v[64:67], v[174:177], v[206:209], v[64:67]
	v_mfma_f32_16x16x32_bf16 v[116:119], v[170:173], v[186:189], v[116:119]
	v_mfma_f32_16x16x32_bf16 v[112:115], v[178:181], v[186:189], v[112:115]
	v_mfma_f32_16x16x32_bf16 v[100:103], v[170:173], v[194:197], v[100:103]
	v_mfma_f32_16x16x32_bf16 v[96:99], v[178:181], v[194:197], v[96:99]
	v_mfma_f32_16x16x32_bf16 v[84:87], v[170:173], v[202:205], v[84:87]
	v_mfma_f32_16x16x32_bf16 v[80:83], v[178:181], v[202:205], v[80:83]
	v_mfma_f32_16x16x32_bf16 v[68:71], v[170:173], v[210:213], v[68:71]
	v_mfma_f32_16x16x32_bf16 v[64:67], v[178:181], v[210:213], v[64:67]
	s_setprio 0
	s_setprio 1
	v_mfma_f32_16x16x32_bf16 v[60:63], v[144:147], v[220:223], v[60:63]
	v_mfma_f32_16x16x32_bf16 v[56:59], v[158:161], v[220:223], v[56:59]
	v_mfma_f32_16x16x32_bf16 v[44:47], v[144:147], v[228:231], v[44:47]
	v_mfma_f32_16x16x32_bf16 v[40:43], v[158:161], v[228:231], v[40:43]
	v_mfma_f32_16x16x32_bf16 v[28:31], v[144:147], v[236:239], v[28:31]
	v_mfma_f32_16x16x32_bf16 v[24:27], v[158:161], v[236:239], v[24:27]
	v_mfma_f32_16x16x32_bf16 v[12:15], v[144:147], v[244:247], v[12:15]
	v_mfma_f32_16x16x32_bf16 v[8:11], v[158:161], v[244:247], v[8:11]
	v_mfma_f32_16x16x32_bf16 v[60:63], v[154:157], v[224:227], v[60:63]
	v_mfma_f32_16x16x32_bf16 v[56:59], v[162:165], v[224:227], v[56:59]
	v_mfma_f32_16x16x32_bf16 v[44:47], v[154:157], v[232:235], v[44:47]
	v_mfma_f32_16x16x32_bf16 v[40:43], v[162:165], v[232:235], v[40:43]
	v_mfma_f32_16x16x32_bf16 v[28:31], v[154:157], v[240:243], v[28:31]
	v_mfma_f32_16x16x32_bf16 v[24:27], v[162:165], v[240:243], v[24:27]
	v_mfma_f32_16x16x32_bf16 v[12:15], v[154:157], v[248:251], v[12:15]
	v_mfma_f32_16x16x32_bf16 v[8:11], v[162:165], v[248:251], v[8:11]
	s_setprio 0
	s_setprio 1
	v_mfma_f32_16x16x32_bf16 v[52:55], v[166:169], v[220:223], v[52:55]
	v_mfma_f32_16x16x32_bf16 v[48:51], v[174:177], v[220:223], v[48:51]
	v_mfma_f32_16x16x32_bf16 v[36:39], v[166:169], v[228:231], v[36:39]
	v_mfma_f32_16x16x32_bf16 v[32:35], v[174:177], v[228:231], v[32:35]
	v_mfma_f32_16x16x32_bf16 v[20:23], v[166:169], v[236:239], v[20:23]
	v_mfma_f32_16x16x32_bf16 v[16:19], v[174:177], v[236:239], v[16:19]
	v_mfma_f32_16x16x32_bf16 v[4:7], v[166:169], v[244:247], v[4:7]
	v_mfma_f32_16x16x32_bf16 v[0:3], v[174:177], v[244:247], v[0:3]
	v_mfma_f32_16x16x32_bf16 v[52:55], v[170:173], v[224:227], v[52:55]
	v_mfma_f32_16x16x32_bf16 v[48:51], v[178:181], v[224:227], v[48:51]
	v_mfma_f32_16x16x32_bf16 v[36:39], v[170:173], v[232:235], v[36:39]
	v_mfma_f32_16x16x32_bf16 v[32:35], v[178:181], v[232:235], v[32:35]
	v_mfma_f32_16x16x32_bf16 v[20:23], v[170:173], v[240:243], v[20:23]
	v_mfma_f32_16x16x32_bf16 v[16:19], v[178:181], v[240:243], v[16:19]
	v_mfma_f32_16x16x32_bf16 v[4:7], v[170:173], v[248:251], v[4:7]
	v_mfma_f32_16x16x32_bf16 v[0:3], v[178:181], v[248:251], v[0:3]
	s_setprio 0
	s_waitcnt vmcnt(0)
	s_barrier
	s_add_u32 vcc_lo, s34, 0x0
	s_addc_u32 vcc_hi, s35, 0
	s_add_i32 m0, s36, 0x2000
	s_nop 0
	global_load_lds_dwordx4 v130, vcc
	s_add_u32 vcc_lo, vcc_lo, 0x10000
	s_addc_u32 vcc_hi, vcc_hi, 0
	s_add_i32 m0, s36, 0x1000
	s_nop 0
	global_load_lds_dwordx4 v134, vcc
	s_add_u32 vcc_lo, vcc_lo, 0x30000
	s_addc_u32 vcc_hi, vcc_hi, 0
	s_add_i32 m0, s36, 0x6000
	s_nop 0
	global_load_lds_dwordx4 v130, vcc
	s_add_u32 vcc_lo, vcc_lo, 0x10000
	s_addc_u32 vcc_hi, vcc_hi, 0
	s_add_i32 m0, s36, 0x5000
	s_nop 0
	global_load_lds_dwordx4 v134, vcc
	s_add_u32 vcc_lo, s34, 0x80
	s_addc_u32 vcc_hi, s35, 0
	s_add_i32 m0, s36, 0x8000
	s_nop 0
	global_load_lds_dwordx4 v134, vcc
	s_sub_u32 vcc_lo, vcc_lo, 0x10000
	s_subb_u32 vcc_hi, vcc_hi, 0
	s_add_i32 m0, s36, 0x7000
	s_nop 0
	global_load_lds_dwordx4 v134, vcc
	s_add_u32 vcc_lo, vcc_lo, 0x50000
	s_addc_u32 vcc_hi, vcc_hi, 0
	s_add_i32 m0, s36, 0xc000
	s_nop 0
	global_load_lds_dwordx4 v134, vcc
	s_sub_u32 vcc_lo, vcc_lo, 0x10000
	s_subb_u32 vcc_hi, vcc_hi, 0
	s_add_i32 m0, s36, 0xb000
	s_nop 0
	global_load_lds_dwordx4 v134, vcc
	ds_read_b128 v[144:147], v151 offset:32768
	ds_read_b128 v[154:157], v151 offset:33792
	ds_read_b128 v[158:161], v151 offset:34816
	ds_read_b128 v[162:165], v151 offset:35840
	ds_read_b128 v[166:169], v152 offset:32768
	ds_read_b128 v[170:173], v152 offset:33792
	ds_read_b128 v[174:177], v152 offset:34816
	ds_read_b128 v[178:181], v152 offset:35840
	ds_read_b128 v[182:185], v153 offset:32768
	ds_read_b128 v[186:189], v153 offset:33792
	ds_read_b128 v[190:193], v153 offset:34816
	ds_read_b128 v[194:197], v153 offset:35840
	ds_read_b128 v[198:201], v153 offset:36864
	ds_read_b128 v[202:205], v153 offset:37888
	ds_read_b128 v[206:209], v153 offset:38912
	ds_read_b128 v[210:213], v153 offset:39936
	ds_read_b128 v[220:223], v153 offset:49152
	ds_read_b128 v[224:227], v153 offset:50176
	ds_read_b128 v[228:231], v153 offset:51200
	ds_read_b128 v[232:235], v153 offset:52224
	ds_read_b128 v[236:239], v153 offset:53248
	ds_read_b128 v[240:243], v153 offset:54272
	ds_read_b128 v[244:247], v153 offset:55296
	ds_read_b128 v[248:251], v153 offset:56320
	s_nop 15
	s_nop 15
	s_waitcnt lgkmcnt(0)
	s_barrier
	s_setprio 1
	v_mfma_f32_16x16x32_bf16 v[124:127], v[144:147], v[182:185], v[124:127]
	v_mfma_f32_16x16x32_bf16 v[120:123], v[158:161], v[182:185], v[120:123]
	v_mfma_f32_16x16x32_bf16 v[108:111], v[144:147], v[190:193], v[108:111]
	v_mfma_f32_16x16x32_bf16 v[104:107], v[158:161], v[190:193], v[104:107]
	v_mfma_f32_16x16x32_bf16 v[92:95], v[144:147], v[198:201], v[92:95]
	v_mfma_f32_16x16x32_bf16 v[88:91], v[158:161], v[198:201], v[88:91]
	v_mfma_f32_16x16x32_bf16 v[76:79], v[144:147], v[206:209], v[76:79]
	v_mfma_f32_16x16x32_bf16 v[72:75], v[158:161], v[206:209], v[72:75]
	v_mfma_f32_16x16x32_bf16 v[124:127], v[154:157], v[186:189], v[124:127]
	v_mfma_f32_16x16x32_bf16 v[120:123], v[162:165], v[186:189], v[120:123]
	v_mfma_f32_16x16x32_bf16 v[108:111], v[154:157], v[194:197], v[108:111]
	v_mfma_f32_16x16x32_bf16 v[104:107], v[162:165], v[194:197], v[104:107]
	v_mfma_f32_16x16x32_bf16 v[92:95], v[154:157], v[202:205], v[92:95]
	v_mfma_f32_16x16x32_bf16 v[88:91], v[162:165], v[202:205], v[88:91]
	v_mfma_f32_16x16x32_bf16 v[76:79], v[154:157], v[210:213], v[76:79]
	v_mfma_f32_16x16x32_bf16 v[72:75], v[162:165], v[210:213], v[72:75]
	s_setprio 0
	s_setprio 1
	v_mfma_f32_16x16x32_bf16 v[116:119], v[166:169], v[182:185], v[116:119]
	v_mfma_f32_16x16x32_bf16 v[112:115], v[174:177], v[182:185], v[112:115]
	v_mfma_f32_16x16x32_bf16 v[100:103], v[166:169], v[190:193], v[100:103]
	v_mfma_f32_16x16x32_bf16 v[96:99], v[174:177], v[190:193], v[96:99]
	v_mfma_f32_16x16x32_bf16 v[84:87], v[166:169], v[198:201], v[84:87]
	v_mfma_f32_16x16x32_bf16 v[80:83], v[174:177], v[198:201], v[80:83]
	v_mfma_f32_16x16x32_bf16 v[68:71], v[166:169], v[206:209], v[68:71]
	v_mfma_f32_16x16x32_bf16 v[64:67], v[174:177], v[206:209], v[64:67]
	v_mfma_f32_16x16x32_bf16 v[116:119], v[170:173], v[186:189], v[116:119]
	v_mfma_f32_16x16x32_bf16 v[112:115], v[178:181], v[186:189], v[112:115]
	v_mfma_f32_16x16x32_bf16 v[100:103], v[170:173], v[194:197], v[100:103]
	v_mfma_f32_16x16x32_bf16 v[96:99], v[178:181], v[194:197], v[96:99]
	v_mfma_f32_16x16x32_bf16 v[84:87], v[170:173], v[202:205], v[84:87]
	v_mfma_f32_16x16x32_bf16 v[80:83], v[178:181], v[202:205], v[80:83]
	v_mfma_f32_16x16x32_bf16 v[68:71], v[170:173], v[210:213], v[68:71]
	v_mfma_f32_16x16x32_bf16 v[64:67], v[178:181], v[210:213], v[64:67]
	s_setprio 0
	s_setprio 1
	v_mfma_f32_16x16x32_bf16 v[60:63], v[144:147], v[220:223], v[60:63]
	v_mfma_f32_16x16x32_bf16 v[56:59], v[158:161], v[220:223], v[56:59]
	v_mfma_f32_16x16x32_bf16 v[44:47], v[144:147], v[228:231], v[44:47]
	v_mfma_f32_16x16x32_bf16 v[40:43], v[158:161], v[228:231], v[40:43]
	v_mfma_f32_16x16x32_bf16 v[28:31], v[144:147], v[236:239], v[28:31]
	v_mfma_f32_16x16x32_bf16 v[24:27], v[158:161], v[236:239], v[24:27]
	v_mfma_f32_16x16x32_bf16 v[12:15], v[144:147], v[244:247], v[12:15]
	v_mfma_f32_16x16x32_bf16 v[8:11], v[158:161], v[244:247], v[8:11]
	v_mfma_f32_16x16x32_bf16 v[60:63], v[154:157], v[224:227], v[60:63]
	v_mfma_f32_16x16x32_bf16 v[56:59], v[162:165], v[224:227], v[56:59]
	v_mfma_f32_16x16x32_bf16 v[44:47], v[154:157], v[232:235], v[44:47]
	v_mfma_f32_16x16x32_bf16 v[40:43], v[162:165], v[232:235], v[40:43]
	v_mfma_f32_16x16x32_bf16 v[28:31], v[154:157], v[240:243], v[28:31]
	v_mfma_f32_16x16x32_bf16 v[24:27], v[162:165], v[240:243], v[24:27]
	v_mfma_f32_16x16x32_bf16 v[12:15], v[154:157], v[248:251], v[12:15]
	v_mfma_f32_16x16x32_bf16 v[8:11], v[162:165], v[248:251], v[8:11]
	s_setprio 0
	s_setprio 1
	v_mfma_f32_16x16x32_bf16 v[52:55], v[166:169], v[220:223], v[52:55]
	v_mfma_f32_16x16x32_bf16 v[48:51], v[174:177], v[220:223], v[48:51]
	v_mfma_f32_16x16x32_bf16 v[36:39], v[166:169], v[228:231], v[36:39]
	v_mfma_f32_16x16x32_bf16 v[32:35], v[174:177], v[228:231], v[32:35]
	v_mfma_f32_16x16x32_bf16 v[20:23], v[166:169], v[236:239], v[20:23]
	v_mfma_f32_16x16x32_bf16 v[16:19], v[174:177], v[236:239], v[16:19]
	v_mfma_f32_16x16x32_bf16 v[4:7], v[166:169], v[244:247], v[4:7]
	v_mfma_f32_16x16x32_bf16 v[0:3], v[174:177], v[244:247], v[0:3]
	v_mfma_f32_16x16x32_bf16 v[52:55], v[170:173], v[224:227], v[52:55]
	v_mfma_f32_16x16x32_bf16 v[48:51], v[178:181], v[224:227], v[48:51]
	v_mfma_f32_16x16x32_bf16 v[36:39], v[170:173], v[232:235], v[36:39]
	v_mfma_f32_16x16x32_bf16 v[32:35], v[178:181], v[232:235], v[32:35]
	v_mfma_f32_16x16x32_bf16 v[20:23], v[170:173], v[240:243], v[20:23]
	v_mfma_f32_16x16x32_bf16 v[16:19], v[178:181], v[240:243], v[16:19]
	v_mfma_f32_16x16x32_bf16 v[4:7], v[170:173], v[248:251], v[4:7]
	v_mfma_f32_16x16x32_bf16 v[0:3], v[178:181], v[248:251], v[0:3]
	s_setprio 0
	s_add_i32 s56, s56, 2
	s_add_u32 s12, s12, 0x100
	s_addc_u32 s13, s13, 0
	s_add_u32 s54, s54, 0x100
	s_addc_u32 s55, s55, 0
	s_add_u32 s30, s12, 0xfffc0080
	s_addc_u32 s31, s13, -1
	s_cmp_eq_u32 s56, 12
	s_cselect_b32 s35, s25, s31
	s_cselect_b32 s34, s49, s30
	s_cselect_b32 s31, s23, s55
	s_cselect_b32 s30, s51, s54
	s_cmp_gt_u32 s56, 13
	s_waitcnt vmcnt(0)
	s_barrier
	s_cbranch_scc0 .Lk64_trail_p4

.Lk64_lead_p5:
	s_sub_u32 vcc_lo, s56, 0x80
	s_subb_u32 vcc_hi, s57, 0
	s_add_i32 m0, s44, 0x18000
	s_nop 0
	global_load_lds_dwordx4 v130, vcc
	s_add_i32 m0, s44, 0x1a000
	s_nop 0
	global_load_lds_dwordx4 v134, vcc
	s_add_u32 vcc_lo, vcc_lo, 0x20000
	s_addc_u32 vcc_hi, vcc_hi, 0
	s_add_i32 m0, s44, 0x19000
	s_nop 0
	global_load_lds_dwordx4 v130, vcc
	s_add_i32 m0, s44, 0x1b000
	s_nop 0
	global_load_lds_dwordx4 v134, vcc
	s_add_u32 vcc_lo, vcc_lo, 0x60000
	s_addc_u32 vcc_hi, vcc_hi, 0
	s_add_i32 m0, s44, 0x1c000
	s_nop 0
	global_load_lds_dwordx4 v130, vcc
	s_add_i32 m0, s44, 0x1e000
	s_nop 0
	global_load_lds_dwordx4 v134, vcc
	s_add_u32 vcc_lo, vcc_lo, 0x20000
	s_addc_u32 vcc_hi, vcc_hi, 0
	s_add_i32 m0, s44, 0x1d000
	s_nop 0
	global_load_lds_dwordx4 v130, vcc
	s_add_i32 m0, s44, 0x1f000
	s_nop 0
	global_load_lds_dwordx4 v134, vcc
	ds_read_b128 v[144:147], v153 offset:0
	ds_read_b128 v[158:161], v153 offset:1024
	ds_read_b128 v[162:165], v153 offset:2048
	ds_read_b128 v[166:169], v153 offset:3072
	ds_read_b128 v[170:173], v154 offset:0
	ds_read_b128 v[174:177], v154 offset:1024
	ds_read_b128 v[178:181], v154 offset:2048
	ds_read_b128 v[182:185], v154 offset:3072
	ds_read_b128 v[186:189], v155 offset:0
	ds_read_b128 v[190:193], v155 offset:1024
	ds_read_b128 v[194:197], v155 offset:2048
	ds_read_b128 v[198:201], v155 offset:3072
	ds_read_b128 v[202:205], v155 offset:4096
	ds_read_b128 v[206:209], v155 offset:5120
	ds_read_b128 v[210:213], v155 offset:6144
	ds_read_b128 v[214:217], v155 offset:7168
	ds_read_b128 v[220:223], v155 offset:16384
	ds_read_b128 v[224:227], v155 offset:17408
	ds_read_b128 v[228:231], v155 offset:18432
	ds_read_b128 v[232:235], v155 offset:19456
	ds_read_b128 v[236:239], v155 offset:20480
	ds_read_b128 v[240:243], v155 offset:21504
	ds_read_b128 v[244:247], v155 offset:22528
	ds_read_b128 v[248:251], v155 offset:23552
	s_nop 15
	s_nop 15
	s_waitcnt lgkmcnt(0)
	s_barrier
	s_setprio 1
	v_mfma_f32_16x16x32_bf16 v[124:127], v[144:147], v[186:189], v[124:127]
	v_mfma_f32_16x16x32_bf16 v[120:123], v[162:165], v[186:189], v[120:123]
	v_mfma_f32_16x16x32_bf16 v[108:111], v[144:147], v[194:197], v[108:111]
	v_mfma_f32_16x16x32_bf16 v[104:107], v[162:165], v[194:197], v[104:107]
	v_mfma_f32_16x16x32_bf16 v[92:95], v[144:147], v[202:205], v[92:95]
	v_mfma_f32_16x16x32_bf16 v[88:91], v[162:165], v[202:205], v[88:91]
	v_mfma_f32_16x16x32_bf16 v[76:79], v[144:147], v[210:213], v[76:79]
	v_mfma_f32_16x16x32_bf16 v[72:75], v[162:165], v[210:213], v[72:75]
	v_mfma_f32_16x16x32_bf16 v[124:127], v[158:161], v[190:193], v[124:127]
	v_mfma_f32_16x16x32_bf16 v[120:123], v[166:169], v[190:193], v[120:123]
	v_mfma_f32_16x16x32_bf16 v[108:111], v[158:161], v[198:201], v[108:111]
	v_mfma_f32_16x16x32_bf16 v[104:107], v[166:169], v[198:201], v[104:107]
	v_mfma_f32_16x16x32_bf16 v[92:95], v[158:161], v[206:209], v[92:95]
	v_mfma_f32_16x16x32_bf16 v[88:91], v[166:169], v[206:209], v[88:91]
	v_mfma_f32_16x16x32_bf16 v[76:79], v[158:161], v[214:217], v[76:79]
	v_mfma_f32_16x16x32_bf16 v[72:75], v[166:169], v[214:217], v[72:75]
	s_setprio 0
	s_setprio 1
	v_mfma_f32_16x16x32_bf16 v[116:119], v[170:173], v[186:189], v[116:119]
	v_mfma_f32_16x16x32_bf16 v[112:115], v[178:181], v[186:189], v[112:115]
	v_mfma_f32_16x16x32_bf16 v[100:103], v[170:173], v[194:197], v[100:103]
	v_mfma_f32_16x16x32_bf16 v[96:99], v[178:181], v[194:197], v[96:99]
	v_mfma_f32_16x16x32_bf16 v[84:87], v[170:173], v[202:205], v[84:87]
	v_mfma_f32_16x16x32_bf16 v[80:83], v[178:181], v[202:205], v[80:83]
	v_mfma_f32_16x16x32_bf16 v[68:71], v[170:173], v[210:213], v[68:71]
	v_mfma_f32_16x16x32_bf16 v[64:67], v[178:181], v[210:213], v[64:67]
	v_mfma_f32_16x16x32_bf16 v[116:119], v[174:177], v[190:193], v[116:119]
	v_mfma_f32_16x16x32_bf16 v[112:115], v[182:185], v[190:193], v[112:115]
	v_mfma_f32_16x16x32_bf16 v[100:103], v[174:177], v[198:201], v[100:103]
	v_mfma_f32_16x16x32_bf16 v[96:99], v[182:185], v[198:201], v[96:99]
	v_mfma_f32_16x16x32_bf16 v[84:87], v[174:177], v[206:209], v[84:87]
	v_mfma_f32_16x16x32_bf16 v[80:83], v[182:185], v[206:209], v[80:83]
	v_mfma_f32_16x16x32_bf16 v[68:71], v[174:177], v[214:217], v[68:71]
	v_mfma_f32_16x16x32_bf16 v[64:67], v[182:185], v[214:217], v[64:67]
	s_setprio 0
	s_setprio 1
	v_mfma_f32_16x16x32_bf16 v[60:63], v[144:147], v[220:223], v[60:63]
	v_mfma_f32_16x16x32_bf16 v[56:59], v[162:165], v[220:223], v[56:59]
	v_mfma_f32_16x16x32_bf16 v[44:47], v[144:147], v[228:231], v[44:47]
	v_mfma_f32_16x16x32_bf16 v[40:43], v[162:165], v[228:231], v[40:43]
	v_mfma_f32_16x16x32_bf16 v[28:31], v[144:147], v[236:239], v[28:31]
	v_mfma_f32_16x16x32_bf16 v[24:27], v[162:165], v[236:239], v[24:27]
	v_mfma_f32_16x16x32_bf16 v[12:15], v[144:147], v[244:247], v[12:15]
	v_mfma_f32_16x16x32_bf16 v[8:11], v[162:165], v[244:247], v[8:11]
	v_mfma_f32_16x16x32_bf16 v[60:63], v[158:161], v[224:227], v[60:63]
	v_mfma_f32_16x16x32_bf16 v[56:59], v[166:169], v[224:227], v[56:59]
	v_mfma_f32_16x16x32_bf16 v[44:47], v[158:161], v[232:235], v[44:47]
	v_mfma_f32_16x16x32_bf16 v[40:43], v[166:169], v[232:235], v[40:43]
	v_mfma_f32_16x16x32_bf16 v[28:31], v[158:161], v[240:243], v[28:31]
	v_mfma_f32_16x16x32_bf16 v[24:27], v[166:169], v[240:243], v[24:27]
	v_mfma_f32_16x16x32_bf16 v[12:15], v[158:161], v[248:251], v[12:15]
	v_mfma_f32_16x16x32_bf16 v[8:11], v[166:169], v[248:251], v[8:11]
	s_setprio 0
	s_setprio 1
	v_mfma_f32_16x16x32_bf16 v[52:55], v[170:173], v[220:223], v[52:55]
	v_mfma_f32_16x16x32_bf16 v[48:51], v[178:181], v[220:223], v[48:51]
	v_mfma_f32_16x16x32_bf16 v[36:39], v[170:173], v[228:231], v[36:39]
	v_mfma_f32_16x16x32_bf16 v[32:35], v[178:181], v[228:231], v[32:35]
	v_mfma_f32_16x16x32_bf16 v[20:23], v[170:173], v[236:239], v[20:23]
	v_mfma_f32_16x16x32_bf16 v[16:19], v[178:181], v[236:239], v[16:19]
	v_mfma_f32_16x16x32_bf16 v[4:7], v[170:173], v[244:247], v[4:7]
	v_mfma_f32_16x16x32_bf16 v[0:3], v[178:181], v[244:247], v[0:3]
	v_mfma_f32_16x16x32_bf16 v[52:55], v[174:177], v[224:227], v[52:55]
	v_mfma_f32_16x16x32_bf16 v[48:51], v[182:185], v[224:227], v[48:51]
	v_mfma_f32_16x16x32_bf16 v[36:39], v[174:177], v[232:235], v[36:39]
	v_mfma_f32_16x16x32_bf16 v[32:35], v[182:185], v[232:235], v[32:35]
	v_mfma_f32_16x16x32_bf16 v[20:23], v[174:177], v[240:243], v[20:23]
	v_mfma_f32_16x16x32_bf16 v[16:19], v[182:185], v[240:243], v[16:19]
	v_mfma_f32_16x16x32_bf16 v[4:7], v[174:177], v[248:251], v[4:7]
	v_mfma_f32_16x16x32_bf16 v[0:3], v[182:185], v[248:251], v[0:3]
	s_setprio 0
	s_waitcnt vmcnt(0)
	s_barrier
	s_add_u32 vcc_lo, s36, 0x0
	s_addc_u32 vcc_hi, s37, 0
	s_add_i32 m0, s44, 0x10000
	s_nop 0
	global_load_lds_dwordx4 v130, vcc
	s_add_i32 m0, s44, 0x12000
	s_nop 0
	global_load_lds_dwordx4 v134, vcc
	s_add_u32 vcc_lo, vcc_lo, 0x20000
	s_addc_u32 vcc_hi, vcc_hi, 0
	s_add_i32 m0, s44, 0x11000
	s_nop 0
	global_load_lds_dwordx4 v130, vcc
	s_add_i32 m0, s44, 0x13000
	s_nop 0
	global_load_lds_dwordx4 v134, vcc
	s_add_u32 vcc_lo, vcc_lo, 0x60000
	s_addc_u32 vcc_hi, vcc_hi, 0
	s_add_i32 m0, s44, 0x14000
	s_nop 0
	global_load_lds_dwordx4 v130, vcc
	s_add_i32 m0, s44, 0x16000
	s_nop 0
	global_load_lds_dwordx4 v134, vcc
	s_add_u32 vcc_lo, vcc_lo, 0x20000
	s_addc_u32 vcc_hi, vcc_hi, 0
	s_add_i32 m0, s44, 0x15000
	s_nop 0
	global_load_lds_dwordx4 v130, vcc
	s_add_i32 m0, s44, 0x17000
	s_nop 0
	global_load_lds_dwordx4 v134, vcc
	ds_read_b128 v[144:147], v153 offset:32768
	ds_read_b128 v[158:161], v153 offset:33792
	ds_read_b128 v[162:165], v153 offset:34816
	ds_read_b128 v[166:169], v153 offset:35840
	ds_read_b128 v[170:173], v154 offset:32768
	ds_read_b128 v[174:177], v154 offset:33792
	ds_read_b128 v[178:181], v154 offset:34816
	ds_read_b128 v[182:185], v154 offset:35840
	ds_read_b128 v[186:189], v155 offset:32768
	ds_read_b128 v[190:193], v155 offset:33792
	ds_read_b128 v[194:197], v155 offset:34816
	ds_read_b128 v[198:201], v155 offset:35840
	ds_read_b128 v[202:205], v155 offset:36864
	ds_read_b128 v[206:209], v155 offset:37888
	ds_read_b128 v[210:213], v155 offset:38912
	ds_read_b128 v[214:217], v155 offset:39936
	ds_read_b128 v[220:223], v155 offset:49152
	ds_read_b128 v[224:227], v155 offset:50176
	ds_read_b128 v[228:231], v155 offset:51200
	ds_read_b128 v[232:235], v155 offset:52224
	ds_read_b128 v[236:239], v155 offset:53248
	ds_read_b128 v[240:243], v155 offset:54272
	ds_read_b128 v[244:247], v155 offset:55296
	ds_read_b128 v[248:251], v155 offset:56320
	s_nop 15
	s_nop 15
	s_waitcnt lgkmcnt(0)
	s_barrier
	s_setprio 1
	v_mfma_f32_16x16x32_bf16 v[124:127], v[144:147], v[186:189], v[124:127]
	v_mfma_f32_16x16x32_bf16 v[120:123], v[162:165], v[186:189], v[120:123]
	v_mfma_f32_16x16x32_bf16 v[108:111], v[144:147], v[194:197], v[108:111]
	v_mfma_f32_16x16x32_bf16 v[104:107], v[162:165], v[194:197], v[104:107]
	v_mfma_f32_16x16x32_bf16 v[92:95], v[144:147], v[202:205], v[92:95]
	v_mfma_f32_16x16x32_bf16 v[88:91], v[162:165], v[202:205], v[88:91]
	v_mfma_f32_16x16x32_bf16 v[76:79], v[144:147], v[210:213], v[76:79]
	v_mfma_f32_16x16x32_bf16 v[72:75], v[162:165], v[210:213], v[72:75]
	v_mfma_f32_16x16x32_bf16 v[124:127], v[158:161], v[190:193], v[124:127]
	v_mfma_f32_16x16x32_bf16 v[120:123], v[166:169], v[190:193], v[120:123]
	v_mfma_f32_16x16x32_bf16 v[108:111], v[158:161], v[198:201], v[108:111]
	v_mfma_f32_16x16x32_bf16 v[104:107], v[166:169], v[198:201], v[104:107]
	v_mfma_f32_16x16x32_bf16 v[92:95], v[158:161], v[206:209], v[92:95]
	v_mfma_f32_16x16x32_bf16 v[88:91], v[166:169], v[206:209], v[88:91]
	v_mfma_f32_16x16x32_bf16 v[76:79], v[158:161], v[214:217], v[76:79]
	v_mfma_f32_16x16x32_bf16 v[72:75], v[166:169], v[214:217], v[72:75]
	s_setprio 0
	s_setprio 1
	v_mfma_f32_16x16x32_bf16 v[116:119], v[170:173], v[186:189], v[116:119]
	v_mfma_f32_16x16x32_bf16 v[112:115], v[178:181], v[186:189], v[112:115]
	v_mfma_f32_16x16x32_bf16 v[100:103], v[170:173], v[194:197], v[100:103]
	v_mfma_f32_16x16x32_bf16 v[96:99], v[178:181], v[194:197], v[96:99]
	v_mfma_f32_16x16x32_bf16 v[84:87], v[170:173], v[202:205], v[84:87]
	v_mfma_f32_16x16x32_bf16 v[80:83], v[178:181], v[202:205], v[80:83]
	v_mfma_f32_16x16x32_bf16 v[68:71], v[170:173], v[210:213], v[68:71]
	v_mfma_f32_16x16x32_bf16 v[64:67], v[178:181], v[210:213], v[64:67]
	v_mfma_f32_16x16x32_bf16 v[116:119], v[174:177], v[190:193], v[116:119]
	v_mfma_f32_16x16x32_bf16 v[112:115], v[182:185], v[190:193], v[112:115]
	v_mfma_f32_16x16x32_bf16 v[100:103], v[174:177], v[198:201], v[100:103]
	v_mfma_f32_16x16x32_bf16 v[96:99], v[182:185], v[198:201], v[96:99]
	v_mfma_f32_16x16x32_bf16 v[84:87], v[174:177], v[206:209], v[84:87]
	v_mfma_f32_16x16x32_bf16 v[80:83], v[182:185], v[206:209], v[80:83]
	v_mfma_f32_16x16x32_bf16 v[68:71], v[174:177], v[214:217], v[68:71]
	v_mfma_f32_16x16x32_bf16 v[64:67], v[182:185], v[214:217], v[64:67]
	s_setprio 0
	s_setprio 1
	v_mfma_f32_16x16x32_bf16 v[60:63], v[144:147], v[220:223], v[60:63]
	v_mfma_f32_16x16x32_bf16 v[56:59], v[162:165], v[220:223], v[56:59]
	v_mfma_f32_16x16x32_bf16 v[44:47], v[144:147], v[228:231], v[44:47]
	v_mfma_f32_16x16x32_bf16 v[40:43], v[162:165], v[228:231], v[40:43]
	v_mfma_f32_16x16x32_bf16 v[28:31], v[144:147], v[236:239], v[28:31]
	v_mfma_f32_16x16x32_bf16 v[24:27], v[162:165], v[236:239], v[24:27]
	v_mfma_f32_16x16x32_bf16 v[12:15], v[144:147], v[244:247], v[12:15]
	v_mfma_f32_16x16x32_bf16 v[8:11], v[162:165], v[244:247], v[8:11]
	v_mfma_f32_16x16x32_bf16 v[60:63], v[158:161], v[224:227], v[60:63]
	v_mfma_f32_16x16x32_bf16 v[56:59], v[166:169], v[224:227], v[56:59]
	v_mfma_f32_16x16x32_bf16 v[44:47], v[158:161], v[232:235], v[44:47]
	v_mfma_f32_16x16x32_bf16 v[40:43], v[166:169], v[232:235], v[40:43]
	v_mfma_f32_16x16x32_bf16 v[28:31], v[158:161], v[240:243], v[28:31]
	v_mfma_f32_16x16x32_bf16 v[24:27], v[166:169], v[240:243], v[24:27]
	v_mfma_f32_16x16x32_bf16 v[12:15], v[158:161], v[248:251], v[12:15]
	v_mfma_f32_16x16x32_bf16 v[8:11], v[166:169], v[248:251], v[8:11]
	s_setprio 0
	s_setprio 1
	v_mfma_f32_16x16x32_bf16 v[52:55], v[170:173], v[220:223], v[52:55]
	v_mfma_f32_16x16x32_bf16 v[48:51], v[178:181], v[220:223], v[48:51]
	v_mfma_f32_16x16x32_bf16 v[36:39], v[170:173], v[228:231], v[36:39]
	v_mfma_f32_16x16x32_bf16 v[32:35], v[178:181], v[228:231], v[32:35]
	v_mfma_f32_16x16x32_bf16 v[20:23], v[170:173], v[236:239], v[20:23]
	v_mfma_f32_16x16x32_bf16 v[16:19], v[178:181], v[236:239], v[16:19]
	v_mfma_f32_16x16x32_bf16 v[4:7], v[170:173], v[244:247], v[4:7]
	v_mfma_f32_16x16x32_bf16 v[0:3], v[178:181], v[244:247], v[0:3]
	v_mfma_f32_16x16x32_bf16 v[52:55], v[174:177], v[224:227], v[52:55]
	v_mfma_f32_16x16x32_bf16 v[48:51], v[182:185], v[224:227], v[48:51]
	v_mfma_f32_16x16x32_bf16 v[36:39], v[174:177], v[232:235], v[36:39]
	v_mfma_f32_16x16x32_bf16 v[32:35], v[182:185], v[232:235], v[32:35]
	v_mfma_f32_16x16x32_bf16 v[20:23], v[174:177], v[240:243], v[20:23]
	v_mfma_f32_16x16x32_bf16 v[16:19], v[182:185], v[240:243], v[16:19]
	v_mfma_f32_16x16x32_bf16 v[4:7], v[174:177], v[248:251], v[4:7]
	v_mfma_f32_16x16x32_bf16 v[0:3], v[182:185], v[248:251], v[0:3]
	s_setprio 0
	s_add_i32 s58, s58, 2
	s_add_u32 s34, s34, 0x100
	s_addc_u32 s35, s35, 0
	s_add_u32 s56, s56, 0x100
	s_addc_u32 s57, s57, 0
	s_add_u32 s36, s34, 0xfff80080
	s_addc_u32 s37, s35, -1
	s_cmp_eq_u32 s58, 28
	s_cselect_b32 s43, s23, s37
	s_cselect_b32 s42, s29, s36
	s_cselect_b32 s37, s13, s57
	s_cselect_b32 s36, s31, s56
	s_cmp_gt_u32 s58, 29
	s_waitcnt vmcnt(0)
	s_barrier
	s_cbranch_scc0 .Lk64_lead_p5
	s_branch .Lk64_done_p5
.Lk64_trail_p5:
	s_sub_u32 vcc_lo, s34, 0x80000
	s_subb_u32 vcc_hi, s35, 0
	s_add_i32 m0, s44, 0xa000
	s_nop 0
	global_load_lds_dwordx4 v132, vcc
	s_add_u32 vcc_lo, vcc_lo, 0x20000
	s_addc_u32 vcc_hi, vcc_hi, 0
	s_add_i32 m0, s44, 0x9000
	s_nop 0
	global_load_lds_dwordx4 v128, vcc
	s_add_u32 vcc_lo, vcc_lo, 0x60000
	s_addc_u32 vcc_hi, vcc_hi, 0
	s_add_i32 m0, s44, 0xe000
	s_nop 0
	global_load_lds_dwordx4 v132, vcc
	s_add_u32 vcc_lo, vcc_lo, 0x20000
	s_addc_u32 vcc_hi, vcc_hi, 0
	s_add_i32 m0, s44, 0xd000
	s_nop 0
	global_load_lds_dwordx4 v128, vcc
	s_add_u32 vcc_lo, s42, 0x0
	s_addc_u32 vcc_hi, s43, 0
	s_mov_b32 m0, s44
	s_nop 0
	global_load_lds_dwordx4 v128, vcc
	s_sub_u32 vcc_lo, vcc_lo, 0x20000
	s_subb_u32 vcc_hi, vcc_hi, 0
	s_sub_i32 m0, s44, 0x1000
	s_nop 0
	global_load_lds_dwordx4 v128, vcc
	s_add_u32 vcc_lo, vcc_lo, 0xa0000
	s_addc_u32 vcc_hi, vcc_hi, 0
	s_add_i32 m0, s44, 0x4000
	s_nop 0
	global_load_lds_dwordx4 v128, vcc
	s_sub_u32 vcc_lo, vcc_lo, 0x20000
	s_subb_u32 vcc_hi, vcc_hi, 0
	s_add_i32 m0, s44, 0x3000
	s_nop 0
	global_load_lds_dwordx4 v128, vcc
	ds_read_b128 v[144:147], v153 offset:0
	ds_read_b128 v[158:161], v153 offset:1024
	ds_read_b128 v[162:165], v153 offset:2048
	ds_read_b128 v[166:169], v153 offset:3072
	ds_read_b128 v[170:173], v154 offset:0
	ds_read_b128 v[174:177], v154 offset:1024
	ds_read_b128 v[178:181], v154 offset:2048
	ds_read_b128 v[182:185], v154 offset:3072
	ds_read_b128 v[186:189], v155 offset:0
	ds_read_b128 v[190:193], v155 offset:1024
	ds_read_b128 v[194:197], v155 offset:2048
	ds_read_b128 v[198:201], v155 offset:3072
	ds_read_b128 v[202:205], v155 offset:4096
	ds_read_b128 v[206:209], v155 offset:5120
	ds_read_b128 v[210:213], v155 offset:6144
	ds_read_b128 v[214:217], v155 offset:7168
	ds_read_b128 v[220:223], v155 offset:16384
	ds_read_b128 v[224:227], v155 offset:17408
	ds_read_b128 v[228:231], v155 offset:18432
	ds_read_b128 v[232:235], v155 offset:19456
	ds_read_b128 v[236:239], v155 offset:20480
	ds_read_b128 v[240:243], v155 offset:21504
	ds_read_b128 v[244:247], v155 offset:22528
	ds_read_b128 v[248:251], v155 offset:23552
	s_nop 15
	s_nop 15
	s_waitcnt lgkmcnt(0)
	s_barrier
	s_setprio 1
	v_mfma_f32_16x16x32_bf16 v[124:127], v[144:147], v[186:189], v[124:127]
	v_mfma_f32_16x16x32_bf16 v[120:123], v[162:165], v[186:189], v[120:123]
	v_mfma_f32_16x16x32_bf16 v[108:111], v[144:147], v[194:197], v[108:111]
	v_mfma_f32_16x16x32_bf16 v[104:107], v[162:165], v[194:197], v[104:107]
	v_mfma_f32_16x16x32_bf16 v[92:95], v[144:147], v[202:205], v[92:95]
	v_mfma_f32_16x16x32_bf16 v[88:91], v[162:165], v[202:205], v[88:91]
	v_mfma_f32_16x16x32_bf16 v[76:79], v[144:147], v[210:213], v[76:79]
	v_mfma_f32_16x16x32_bf16 v[72:75], v[162:165], v[210:213], v[72:75]
	v_mfma_f32_16x16x32_bf16 v[124:127], v[158:161], v[190:193], v[124:127]
	v_mfma_f32_16x16x32_bf16 v[120:123], v[166:169], v[190:193], v[120:123]
	v_mfma_f32_16x16x32_bf16 v[108:111], v[158:161], v[198:201], v[108:111]
	v_mfma_f32_16x16x32_bf16 v[104:107], v[166:169], v[198:201], v[104:107]
	v_mfma_f32_16x16x32_bf16 v[92:95], v[158:161], v[206:209], v[92:95]
	v_mfma_f32_16x16x32_bf16 v[88:91], v[166:169], v[206:209], v[88:91]
	v_mfma_f32_16x16x32_bf16 v[76:79], v[158:161], v[214:217], v[76:79]
	v_mfma_f32_16x16x32_bf16 v[72:75], v[166:169], v[214:217], v[72:75]
	s_setprio 0
	s_setprio 1
	v_mfma_f32_16x16x32_bf16 v[116:119], v[170:173], v[186:189], v[116:119]
	v_mfma_f32_16x16x32_bf16 v[112:115], v[178:181], v[186:189], v[112:115]
	v_mfma_f32_16x16x32_bf16 v[100:103], v[170:173], v[194:197], v[100:103]
	v_mfma_f32_16x16x32_bf16 v[96:99], v[178:181], v[194:197], v[96:99]
	v_mfma_f32_16x16x32_bf16 v[84:87], v[170:173], v[202:205], v[84:87]
	v_mfma_f32_16x16x32_bf16 v[80:83], v[178:181], v[202:205], v[80:83]
	v_mfma_f32_16x16x32_bf16 v[68:71], v[170:173], v[210:213], v[68:71]
	v_mfma_f32_16x16x32_bf16 v[64:67], v[178:181], v[210:213], v[64:67]
	v_mfma_f32_16x16x32_bf16 v[116:119], v[174:177], v[190:193], v[116:119]
	v_mfma_f32_16x16x32_bf16 v[112:115], v[182:185], v[190:193], v[112:115]
	v_mfma_f32_16x16x32_bf16 v[100:103], v[174:177], v[198:201], v[100:103]
	v_mfma_f32_16x16x32_bf16 v[96:99], v[182:185], v[198:201], v[96:99]
	v_mfma_f32_16x16x32_bf16 v[84:87], v[174:177], v[206:209], v[84:87]
	v_mfma_f32_16x16x32_bf16 v[80:83], v[182:185], v[206:209], v[80:83]
	v_mfma_f32_16x16x32_bf16 v[68:71], v[174:177], v[214:217], v[68:71]
	v_mfma_f32_16x16x32_bf16 v[64:67], v[182:185], v[214:217], v[64:67]
	s_setprio 0
	s_setprio 1
	v_mfma_f32_16x16x32_bf16 v[60:63], v[144:147], v[220:223], v[60:63]
	v_mfma_f32_16x16x32_bf16 v[56:59], v[162:165], v[220:223], v[56:59]
	v_mfma_f32_16x16x32_bf16 v[44:47], v[144:147], v[228:231], v[44:47]
	v_mfma_f32_16x16x32_bf16 v[40:43], v[162:165], v[228:231], v[40:43]
	v_mfma_f32_16x16x32_bf16 v[28:31], v[144:147], v[236:239], v[28:31]
	v_mfma_f32_16x16x32_bf16 v[24:27], v[162:165], v[236:239], v[24:27]
	v_mfma_f32_16x16x32_bf16 v[12:15], v[144:147], v[244:247], v[12:15]
	v_mfma_f32_16x16x32_bf16 v[8:11], v[162:165], v[244:247], v[8:11]
	v_mfma_f32_16x16x32_bf16 v[60:63], v[158:161], v[224:227], v[60:63]
	v_mfma_f32_16x16x32_bf16 v[56:59], v[166:169], v[224:227], v[56:59]
	v_mfma_f32_16x16x32_bf16 v[44:47], v[158:161], v[232:235], v[44:47]
	v_mfma_f32_16x16x32_bf16 v[40:43], v[166:169], v[232:235], v[40:43]
	v_mfma_f32_16x16x32_bf16 v[28:31], v[158:161], v[240:243], v[28:31]
	v_mfma_f32_16x16x32_bf16 v[24:27], v[166:169], v[240:243], v[24:27]
	v_mfma_f32_16x16x32_bf16 v[12:15], v[158:161], v[248:251], v[12:15]
	v_mfma_f32_16x16x32_bf16 v[8:11], v[166:169], v[248:251], v[8:11]
	s_setprio 0
	s_setprio 1
	v_mfma_f32_16x16x32_bf16 v[52:55], v[170:173], v[220:223], v[52:55]
	v_mfma_f32_16x16x32_bf16 v[48:51], v[178:181], v[220:223], v[48:51]
	v_mfma_f32_16x16x32_bf16 v[36:39], v[170:173], v[228:231], v[36:39]
	v_mfma_f32_16x16x32_bf16 v[32:35], v[178:181], v[228:231], v[32:35]
	v_mfma_f32_16x16x32_bf16 v[20:23], v[170:173], v[236:239], v[20:23]
	v_mfma_f32_16x16x32_bf16 v[16:19], v[178:181], v[236:239], v[16:19]
	v_mfma_f32_16x16x32_bf16 v[4:7], v[170:173], v[244:247], v[4:7]
	v_mfma_f32_16x16x32_bf16 v[0:3], v[178:181], v[244:247], v[0:3]
	v_mfma_f32_16x16x32_bf16 v[52:55], v[174:177], v[224:227], v[52:55]
	v_mfma_f32_16x16x32_bf16 v[48:51], v[182:185], v[224:227], v[48:51]
	v_mfma_f32_16x16x32_bf16 v[36:39], v[174:177], v[232:235], v[36:39]
	v_mfma_f32_16x16x32_bf16 v[32:35], v[182:185], v[232:235], v[32:35]
	v_mfma_f32_16x16x32_bf16 v[20:23], v[174:177], v[240:243], v[20:23]
	v_mfma_f32_16x16x32_bf16 v[16:19], v[182:185], v[240:243], v[16:19]
	v_mfma_f32_16x16x32_bf16 v[4:7], v[174:177], v[248:251], v[4:7]
	v_mfma_f32_16x16x32_bf16 v[0:3], v[182:185], v[248:251], v[0:3]
	s_setprio 0
	s_waitcnt vmcnt(0)
	s_barrier
	s_add_u32 vcc_lo, s42, 0x0
	s_addc_u32 vcc_hi, s43, 0
	s_add_i32 m0, s44, 0x2000
	s_nop 0
	global_load_lds_dwordx4 v132, vcc
	s_add_u32 vcc_lo, vcc_lo, 0x20000
	s_addc_u32 vcc_hi, vcc_hi, 0
	s_add_i32 m0, s44, 0x1000
	s_nop 0
	global_load_lds_dwordx4 v128, vcc
	s_add_u32 vcc_lo, vcc_lo, 0x60000
	s_addc_u32 vcc_hi, vcc_hi, 0
	s_add_i32 m0, s44, 0x6000
	s_nop 0
	global_load_lds_dwordx4 v132, vcc
	s_add_u32 vcc_lo, vcc_lo, 0x20000
	s_addc_u32 vcc_hi, vcc_hi, 0
	s_add_i32 m0, s44, 0x5000
	s_nop 0
	global_load_lds_dwordx4 v128, vcc
	s_add_u32 vcc_lo, s42, 0x80
	s_addc_u32 vcc_hi, s43, 0
	s_add_i32 m0, s44, 0x8000
	s_nop 0
	global_load_lds_dwordx4 v128, vcc
	s_sub_u32 vcc_lo, vcc_lo, 0x20000
	s_subb_u32 vcc_hi, vcc_hi, 0
	s_add_i32 m0, s44, 0x7000
	s_nop 0
	global_load_lds_dwordx4 v128, vcc
	s_add_u32 vcc_lo, vcc_lo, 0xa0000
	s_addc_u32 vcc_hi, vcc_hi, 0
	s_add_i32 m0, s44, 0xc000
	s_nop 0
	global_load_lds_dwordx4 v128, vcc
	s_sub_u32 vcc_lo, vcc_lo, 0x20000
	s_subb_u32 vcc_hi, vcc_hi, 0
	s_add_i32 m0, s44, 0xb000
	s_nop 0
	global_load_lds_dwordx4 v128, vcc
	ds_read_b128 v[144:147], v153 offset:32768
	ds_read_b128 v[158:161], v153 offset:33792
	ds_read_b128 v[162:165], v153 offset:34816
	ds_read_b128 v[166:169], v153 offset:35840
	ds_read_b128 v[170:173], v154 offset:32768
	ds_read_b128 v[174:177], v154 offset:33792
	ds_read_b128 v[178:181], v154 offset:34816
	ds_read_b128 v[182:185], v154 offset:35840
	ds_read_b128 v[186:189], v155 offset:32768
	ds_read_b128 v[190:193], v155 offset:33792
	ds_read_b128 v[194:197], v155 offset:34816
	ds_read_b128 v[198:201], v155 offset:35840
	ds_read_b128 v[202:205], v155 offset:36864
	ds_read_b128 v[206:209], v155 offset:37888
	ds_read_b128 v[210:213], v155 offset:38912
	ds_read_b128 v[214:217], v155 offset:39936
	ds_read_b128 v[220:223], v155 offset:49152
	ds_read_b128 v[224:227], v155 offset:50176
	ds_read_b128 v[228:231], v155 offset:51200
	ds_read_b128 v[232:235], v155 offset:52224
	ds_read_b128 v[236:239], v155 offset:53248
	ds_read_b128 v[240:243], v155 offset:54272
	ds_read_b128 v[244:247], v155 offset:55296
	ds_read_b128 v[248:251], v155 offset:56320
	s_nop 15
	s_nop 15
	s_waitcnt lgkmcnt(0)
	s_barrier
	s_setprio 1
	v_mfma_f32_16x16x32_bf16 v[124:127], v[144:147], v[186:189], v[124:127]
	v_mfma_f32_16x16x32_bf16 v[120:123], v[162:165], v[186:189], v[120:123]
	v_mfma_f32_16x16x32_bf16 v[108:111], v[144:147], v[194:197], v[108:111]
	v_mfma_f32_16x16x32_bf16 v[104:107], v[162:165], v[194:197], v[104:107]
	v_mfma_f32_16x16x32_bf16 v[92:95], v[144:147], v[202:205], v[92:95]
	v_mfma_f32_16x16x32_bf16 v[88:91], v[162:165], v[202:205], v[88:91]
	v_mfma_f32_16x16x32_bf16 v[76:79], v[144:147], v[210:213], v[76:79]
	v_mfma_f32_16x16x32_bf16 v[72:75], v[162:165], v[210:213], v[72:75]
	v_mfma_f32_16x16x32_bf16 v[124:127], v[158:161], v[190:193], v[124:127]
	v_mfma_f32_16x16x32_bf16 v[120:123], v[166:169], v[190:193], v[120:123]
	v_mfma_f32_16x16x32_bf16 v[108:111], v[158:161], v[198:201], v[108:111]
	v_mfma_f32_16x16x32_bf16 v[104:107], v[166:169], v[198:201], v[104:107]
	v_mfma_f32_16x16x32_bf16 v[92:95], v[158:161], v[206:209], v[92:95]
	v_mfma_f32_16x16x32_bf16 v[88:91], v[166:169], v[206:209], v[88:91]
	v_mfma_f32_16x16x32_bf16 v[76:79], v[158:161], v[214:217], v[76:79]
	v_mfma_f32_16x16x32_bf16 v[72:75], v[166:169], v[214:217], v[72:75]
	s_setprio 0
	s_setprio 1
	v_mfma_f32_16x16x32_bf16 v[116:119], v[170:173], v[186:189], v[116:119]
	v_mfma_f32_16x16x32_bf16 v[112:115], v[178:181], v[186:189], v[112:115]
	v_mfma_f32_16x16x32_bf16 v[100:103], v[170:173], v[194:197], v[100:103]
	v_mfma_f32_16x16x32_bf16 v[96:99], v[178:181], v[194:197], v[96:99]
	v_mfma_f32_16x16x32_bf16 v[84:87], v[170:173], v[202:205], v[84:87]
	v_mfma_f32_16x16x32_bf16 v[80:83], v[178:181], v[202:205], v[80:83]
	v_mfma_f32_16x16x32_bf16 v[68:71], v[170:173], v[210:213], v[68:71]
	v_mfma_f32_16x16x32_bf16 v[64:67], v[178:181], v[210:213], v[64:67]
	v_mfma_f32_16x16x32_bf16 v[116:119], v[174:177], v[190:193], v[116:119]
	v_mfma_f32_16x16x32_bf16 v[112:115], v[182:185], v[190:193], v[112:115]
	v_mfma_f32_16x16x32_bf16 v[100:103], v[174:177], v[198:201], v[100:103]
	v_mfma_f32_16x16x32_bf16 v[96:99], v[182:185], v[198:201], v[96:99]
	v_mfma_f32_16x16x32_bf16 v[84:87], v[174:177], v[206:209], v[84:87]
	v_mfma_f32_16x16x32_bf16 v[80:83], v[182:185], v[206:209], v[80:83]
	v_mfma_f32_16x16x32_bf16 v[68:71], v[174:177], v[214:217], v[68:71]
	v_mfma_f32_16x16x32_bf16 v[64:67], v[182:185], v[214:217], v[64:67]
	s_setprio 0
	s_setprio 1
	v_mfma_f32_16x16x32_bf16 v[60:63], v[144:147], v[220:223], v[60:63]
	v_mfma_f32_16x16x32_bf16 v[56:59], v[162:165], v[220:223], v[56:59]
	v_mfma_f32_16x16x32_bf16 v[44:47], v[144:147], v[228:231], v[44:47]
	v_mfma_f32_16x16x32_bf16 v[40:43], v[162:165], v[228:231], v[40:43]
	v_mfma_f32_16x16x32_bf16 v[28:31], v[144:147], v[236:239], v[28:31]
	v_mfma_f32_16x16x32_bf16 v[24:27], v[162:165], v[236:239], v[24:27]
	v_mfma_f32_16x16x32_bf16 v[12:15], v[144:147], v[244:247], v[12:15]
	v_mfma_f32_16x16x32_bf16 v[8:11], v[162:165], v[244:247], v[8:11]
	v_mfma_f32_16x16x32_bf16 v[60:63], v[158:161], v[224:227], v[60:63]
	v_mfma_f32_16x16x32_bf16 v[56:59], v[166:169], v[224:227], v[56:59]
	v_mfma_f32_16x16x32_bf16 v[44:47], v[158:161], v[232:235], v[44:47]
	v_mfma_f32_16x16x32_bf16 v[40:43], v[166:169], v[232:235], v[40:43]
	v_mfma_f32_16x16x32_bf16 v[28:31], v[158:161], v[240:243], v[28:31]
	v_mfma_f32_16x16x32_bf16 v[24:27], v[166:169], v[240:243], v[24:27]
	v_mfma_f32_16x16x32_bf16 v[12:15], v[158:161], v[248:251], v[12:15]
	v_mfma_f32_16x16x32_bf16 v[8:11], v[166:169], v[248:251], v[8:11]
	s_setprio 0
	s_setprio 1
	v_mfma_f32_16x16x32_bf16 v[52:55], v[170:173], v[220:223], v[52:55]
	v_mfma_f32_16x16x32_bf16 v[48:51], v[178:181], v[220:223], v[48:51]
	v_mfma_f32_16x16x32_bf16 v[36:39], v[170:173], v[228:231], v[36:39]
	v_mfma_f32_16x16x32_bf16 v[32:35], v[178:181], v[228:231], v[32:35]
	v_mfma_f32_16x16x32_bf16 v[20:23], v[170:173], v[236:239], v[20:23]
	v_mfma_f32_16x16x32_bf16 v[16:19], v[178:181], v[236:239], v[16:19]
	v_mfma_f32_16x16x32_bf16 v[4:7], v[170:173], v[244:247], v[4:7]
	v_mfma_f32_16x16x32_bf16 v[0:3], v[178:181], v[244:247], v[0:3]
	v_mfma_f32_16x16x32_bf16 v[52:55], v[174:177], v[224:227], v[52:55]
	v_mfma_f32_16x16x32_bf16 v[48:51], v[182:185], v[224:227], v[48:51]
	v_mfma_f32_16x16x32_bf16 v[36:39], v[174:177], v[232:235], v[36:39]
	v_mfma_f32_16x16x32_bf16 v[32:35], v[182:185], v[232:235], v[32:35]
	v_mfma_f32_16x16x32_bf16 v[20:23], v[174:177], v[240:243], v[20:23]
	v_mfma_f32_16x16x32_bf16 v[16:19], v[182:185], v[240:243], v[16:19]
	v_mfma_f32_16x16x32_bf16 v[4:7], v[174:177], v[248:251], v[4:7]
	v_mfma_f32_16x16x32_bf16 v[0:3], v[182:185], v[248:251], v[0:3]
	s_setprio 0
	s_add_i32 s58, s58, 2
	s_add_u32 s34, s34, 0x100
	s_addc_u32 s35, s35, 0
	s_add_u32 s56, s56, 0x100
	s_addc_u32 s57, s57, 0
	s_add_u32 s36, s34, 0xfff80080
	s_addc_u32 s37, s35, -1
	s_cmp_eq_u32 s58, 28
	s_cselect_b32 s43, s23, s37
	s_cselect_b32 s42, s29, s36
	s_cselect_b32 s37, s13, s57
	s_cselect_b32 s36, s31, s56
	s_cmp_gt_u32 s58, 29
	s_waitcnt vmcnt(0)
	s_barrier
	s_cbranch_scc0 .Lk64_trail_p5

.Lk64_lead_p6:
	s_sub_u32 vcc_lo, s54, 0x80
	s_subb_u32 vcc_hi, s55, 0
	s_add_i32 m0, s37, 0x18000
	s_nop 0
	global_load_lds_dwordx4 v148, vcc
	s_add_i32 m0, s37, 0x1a000
	s_nop 0
	global_load_lds_dwordx4 v144, vcc
	s_add_u32 vcc_lo, vcc_lo, 0x20000
	s_addc_u32 vcc_hi, vcc_hi, 0
	s_add_i32 m0, s37, 0x19000
	s_nop 0
	global_load_lds_dwordx4 v148, vcc
	s_add_i32 m0, s37, 0x1b000
	s_nop 0
	global_load_lds_dwordx4 v144, vcc
	s_add_u32 vcc_lo, vcc_lo, 0x60000
	s_addc_u32 vcc_hi, vcc_hi, 0
	s_add_i32 m0, s37, 0x1c000
	s_nop 0
	global_load_lds_dwordx4 v148, vcc
	s_add_i32 m0, s37, 0x1e000
	s_nop 0
	global_load_lds_dwordx4 v144, vcc
	s_add_u32 vcc_lo, vcc_lo, 0x20000
	s_addc_u32 vcc_hi, vcc_hi, 0
	s_add_i32 m0, s37, 0x1d000
	s_nop 0
	global_load_lds_dwordx4 v148, vcc
	s_add_i32 m0, s37, 0x1f000
	s_nop 0
	global_load_lds_dwordx4 v144, vcc
	s_cmp_eq_u32 s56, 28
	s_cbranch_scc0 .Lk64_epd_p6_l
	s_ashr_i32 vcc_lo, s10, 3
	s_mul_i32 vcc_lo, vcc_lo, 0xb000
	s_lshl_b32 vcc_hi, s11, 10
	s_add_i32 vcc_lo, vcc_lo, vcc_hi
	s_lshr_b32 vcc_hi, s37, 2
	s_add_i32 vcc_lo, vcc_lo, vcc_hi
	s_add_u32 vcc_lo, s66, vcc_lo
	s_addc_u32 vcc_hi, s67, 0
	v_and_b32_e32 v248, 63, v252
	v_lshlrev_b32_e32 v248, 2, v248
	s_lshr_b32 m0, s37, 2
	s_add_i32 m0, m0, 0x20000
	s_nop 0
	global_load_lds_dword v248, vcc
.Lk64_epd_p6_l:
	ds_read_b128 v[32:35], v169 offset:0
	ds_read_b128 v[36:39], v169 offset:1024
	ds_read_b128 v[40:43], v169 offset:2048
	ds_read_b128 v[44:47], v169 offset:3072
	ds_read_b128 v[162:165], v170 offset:0
	ds_read_b128 v[174:177], v170 offset:1024
	ds_read_b128 v[178:181], v170 offset:2048
	ds_read_b128 v[182:185], v170 offset:3072
	ds_read_b128 v[186:189], v171 offset:0
	ds_read_b128 v[190:193], v171 offset:1024
	ds_read_b128 v[194:197], v171 offset:2048
	ds_read_b128 v[198:201], v171 offset:3072
	ds_read_b128 v[202:205], v171 offset:4096
	ds_read_b128 v[206:209], v171 offset:5120
	ds_read_b128 v[210:213], v171 offset:6144
	ds_read_b128 v[214:217], v171 offset:7168
	ds_read_b128 v[220:223], v171 offset:16384
	ds_read_b128 v[224:227], v171 offset:17408
	ds_read_b128 v[228:231], v171 offset:18432
	ds_read_b128 v[232:235], v171 offset:19456
	ds_read_b128 v[236:239], v171 offset:20480
	ds_read_b128 v[240:243], v171 offset:21504
	ds_read_b128 v[244:247], v171 offset:22528
	ds_read_b128 v[248:251], v171 offset:23552
	s_nop 15
	s_nop 15
	s_waitcnt lgkmcnt(0)
	s_barrier
	s_setprio 1
	v_mfma_f32_16x16x32_bf16 v[140:143], v[32:35], v[186:189], v[140:143]
	v_mfma_f32_16x16x32_bf16 v[136:139], v[40:43], v[186:189], v[136:139]
	v_mfma_f32_16x16x32_bf16 v[124:127], v[32:35], v[194:197], v[124:127]
	v_mfma_f32_16x16x32_bf16 v[120:123], v[40:43], v[194:197], v[120:123]
	v_mfma_f32_16x16x32_bf16 v[108:111], v[32:35], v[202:205], v[108:111]
	v_mfma_f32_16x16x32_bf16 v[104:107], v[40:43], v[202:205], v[104:107]
	v_mfma_f32_16x16x32_bf16 v[92:95], v[32:35], v[210:213], v[92:95]
	v_mfma_f32_16x16x32_bf16 v[88:91], v[40:43], v[210:213], v[88:91]
	v_mfma_f32_16x16x32_bf16 v[140:143], v[36:39], v[190:193], v[140:143]
	v_mfma_f32_16x16x32_bf16 v[136:139], v[44:47], v[190:193], v[136:139]
	v_mfma_f32_16x16x32_bf16 v[124:127], v[36:39], v[198:201], v[124:127]
	v_mfma_f32_16x16x32_bf16 v[120:123], v[44:47], v[198:201], v[120:123]
	v_mfma_f32_16x16x32_bf16 v[108:111], v[36:39], v[206:209], v[108:111]
	v_mfma_f32_16x16x32_bf16 v[104:107], v[44:47], v[206:209], v[104:107]
	v_mfma_f32_16x16x32_bf16 v[92:95], v[36:39], v[214:217], v[92:95]
	v_mfma_f32_16x16x32_bf16 v[88:91], v[44:47], v[214:217], v[88:91]
	s_setprio 0
	s_setprio 1
	v_mfma_f32_16x16x32_bf16 v[132:135], v[162:165], v[186:189], v[132:135]
	v_mfma_f32_16x16x32_bf16 v[128:131], v[178:181], v[186:189], v[128:131]
	v_mfma_f32_16x16x32_bf16 v[116:119], v[162:165], v[194:197], v[116:119]
	v_mfma_f32_16x16x32_bf16 v[112:115], v[178:181], v[194:197], v[112:115]
	v_mfma_f32_16x16x32_bf16 v[100:103], v[162:165], v[202:205], v[100:103]
	v_mfma_f32_16x16x32_bf16 v[96:99], v[178:181], v[202:205], v[96:99]
	v_mfma_f32_16x16x32_bf16 v[84:87], v[162:165], v[210:213], v[84:87]
	v_mfma_f32_16x16x32_bf16 v[80:83], v[178:181], v[210:213], v[80:83]
	v_mfma_f32_16x16x32_bf16 v[132:135], v[174:177], v[190:193], v[132:135]
	v_mfma_f32_16x16x32_bf16 v[128:131], v[182:185], v[190:193], v[128:131]
	v_mfma_f32_16x16x32_bf16 v[116:119], v[174:177], v[198:201], v[116:119]
	v_mfma_f32_16x16x32_bf16 v[112:115], v[182:185], v[198:201], v[112:115]
	v_mfma_f32_16x16x32_bf16 v[100:103], v[174:177], v[206:209], v[100:103]
	v_mfma_f32_16x16x32_bf16 v[96:99], v[182:185], v[206:209], v[96:99]
	v_mfma_f32_16x16x32_bf16 v[84:87], v[174:177], v[214:217], v[84:87]
	v_mfma_f32_16x16x32_bf16 v[80:83], v[182:185], v[214:217], v[80:83]
	s_setprio 0
	s_setprio 1
	v_mfma_f32_16x16x32_bf16 v[76:79], v[32:35], v[220:223], v[76:79]
	v_mfma_f32_16x16x32_bf16 v[72:75], v[40:43], v[220:223], v[72:75]
	v_mfma_f32_16x16x32_bf16 v[60:63], v[32:35], v[228:231], v[60:63]
	v_mfma_f32_16x16x32_bf16 v[56:59], v[40:43], v[228:231], v[56:59]
	v_mfma_f32_16x16x32_bf16 v[28:31], v[32:35], v[236:239], v[28:31]
	v_mfma_f32_16x16x32_bf16 v[24:27], v[40:43], v[236:239], v[24:27]
	v_mfma_f32_16x16x32_bf16 v[12:15], v[32:35], v[244:247], v[12:15]
	v_mfma_f32_16x16x32_bf16 v[8:11], v[40:43], v[244:247], v[8:11]
	v_mfma_f32_16x16x32_bf16 v[76:79], v[36:39], v[224:227], v[76:79]
	v_mfma_f32_16x16x32_bf16 v[72:75], v[44:47], v[224:227], v[72:75]
	v_mfma_f32_16x16x32_bf16 v[60:63], v[36:39], v[232:235], v[60:63]
	v_mfma_f32_16x16x32_bf16 v[56:59], v[44:47], v[232:235], v[56:59]
	v_mfma_f32_16x16x32_bf16 v[28:31], v[36:39], v[240:243], v[28:31]
	v_mfma_f32_16x16x32_bf16 v[24:27], v[44:47], v[240:243], v[24:27]
	v_mfma_f32_16x16x32_bf16 v[12:15], v[36:39], v[248:251], v[12:15]
	v_mfma_f32_16x16x32_bf16 v[8:11], v[44:47], v[248:251], v[8:11]
	s_setprio 0
	s_setprio 1
	v_mfma_f32_16x16x32_bf16 v[68:71], v[162:165], v[220:223], v[68:71]
	v_mfma_f32_16x16x32_bf16 v[64:67], v[178:181], v[220:223], v[64:67]
	v_mfma_f32_16x16x32_bf16 v[52:55], v[162:165], v[228:231], v[52:55]
	v_mfma_f32_16x16x32_bf16 v[48:51], v[178:181], v[228:231], v[48:51]
	v_mfma_f32_16x16x32_bf16 v[20:23], v[162:165], v[236:239], v[20:23]
	v_mfma_f32_16x16x32_bf16 v[16:19], v[178:181], v[236:239], v[16:19]
	v_mfma_f32_16x16x32_bf16 v[4:7], v[162:165], v[244:247], v[4:7]
	v_mfma_f32_16x16x32_bf16 v[0:3], v[178:181], v[244:247], v[0:3]
	v_mfma_f32_16x16x32_bf16 v[68:71], v[174:177], v[224:227], v[68:71]
	v_mfma_f32_16x16x32_bf16 v[64:67], v[182:185], v[224:227], v[64:67]
	v_mfma_f32_16x16x32_bf16 v[52:55], v[174:177], v[232:235], v[52:55]
	v_mfma_f32_16x16x32_bf16 v[48:51], v[182:185], v[232:235], v[48:51]
	v_mfma_f32_16x16x32_bf16 v[20:23], v[174:177], v[240:243], v[20:23]
	v_mfma_f32_16x16x32_bf16 v[16:19], v[182:185], v[240:243], v[16:19]
	v_mfma_f32_16x16x32_bf16 v[4:7], v[174:177], v[248:251], v[4:7]
	v_mfma_f32_16x16x32_bf16 v[0:3], v[182:185], v[248:251], v[0:3]
	s_setprio 0
	s_waitcnt vmcnt(0)
	s_barrier
	s_add_u32 vcc_lo, s30, 0x0
	s_addc_u32 vcc_hi, s31, 0
	s_add_i32 m0, s37, 0x10000
	s_nop 0
	global_load_lds_dwordx4 v148, vcc
	s_add_i32 m0, s37, 0x12000
	s_nop 0
	global_load_lds_dwordx4 v144, vcc
	s_add_u32 vcc_lo, vcc_lo, 0x20000
	s_addc_u32 vcc_hi, vcc_hi, 0
	s_add_i32 m0, s37, 0x11000
	s_nop 0
	global_load_lds_dwordx4 v148, vcc
	s_add_i32 m0, s37, 0x13000
	s_nop 0
	global_load_lds_dwordx4 v144, vcc
	s_add_u32 vcc_lo, vcc_lo, 0x60000
	s_addc_u32 vcc_hi, vcc_hi, 0
	s_add_i32 m0, s37, 0x14000
	s_nop 0
	global_load_lds_dwordx4 v148, vcc
	s_add_i32 m0, s37, 0x16000
	s_nop 0
	global_load_lds_dwordx4 v144, vcc
	s_add_u32 vcc_lo, vcc_lo, 0x20000
	s_addc_u32 vcc_hi, vcc_hi, 0
	s_add_i32 m0, s37, 0x15000
	s_nop 0
	global_load_lds_dwordx4 v148, vcc
	s_add_i32 m0, s37, 0x17000
	s_nop 0
	global_load_lds_dwordx4 v144, vcc
	ds_read_b128 v[32:35], v169 offset:32768
	ds_read_b128 v[36:39], v169 offset:33792
	ds_read_b128 v[40:43], v169 offset:34816
	ds_read_b128 v[44:47], v169 offset:35840
	ds_read_b128 v[162:165], v170 offset:32768
	ds_read_b128 v[174:177], v170 offset:33792
	ds_read_b128 v[178:181], v170 offset:34816
	ds_read_b128 v[182:185], v170 offset:35840
	ds_read_b128 v[186:189], v171 offset:32768
	ds_read_b128 v[190:193], v171 offset:33792
	ds_read_b128 v[194:197], v171 offset:34816
	ds_read_b128 v[198:201], v171 offset:35840
	ds_read_b128 v[202:205], v171 offset:36864
	ds_read_b128 v[206:209], v171 offset:37888
	ds_read_b128 v[210:213], v171 offset:38912
	ds_read_b128 v[214:217], v171 offset:39936
	ds_read_b128 v[220:223], v171 offset:49152
	ds_read_b128 v[224:227], v171 offset:50176
	ds_read_b128 v[228:231], v171 offset:51200
	ds_read_b128 v[232:235], v171 offset:52224
	ds_read_b128 v[236:239], v171 offset:53248
	ds_read_b128 v[240:243], v171 offset:54272
	ds_read_b128 v[244:247], v171 offset:55296
	ds_read_b128 v[248:251], v171 offset:56320
	s_nop 15
	s_nop 15
	s_waitcnt lgkmcnt(0)
	s_barrier
	s_setprio 1
	v_mfma_f32_16x16x32_bf16 v[140:143], v[32:35], v[186:189], v[140:143]
	v_mfma_f32_16x16x32_bf16 v[136:139], v[40:43], v[186:189], v[136:139]
	v_mfma_f32_16x16x32_bf16 v[124:127], v[32:35], v[194:197], v[124:127]
	v_mfma_f32_16x16x32_bf16 v[120:123], v[40:43], v[194:197], v[120:123]
	v_mfma_f32_16x16x32_bf16 v[108:111], v[32:35], v[202:205], v[108:111]
	v_mfma_f32_16x16x32_bf16 v[104:107], v[40:43], v[202:205], v[104:107]
	v_mfma_f32_16x16x32_bf16 v[92:95], v[32:35], v[210:213], v[92:95]
	v_mfma_f32_16x16x32_bf16 v[88:91], v[40:43], v[210:213], v[88:91]
	v_mfma_f32_16x16x32_bf16 v[140:143], v[36:39], v[190:193], v[140:143]
	v_mfma_f32_16x16x32_bf16 v[136:139], v[44:47], v[190:193], v[136:139]
	v_mfma_f32_16x16x32_bf16 v[124:127], v[36:39], v[198:201], v[124:127]
	v_mfma_f32_16x16x32_bf16 v[120:123], v[44:47], v[198:201], v[120:123]
	v_mfma_f32_16x16x32_bf16 v[108:111], v[36:39], v[206:209], v[108:111]
	v_mfma_f32_16x16x32_bf16 v[104:107], v[44:47], v[206:209], v[104:107]
	v_mfma_f32_16x16x32_bf16 v[92:95], v[36:39], v[214:217], v[92:95]
	v_mfma_f32_16x16x32_bf16 v[88:91], v[44:47], v[214:217], v[88:91]
	s_setprio 0
	s_setprio 1
	v_mfma_f32_16x16x32_bf16 v[132:135], v[162:165], v[186:189], v[132:135]
	v_mfma_f32_16x16x32_bf16 v[128:131], v[178:181], v[186:189], v[128:131]
	v_mfma_f32_16x16x32_bf16 v[116:119], v[162:165], v[194:197], v[116:119]
	v_mfma_f32_16x16x32_bf16 v[112:115], v[178:181], v[194:197], v[112:115]
	v_mfma_f32_16x16x32_bf16 v[100:103], v[162:165], v[202:205], v[100:103]
	v_mfma_f32_16x16x32_bf16 v[96:99], v[178:181], v[202:205], v[96:99]
	v_mfma_f32_16x16x32_bf16 v[84:87], v[162:165], v[210:213], v[84:87]
	v_mfma_f32_16x16x32_bf16 v[80:83], v[178:181], v[210:213], v[80:83]
	v_mfma_f32_16x16x32_bf16 v[132:135], v[174:177], v[190:193], v[132:135]
	v_mfma_f32_16x16x32_bf16 v[128:131], v[182:185], v[190:193], v[128:131]
	v_mfma_f32_16x16x32_bf16 v[116:119], v[174:177], v[198:201], v[116:119]
	v_mfma_f32_16x16x32_bf16 v[112:115], v[182:185], v[198:201], v[112:115]
	v_mfma_f32_16x16x32_bf16 v[100:103], v[174:177], v[206:209], v[100:103]
	v_mfma_f32_16x16x32_bf16 v[96:99], v[182:185], v[206:209], v[96:99]
	v_mfma_f32_16x16x32_bf16 v[84:87], v[174:177], v[214:217], v[84:87]
	v_mfma_f32_16x16x32_bf16 v[80:83], v[182:185], v[214:217], v[80:83]
	s_setprio 0
	s_setprio 1
	v_mfma_f32_16x16x32_bf16 v[76:79], v[32:35], v[220:223], v[76:79]
	v_mfma_f32_16x16x32_bf16 v[72:75], v[40:43], v[220:223], v[72:75]
	v_mfma_f32_16x16x32_bf16 v[60:63], v[32:35], v[228:231], v[60:63]
	v_mfma_f32_16x16x32_bf16 v[56:59], v[40:43], v[228:231], v[56:59]
	v_mfma_f32_16x16x32_bf16 v[28:31], v[32:35], v[236:239], v[28:31]
	v_mfma_f32_16x16x32_bf16 v[24:27], v[40:43], v[236:239], v[24:27]
	v_mfma_f32_16x16x32_bf16 v[12:15], v[32:35], v[244:247], v[12:15]
	v_mfma_f32_16x16x32_bf16 v[8:11], v[40:43], v[244:247], v[8:11]
	v_mfma_f32_16x16x32_bf16 v[76:79], v[36:39], v[224:227], v[76:79]
	v_mfma_f32_16x16x32_bf16 v[72:75], v[44:47], v[224:227], v[72:75]
	v_mfma_f32_16x16x32_bf16 v[60:63], v[36:39], v[232:235], v[60:63]
	v_mfma_f32_16x16x32_bf16 v[56:59], v[44:47], v[232:235], v[56:59]
	v_mfma_f32_16x16x32_bf16 v[28:31], v[36:39], v[240:243], v[28:31]
	v_mfma_f32_16x16x32_bf16 v[24:27], v[44:47], v[240:243], v[24:27]
	v_mfma_f32_16x16x32_bf16 v[12:15], v[36:39], v[248:251], v[12:15]
	v_mfma_f32_16x16x32_bf16 v[8:11], v[44:47], v[248:251], v[8:11]
	s_setprio 0
	s_setprio 1
	v_mfma_f32_16x16x32_bf16 v[68:71], v[162:165], v[220:223], v[68:71]
	v_mfma_f32_16x16x32_bf16 v[64:67], v[178:181], v[220:223], v[64:67]
	v_mfma_f32_16x16x32_bf16 v[52:55], v[162:165], v[228:231], v[52:55]
	v_mfma_f32_16x16x32_bf16 v[48:51], v[178:181], v[228:231], v[48:51]
	v_mfma_f32_16x16x32_bf16 v[20:23], v[162:165], v[236:239], v[20:23]
	v_mfma_f32_16x16x32_bf16 v[16:19], v[178:181], v[236:239], v[16:19]
	v_mfma_f32_16x16x32_bf16 v[4:7], v[162:165], v[244:247], v[4:7]
	v_mfma_f32_16x16x32_bf16 v[0:3], v[178:181], v[244:247], v[0:3]
	v_mfma_f32_16x16x32_bf16 v[68:71], v[174:177], v[224:227], v[68:71]
	v_mfma_f32_16x16x32_bf16 v[64:67], v[182:185], v[224:227], v[64:67]
	v_mfma_f32_16x16x32_bf16 v[52:55], v[174:177], v[232:235], v[52:55]
	v_mfma_f32_16x16x32_bf16 v[48:51], v[182:185], v[232:235], v[48:51]
	v_mfma_f32_16x16x32_bf16 v[20:23], v[174:177], v[240:243], v[20:23]
	v_mfma_f32_16x16x32_bf16 v[16:19], v[182:185], v[240:243], v[16:19]
	v_mfma_f32_16x16x32_bf16 v[4:7], v[174:177], v[248:251], v[4:7]
	v_mfma_f32_16x16x32_bf16 v[0:3], v[182:185], v[248:251], v[0:3]
	s_setprio 0
	s_add_i32 s56, s56, 2
	s_add_u32 s12, s12, 0x100
	s_addc_u32 s13, s13, 0
	s_add_u32 s54, s54, 0x100
	s_addc_u32 s55, s55, 0
	s_add_u32 s30, s12, 0xfff80080
	s_addc_u32 s31, s13, -1
	s_cmp_eq_u32 s56, 28
	s_cselect_b32 s35, s25, s31
	s_cselect_b32 s34, s52, s30
	s_cselect_b32 s31, s23, s55
	s_cselect_b32 s30, s53, s54
	s_cmp_gt_u32 s56, 29
	s_waitcnt vmcnt(0)
	s_barrier
	s_cbranch_scc0 .Lk64_lead_p6
	s_branch .Lk64_done_p6

.Lk64_epd_p6_t:
	ds_read_b128 v[32:35], v169 offset:0
	ds_read_b128 v[36:39], v169 offset:1024
	ds_read_b128 v[40:43], v169 offset:2048
	ds_read_b128 v[44:47], v169 offset:3072
	ds_read_b128 v[162:165], v170 offset:0
	ds_read_b128 v[174:177], v170 offset:1024
	ds_read_b128 v[178:181], v170 offset:2048
	ds_read_b128 v[182:185], v170 offset:3072
	ds_read_b128 v[186:189], v171 offset:0
	ds_read_b128 v[190:193], v171 offset:1024
	ds_read_b128 v[194:197], v171 offset:2048
	ds_read_b128 v[198:201], v171 offset:3072
	ds_read_b128 v[202:205], v171 offset:4096
	ds_read_b128 v[206:209], v171 offset:5120
	ds_read_b128 v[210:213], v171 offset:6144
	ds_read_b128 v[214:217], v171 offset:7168
	ds_read_b128 v[220:223], v171 offset:16384
	ds_read_b128 v[224:227], v171 offset:17408
	ds_read_b128 v[228:231], v171 offset:18432
	ds_read_b128 v[232:235], v171 offset:19456
	ds_read_b128 v[236:239], v171 offset:20480
	ds_read_b128 v[240:243], v171 offset:21504
	ds_read_b128 v[244:247], v171 offset:22528
	ds_read_b128 v[248:251], v171 offset:23552
	s_nop 15
	s_nop 15
	s_waitcnt lgkmcnt(0)
	s_barrier
	s_setprio 1
	v_mfma_f32_16x16x32_bf16 v[140:143], v[32:35], v[186:189], v[140:143]
	v_mfma_f32_16x16x32_bf16 v[136:139], v[40:43], v[186:189], v[136:139]
	v_mfma_f32_16x16x32_bf16 v[124:127], v[32:35], v[194:197], v[124:127]
	v_mfma_f32_16x16x32_bf16 v[120:123], v[40:43], v[194:197], v[120:123]
	v_mfma_f32_16x16x32_bf16 v[108:111], v[32:35], v[202:205], v[108:111]
	v_mfma_f32_16x16x32_bf16 v[104:107], v[40:43], v[202:205], v[104:107]
	v_mfma_f32_16x16x32_bf16 v[92:95], v[32:35], v[210:213], v[92:95]
	v_mfma_f32_16x16x32_bf16 v[88:91], v[40:43], v[210:213], v[88:91]
	v_mfma_f32_16x16x32_bf16 v[140:143], v[36:39], v[190:193], v[140:143]
	v_mfma_f32_16x16x32_bf16 v[136:139], v[44:47], v[190:193], v[136:139]
	v_mfma_f32_16x16x32_bf16 v[124:127], v[36:39], v[198:201], v[124:127]
	v_mfma_f32_16x16x32_bf16 v[120:123], v[44:47], v[198:201], v[120:123]
	v_mfma_f32_16x16x32_bf16 v[108:111], v[36:39], v[206:209], v[108:111]
	v_mfma_f32_16x16x32_bf16 v[104:107], v[44:47], v[206:209], v[104:107]
	v_mfma_f32_16x16x32_bf16 v[92:95], v[36:39], v[214:217], v[92:95]
	v_mfma_f32_16x16x32_bf16 v[88:91], v[44:47], v[214:217], v[88:91]
	s_setprio 0
	s_setprio 1
	v_mfma_f32_16x16x32_bf16 v[132:135], v[162:165], v[186:189], v[132:135]
	v_mfma_f32_16x16x32_bf16 v[128:131], v[178:181], v[186:189], v[128:131]
	v_mfma_f32_16x16x32_bf16 v[116:119], v[162:165], v[194:197], v[116:119]
	v_mfma_f32_16x16x32_bf16 v[112:115], v[178:181], v[194:197], v[112:115]
	v_mfma_f32_16x16x32_bf16 v[100:103], v[162:165], v[202:205], v[100:103]
	v_mfma_f32_16x16x32_bf16 v[96:99], v[178:181], v[202:205], v[96:99]
	v_mfma_f32_16x16x32_bf16 v[84:87], v[162:165], v[210:213], v[84:87]
	v_mfma_f32_16x16x32_bf16 v[80:83], v[178:181], v[210:213], v[80:83]
	v_mfma_f32_16x16x32_bf16 v[132:135], v[174:177], v[190:193], v[132:135]
	v_mfma_f32_16x16x32_bf16 v[128:131], v[182:185], v[190:193], v[128:131]
	v_mfma_f32_16x16x32_bf16 v[116:119], v[174:177], v[198:201], v[116:119]
	v_mfma_f32_16x16x32_bf16 v[112:115], v[182:185], v[198:201], v[112:115]
	v_mfma_f32_16x16x32_bf16 v[100:103], v[174:177], v[206:209], v[100:103]
	v_mfma_f32_16x16x32_bf16 v[96:99], v[182:185], v[206:209], v[96:99]
	v_mfma_f32_16x16x32_bf16 v[84:87], v[174:177], v[214:217], v[84:87]
	v_mfma_f32_16x16x32_bf16 v[80:83], v[182:185], v[214:217], v[80:83]
	s_setprio 0
	s_setprio 1
	v_mfma_f32_16x16x32_bf16 v[76:79], v[32:35], v[220:223], v[76:79]
	v_mfma_f32_16x16x32_bf16 v[72:75], v[40:43], v[220:223], v[72:75]
	v_mfma_f32_16x16x32_bf16 v[60:63], v[32:35], v[228:231], v[60:63]
	v_mfma_f32_16x16x32_bf16 v[56:59], v[40:43], v[228:231], v[56:59]
	v_mfma_f32_16x16x32_bf16 v[28:31], v[32:35], v[236:239], v[28:31]
	v_mfma_f32_16x16x32_bf16 v[24:27], v[40:43], v[236:239], v[24:27]
	v_mfma_f32_16x16x32_bf16 v[12:15], v[32:35], v[244:247], v[12:15]
	v_mfma_f32_16x16x32_bf16 v[8:11], v[40:43], v[244:247], v[8:11]
	v_mfma_f32_16x16x32_bf16 v[76:79], v[36:39], v[224:227], v[76:79]
	v_mfma_f32_16x16x32_bf16 v[72:75], v[44:47], v[224:227], v[72:75]
	v_mfma_f32_16x16x32_bf16 v[60:63], v[36:39], v[232:235], v[60:63]
	v_mfma_f32_16x16x32_bf16 v[56:59], v[44:47], v[232:235], v[56:59]
	v_mfma_f32_16x16x32_bf16 v[28:31], v[36:39], v[240:243], v[28:31]
	v_mfma_f32_16x16x32_bf16 v[24:27], v[44:47], v[240:243], v[24:27]
	v_mfma_f32_16x16x32_bf16 v[12:15], v[36:39], v[248:251], v[12:15]
	v_mfma_f32_16x16x32_bf16 v[8:11], v[44:47], v[248:251], v[8:11]
	s_setprio 0
	s_setprio 1
	v_mfma_f32_16x16x32_bf16 v[68:71], v[162:165], v[220:223], v[68:71]
	v_mfma_f32_16x16x32_bf16 v[64:67], v[178:181], v[220:223], v[64:67]
	v_mfma_f32_16x16x32_bf16 v[52:55], v[162:165], v[228:231], v[52:55]
	v_mfma_f32_16x16x32_bf16 v[48:51], v[178:181], v[228:231], v[48:51]
	v_mfma_f32_16x16x32_bf16 v[20:23], v[162:165], v[236:239], v[20:23]
	v_mfma_f32_16x16x32_bf16 v[16:19], v[178:181], v[236:239], v[16:19]
	v_mfma_f32_16x16x32_bf16 v[4:7], v[162:165], v[244:247], v[4:7]
	v_mfma_f32_16x16x32_bf16 v[0:3], v[178:181], v[244:247], v[0:3]
	v_mfma_f32_16x16x32_bf16 v[68:71], v[174:177], v[224:227], v[68:71]
	v_mfma_f32_16x16x32_bf16 v[64:67], v[182:185], v[224:227], v[64:67]
	v_mfma_f32_16x16x32_bf16 v[52:55], v[174:177], v[232:235], v[52:55]
	v_mfma_f32_16x16x32_bf16 v[48:51], v[182:185], v[232:235], v[48:51]
	v_mfma_f32_16x16x32_bf16 v[20:23], v[174:177], v[240:243], v[20:23]
	v_mfma_f32_16x16x32_bf16 v[16:19], v[182:185], v[240:243], v[16:19]
	v_mfma_f32_16x16x32_bf16 v[4:7], v[174:177], v[248:251], v[4:7]
	v_mfma_f32_16x16x32_bf16 v[0:3], v[182:185], v[248:251], v[0:3]
	s_setprio 0
	s_waitcnt vmcnt(0)
	s_barrier
	s_add_u32 vcc_lo, s34, 0x0
	s_addc_u32 vcc_hi, s35, 0
	s_add_i32 m0, s37, 0x2000
	s_nop 0
	global_load_lds_dwordx4 v146, vcc
	s_add_u32 vcc_lo, vcc_lo, 0x20000
	s_addc_u32 vcc_hi, vcc_hi, 0
	s_add_i32 m0, s37, 0x1000
	s_nop 0
	global_load_lds_dwordx4 v150, vcc
	s_add_u32 vcc_lo, vcc_lo, 0x60000
	s_addc_u32 vcc_hi, vcc_hi, 0
	s_add_i32 m0, s37, 0x6000
	s_nop 0
	global_load_lds_dwordx4 v146, vcc
	s_add_u32 vcc_lo, vcc_lo, 0x20000
	s_addc_u32 vcc_hi, vcc_hi, 0
	s_add_i32 m0, s37, 0x5000
	s_nop 0
	global_load_lds_dwordx4 v150, vcc
	s_add_u32 vcc_lo, s34, 0x80
	s_addc_u32 vcc_hi, s35, 0
	s_add_i32 m0, s37, 0x8000
	s_nop 0
	global_load_lds_dwordx4 v150, vcc
	s_sub_u32 vcc_lo, vcc_lo, 0x20000
	s_subb_u32 vcc_hi, vcc_hi, 0
	s_add_i32 m0, s37, 0x7000
	s_nop 0
	global_load_lds_dwordx4 v150, vcc
	s_add_u32 vcc_lo, vcc_lo, 0xa0000
	s_addc_u32 vcc_hi, vcc_hi, 0
	s_add_i32 m0, s37, 0xc000
	s_nop 0
	global_load_lds_dwordx4 v150, vcc
	s_sub_u32 vcc_lo, vcc_lo, 0x20000
	s_subb_u32 vcc_hi, vcc_hi, 0
	s_add_i32 m0, s37, 0xb000
	s_nop 0
	global_load_lds_dwordx4 v150, vcc
	ds_read_b128 v[32:35], v169 offset:32768
	ds_read_b128 v[36:39], v169 offset:33792
	ds_read_b128 v[40:43], v169 offset:34816
	ds_read_b128 v[44:47], v169 offset:35840
	ds_read_b128 v[162:165], v170 offset:32768
	ds_read_b128 v[174:177], v170 offset:33792
	ds_read_b128 v[178:181], v170 offset:34816
	ds_read_b128 v[182:185], v170 offset:35840
	ds_read_b128 v[186:189], v171 offset:32768
	ds_read_b128 v[190:193], v171 offset:33792
	ds_read_b128 v[194:197], v171 offset:34816
	ds_read_b128 v[198:201], v171 offset:35840
	ds_read_b128 v[202:205], v171 offset:36864
	ds_read_b128 v[206:209], v171 offset:37888
	ds_read_b128 v[210:213], v171 offset:38912
	ds_read_b128 v[214:217], v171 offset:39936
	ds_read_b128 v[220:223], v171 offset:49152
	ds_read_b128 v[224:227], v171 offset:50176
	ds_read_b128 v[228:231], v171 offset:51200
	ds_read_b128 v[232:235], v171 offset:52224
	ds_read_b128 v[236:239], v171 offset:53248
	ds_read_b128 v[240:243], v171 offset:54272
	ds_read_b128 v[244:247], v171 offset:55296
	ds_read_b128 v[248:251], v171 offset:56320
	s_nop 15
	s_nop 15
	s_waitcnt lgkmcnt(0)
	s_barrier
	s_setprio 1
	v_mfma_f32_16x16x32_bf16 v[140:143], v[32:35], v[186:189], v[140:143]
	v_mfma_f32_16x16x32_bf16 v[136:139], v[40:43], v[186:189], v[136:139]
	v_mfma_f32_16x16x32_bf16 v[124:127], v[32:35], v[194:197], v[124:127]
	v_mfma_f32_16x16x32_bf16 v[120:123], v[40:43], v[194:197], v[120:123]
	v_mfma_f32_16x16x32_bf16 v[108:111], v[32:35], v[202:205], v[108:111]
	v_mfma_f32_16x16x32_bf16 v[104:107], v[40:43], v[202:205], v[104:107]
	v_mfma_f32_16x16x32_bf16 v[92:95], v[32:35], v[210:213], v[92:95]
	v_mfma_f32_16x16x32_bf16 v[88:91], v[40:43], v[210:213], v[88:91]
	v_mfma_f32_16x16x32_bf16 v[140:143], v[36:39], v[190:193], v[140:143]
	v_mfma_f32_16x16x32_bf16 v[136:139], v[44:47], v[190:193], v[136:139]
	v_mfma_f32_16x16x32_bf16 v[124:127], v[36:39], v[198:201], v[124:127]
	v_mfma_f32_16x16x32_bf16 v[120:123], v[44:47], v[198:201], v[120:123]
	v_mfma_f32_16x16x32_bf16 v[108:111], v[36:39], v[206:209], v[108:111]
	v_mfma_f32_16x16x32_bf16 v[104:107], v[44:47], v[206:209], v[104:107]
	v_mfma_f32_16x16x32_bf16 v[92:95], v[36:39], v[214:217], v[92:95]
	v_mfma_f32_16x16x32_bf16 v[88:91], v[44:47], v[214:217], v[88:91]
	s_setprio 0
	s_setprio 1
	v_mfma_f32_16x16x32_bf16 v[132:135], v[162:165], v[186:189], v[132:135]
	v_mfma_f32_16x16x32_bf16 v[128:131], v[178:181], v[186:189], v[128:131]
	v_mfma_f32_16x16x32_bf16 v[116:119], v[162:165], v[194:197], v[116:119]
	v_mfma_f32_16x16x32_bf16 v[112:115], v[178:181], v[194:197], v[112:115]
	v_mfma_f32_16x16x32_bf16 v[100:103], v[162:165], v[202:205], v[100:103]
	v_mfma_f32_16x16x32_bf16 v[96:99], v[178:181], v[202:205], v[96:99]
	v_mfma_f32_16x16x32_bf16 v[84:87], v[162:165], v[210:213], v[84:87]
	v_mfma_f32_16x16x32_bf16 v[80:83], v[178:181], v[210:213], v[80:83]
	v_mfma_f32_16x16x32_bf16 v[132:135], v[174:177], v[190:193], v[132:135]
	v_mfma_f32_16x16x32_bf16 v[128:131], v[182:185], v[190:193], v[128:131]
	v_mfma_f32_16x16x32_bf16 v[116:119], v[174:177], v[198:201], v[116:119]
	v_mfma_f32_16x16x32_bf16 v[112:115], v[182:185], v[198:201], v[112:115]
	v_mfma_f32_16x16x32_bf16 v[100:103], v[174:177], v[206:209], v[100:103]
	v_mfma_f32_16x16x32_bf16 v[96:99], v[182:185], v[206:209], v[96:99]
	v_mfma_f32_16x16x32_bf16 v[84:87], v[174:177], v[214:217], v[84:87]
	v_mfma_f32_16x16x32_bf16 v[80:83], v[182:185], v[214:217], v[80:83]
	s_setprio 0
	s_setprio 1
	v_mfma_f32_16x16x32_bf16 v[76:79], v[32:35], v[220:223], v[76:79]
	v_mfma_f32_16x16x32_bf16 v[72:75], v[40:43], v[220:223], v[72:75]
	v_mfma_f32_16x16x32_bf16 v[60:63], v[32:35], v[228:231], v[60:63]
	v_mfma_f32_16x16x32_bf16 v[56:59], v[40:43], v[228:231], v[56:59]
	v_mfma_f32_16x16x32_bf16 v[28:31], v[32:35], v[236:239], v[28:31]
	v_mfma_f32_16x16x32_bf16 v[24:27], v[40:43], v[236:239], v[24:27]
	v_mfma_f32_16x16x32_bf16 v[12:15], v[32:35], v[244:247], v[12:15]
	v_mfma_f32_16x16x32_bf16 v[8:11], v[40:43], v[244:247], v[8:11]
	v_mfma_f32_16x16x32_bf16 v[76:79], v[36:39], v[224:227], v[76:79]
	v_mfma_f32_16x16x32_bf16 v[72:75], v[44:47], v[224:227], v[72:75]
	v_mfma_f32_16x16x32_bf16 v[60:63], v[36:39], v[232:235], v[60:63]
	v_mfma_f32_16x16x32_bf16 v[56:59], v[44:47], v[232:235], v[56:59]
	v_mfma_f32_16x16x32_bf16 v[28:31], v[36:39], v[240:243], v[28:31]
	v_mfma_f32_16x16x32_bf16 v[24:27], v[44:47], v[240:243], v[24:27]
	v_mfma_f32_16x16x32_bf16 v[12:15], v[36:39], v[248:251], v[12:15]
	v_mfma_f32_16x16x32_bf16 v[8:11], v[44:47], v[248:251], v[8:11]
	s_setprio 0
	s_setprio 1
	v_mfma_f32_16x16x32_bf16 v[68:71], v[162:165], v[220:223], v[68:71]
	v_mfma_f32_16x16x32_bf16 v[64:67], v[178:181], v[220:223], v[64:67]
	v_mfma_f32_16x16x32_bf16 v[52:55], v[162:165], v[228:231], v[52:55]
	v_mfma_f32_16x16x32_bf16 v[48:51], v[178:181], v[228:231], v[48:51]
	v_mfma_f32_16x16x32_bf16 v[20:23], v[162:165], v[236:239], v[20:23]
	v_mfma_f32_16x16x32_bf16 v[16:19], v[178:181], v[236:239], v[16:19]
	v_mfma_f32_16x16x32_bf16 v[4:7], v[162:165], v[244:247], v[4:7]
	v_mfma_f32_16x16x32_bf16 v[0:3], v[178:181], v[244:247], v[0:3]
	v_mfma_f32_16x16x32_bf16 v[68:71], v[174:177], v[224:227], v[68:71]
	v_mfma_f32_16x16x32_bf16 v[64:67], v[182:185], v[224:227], v[64:67]
	v_mfma_f32_16x16x32_bf16 v[52:55], v[174:177], v[232:235], v[52:55]
	v_mfma_f32_16x16x32_bf16 v[48:51], v[182:185], v[232:235], v[48:51]
	v_mfma_f32_16x16x32_bf16 v[20:23], v[174:177], v[240:243], v[20:23]
	v_mfma_f32_16x16x32_bf16 v[16:19], v[182:185], v[240:243], v[16:19]
	v_mfma_f32_16x16x32_bf16 v[4:7], v[174:177], v[248:251], v[4:7]
	v_mfma_f32_16x16x32_bf16 v[0:3], v[182:185], v[248:251], v[0:3]
	s_setprio 0
	s_add_i32 s56, s56, 2
	s_add_u32 s12, s12, 0x100
	s_addc_u32 s13, s13, 0
	s_add_u32 s54, s54, 0x100
	s_addc_u32 s55, s55, 0
	s_add_u32 s30, s12, 0xfff80080
	s_addc_u32 s31, s13, -1
	s_cmp_eq_u32 s56, 28
	s_cselect_b32 s35, s25, s31
	s_cselect_b32 s34, s52, s30
	s_cselect_b32 s31, s23, s55
	s_cselect_b32 s30, s53, s54
	s_cmp_gt_u32 s56, 29
	s_waitcnt vmcnt(0)
	s_barrier
	s_cbranch_scc0 .Lk64_trail_p6

.Lk64_lead_p7:
	s_sub_u32 vcc_lo, s46, 0x80
	s_subb_u32 vcc_hi, s47, 0
	s_add_i32 m0, s30, 0x18000
	s_nop 0
	global_load_lds_dwordx4 v130, vcc
	s_add_i32 m0, s30, 0x1a000
	s_nop 0
	global_load_lds_dwordx4 v134, vcc
	s_add_u32 vcc_lo, vcc_lo, 0x58000
	s_addc_u32 vcc_hi, vcc_hi, 0
	s_add_i32 m0, s30, 0x19000
	s_nop 0
	global_load_lds_dwordx4 v130, vcc
	s_add_i32 m0, s30, 0x1b000
	s_nop 0
	global_load_lds_dwordx4 v134, vcc
	s_add_u32 vcc_lo, vcc_lo, 0x108000
	s_addc_u32 vcc_hi, vcc_hi, 0
	s_add_i32 m0, s30, 0x1c000
	s_nop 0
	global_load_lds_dwordx4 v130, vcc
	s_add_i32 m0, s30, 0x1e000
	s_nop 0
	global_load_lds_dwordx4 v134, vcc
	s_add_u32 vcc_lo, vcc_lo, 0x58000
	s_addc_u32 vcc_hi, vcc_hi, 0
	s_add_i32 m0, s30, 0x1d000
	s_nop 0
	global_load_lds_dwordx4 v130, vcc
	s_add_i32 m0, s30, 0x1f000
	s_nop 0
	global_load_lds_dwordx4 v134, vcc
	ds_read_b128 v[144:147], v185 offset:0
	ds_read_b128 v[148:151], v185 offset:1024
	ds_read_b128 v[152:155], v185 offset:2048
	ds_read_b128 v[156:159], v185 offset:3072
	ds_read_b128 v[160:163], v186 offset:0
	ds_read_b128 v[164:167], v186 offset:1024
	ds_read_b128 v[168:171], v186 offset:2048
	ds_read_b128 v[172:175], v186 offset:3072
	ds_read_b128 v[176:179], v187 offset:0
	ds_read_b128 v[190:193], v187 offset:1024
	ds_read_b128 v[194:197], v187 offset:2048
	ds_read_b128 v[198:201], v187 offset:3072
	ds_read_b128 v[202:205], v187 offset:4096
	ds_read_b128 v[206:209], v187 offset:5120
	ds_read_b128 v[210:213], v187 offset:6144
	ds_read_b128 v[214:217], v187 offset:7168
	ds_read_b128 v[220:223], v187 offset:16384
	ds_read_b128 v[224:227], v187 offset:17408
	ds_read_b128 v[228:231], v187 offset:18432
	ds_read_b128 v[232:235], v187 offset:19456
	ds_read_b128 v[236:239], v187 offset:20480
	ds_read_b128 v[240:243], v187 offset:21504
	ds_read_b128 v[244:247], v187 offset:22528
	ds_read_b128 v[248:251], v187 offset:23552
	s_nop 15
	s_nop 15
	s_waitcnt lgkmcnt(0)
	s_barrier
	s_setprio 1
	v_mfma_f32_16x16x32_bf16 v[72:75], v[144:147], v[176:179], v[72:75]
	v_mfma_f32_16x16x32_bf16 v[76:79], v[152:155], v[176:179], v[76:79]
	v_mfma_f32_16x16x32_bf16 v[96:99], v[144:147], v[194:197], v[96:99]
	v_mfma_f32_16x16x32_bf16 v[100:103], v[152:155], v[194:197], v[100:103]
	v_mfma_f32_16x16x32_bf16 v[120:123], v[144:147], v[202:205], v[120:123]
	v_mfma_f32_16x16x32_bf16 v[124:127], v[152:155], v[202:205], v[124:127]
	v_mfma_f32_16x16x32_bf16 v[92:95], v[144:147], v[210:213], v[92:95]
	v_mfma_f32_16x16x32_bf16 v[84:87], v[152:155], v[210:213], v[84:87]
	v_mfma_f32_16x16x32_bf16 v[72:75], v[148:151], v[190:193], v[72:75]
	v_mfma_f32_16x16x32_bf16 v[76:79], v[156:159], v[190:193], v[76:79]
	v_mfma_f32_16x16x32_bf16 v[96:99], v[148:151], v[198:201], v[96:99]
	v_mfma_f32_16x16x32_bf16 v[100:103], v[156:159], v[198:201], v[100:103]
	v_mfma_f32_16x16x32_bf16 v[120:123], v[148:151], v[206:209], v[120:123]
	v_mfma_f32_16x16x32_bf16 v[124:127], v[156:159], v[206:209], v[124:127]
	v_mfma_f32_16x16x32_bf16 v[92:95], v[148:151], v[214:217], v[92:95]
	v_mfma_f32_16x16x32_bf16 v[84:87], v[156:159], v[214:217], v[84:87]
	s_setprio 0
	s_setprio 1
	v_mfma_f32_16x16x32_bf16 v[80:83], v[160:163], v[176:179], v[80:83]
	v_mfma_f32_16x16x32_bf16 v[88:91], v[168:171], v[176:179], v[88:91]
	v_mfma_f32_16x16x32_bf16 v[108:111], v[160:163], v[194:197], v[108:111]
	v_mfma_f32_16x16x32_bf16 v[112:115], v[168:171], v[194:197], v[112:115]
	v_mfma_f32_16x16x32_bf16 v[116:119], v[160:163], v[202:205], v[116:119]
	v_mfma_f32_16x16x32_bf16 v[104:107], v[168:171], v[202:205], v[104:107]
	v_mfma_f32_16x16x32_bf16 v[68:71], v[160:163], v[210:213], v[68:71]
	v_mfma_f32_16x16x32_bf16 v[64:67], v[168:171], v[210:213], v[64:67]
	v_mfma_f32_16x16x32_bf16 v[80:83], v[164:167], v[190:193], v[80:83]
	v_mfma_f32_16x16x32_bf16 v[88:91], v[172:175], v[190:193], v[88:91]
	v_mfma_f32_16x16x32_bf16 v[108:111], v[164:167], v[198:201], v[108:111]
	v_mfma_f32_16x16x32_bf16 v[112:115], v[172:175], v[198:201], v[112:115]
	v_mfma_f32_16x16x32_bf16 v[116:119], v[164:167], v[206:209], v[116:119]
	v_mfma_f32_16x16x32_bf16 v[104:107], v[172:175], v[206:209], v[104:107]
	v_mfma_f32_16x16x32_bf16 v[68:71], v[164:167], v[214:217], v[68:71]
	v_mfma_f32_16x16x32_bf16 v[64:67], v[172:175], v[214:217], v[64:67]
	s_setprio 0
	s_setprio 1
	v_mfma_f32_16x16x32_bf16 v[60:63], v[144:147], v[220:223], v[60:63]
	v_mfma_f32_16x16x32_bf16 v[56:59], v[152:155], v[220:223], v[56:59]
	v_mfma_f32_16x16x32_bf16 v[44:47], v[144:147], v[228:231], v[44:47]
	v_mfma_f32_16x16x32_bf16 v[40:43], v[152:155], v[228:231], v[40:43]
	v_mfma_f32_16x16x32_bf16 v[28:31], v[144:147], v[236:239], v[28:31]
	v_mfma_f32_16x16x32_bf16 v[24:27], v[152:155], v[236:239], v[24:27]
	v_mfma_f32_16x16x32_bf16 v[12:15], v[144:147], v[244:247], v[12:15]
	v_mfma_f32_16x16x32_bf16 v[8:11], v[152:155], v[244:247], v[8:11]
	v_mfma_f32_16x16x32_bf16 v[60:63], v[148:151], v[224:227], v[60:63]
	v_mfma_f32_16x16x32_bf16 v[56:59], v[156:159], v[224:227], v[56:59]
	v_mfma_f32_16x16x32_bf16 v[44:47], v[148:151], v[232:235], v[44:47]
	v_mfma_f32_16x16x32_bf16 v[40:43], v[156:159], v[232:235], v[40:43]
	v_mfma_f32_16x16x32_bf16 v[28:31], v[148:151], v[240:243], v[28:31]
	v_mfma_f32_16x16x32_bf16 v[24:27], v[156:159], v[240:243], v[24:27]
	v_mfma_f32_16x16x32_bf16 v[12:15], v[148:151], v[248:251], v[12:15]
	v_mfma_f32_16x16x32_bf16 v[8:11], v[156:159], v[248:251], v[8:11]
	s_setprio 0
	s_setprio 1
	v_mfma_f32_16x16x32_bf16 v[52:55], v[160:163], v[220:223], v[52:55]
	v_mfma_f32_16x16x32_bf16 v[48:51], v[168:171], v[220:223], v[48:51]
	v_mfma_f32_16x16x32_bf16 v[36:39], v[160:163], v[228:231], v[36:39]
	v_mfma_f32_16x16x32_bf16 v[32:35], v[168:171], v[228:231], v[32:35]
	v_mfma_f32_16x16x32_bf16 v[20:23], v[160:163], v[236:239], v[20:23]
	v_mfma_f32_16x16x32_bf16 v[16:19], v[168:171], v[236:239], v[16:19]
	v_mfma_f32_16x16x32_bf16 v[4:7], v[160:163], v[244:247], v[4:7]
	v_mfma_f32_16x16x32_bf16 v[0:3], v[168:171], v[244:247], v[0:3]
	v_mfma_f32_16x16x32_bf16 v[52:55], v[164:167], v[224:227], v[52:55]
	v_mfma_f32_16x16x32_bf16 v[48:51], v[172:175], v[224:227], v[48:51]
	v_mfma_f32_16x16x32_bf16 v[36:39], v[164:167], v[232:235], v[36:39]
	v_mfma_f32_16x16x32_bf16 v[32:35], v[172:175], v[232:235], v[32:35]
	v_mfma_f32_16x16x32_bf16 v[20:23], v[164:167], v[240:243], v[20:23]
	v_mfma_f32_16x16x32_bf16 v[16:19], v[172:175], v[240:243], v[16:19]
	v_mfma_f32_16x16x32_bf16 v[4:7], v[164:167], v[248:251], v[4:7]
	v_mfma_f32_16x16x32_bf16 v[0:3], v[172:175], v[248:251], v[0:3]
	s_setprio 0
	s_waitcnt vmcnt(0)
	s_barrier
	s_add_u32 vcc_lo, s26, 0x0
	s_addc_u32 vcc_hi, s27, 0
	s_add_i32 m0, s30, 0x10000
	s_nop 0
	global_load_lds_dwordx4 v130, vcc
	s_add_i32 m0, s30, 0x12000
	s_nop 0
	global_load_lds_dwordx4 v134, vcc
	s_add_u32 vcc_lo, vcc_lo, 0x58000
	s_addc_u32 vcc_hi, vcc_hi, 0
	s_add_i32 m0, s30, 0x11000
	s_nop 0
	global_load_lds_dwordx4 v130, vcc
	s_add_i32 m0, s30, 0x13000
	s_nop 0
	global_load_lds_dwordx4 v134, vcc
	s_add_u32 vcc_lo, vcc_lo, 0x108000
	s_addc_u32 vcc_hi, vcc_hi, 0
	s_add_i32 m0, s30, 0x14000
	s_nop 0
	global_load_lds_dwordx4 v130, vcc
	s_add_i32 m0, s30, 0x16000
	s_nop 0
	global_load_lds_dwordx4 v134, vcc
	s_add_u32 vcc_lo, vcc_lo, 0x58000
	s_addc_u32 vcc_hi, vcc_hi, 0
	s_add_i32 m0, s30, 0x15000
	s_nop 0
	global_load_lds_dwordx4 v130, vcc
	s_add_i32 m0, s30, 0x17000
	s_nop 0
	global_load_lds_dwordx4 v134, vcc
	ds_read_b128 v[144:147], v185 offset:32768
	ds_read_b128 v[148:151], v185 offset:33792
	ds_read_b128 v[152:155], v185 offset:34816
	ds_read_b128 v[156:159], v185 offset:35840
	ds_read_b128 v[160:163], v186 offset:32768
	ds_read_b128 v[164:167], v186 offset:33792
	ds_read_b128 v[168:171], v186 offset:34816
	ds_read_b128 v[172:175], v186 offset:35840
	ds_read_b128 v[176:179], v187 offset:32768
	ds_read_b128 v[190:193], v187 offset:33792
	ds_read_b128 v[194:197], v187 offset:34816
	ds_read_b128 v[198:201], v187 offset:35840
	ds_read_b128 v[202:205], v187 offset:36864
	ds_read_b128 v[206:209], v187 offset:37888
	ds_read_b128 v[210:213], v187 offset:38912
	ds_read_b128 v[214:217], v187 offset:39936
	ds_read_b128 v[220:223], v187 offset:49152
	ds_read_b128 v[224:227], v187 offset:50176
	ds_read_b128 v[228:231], v187 offset:51200
	ds_read_b128 v[232:235], v187 offset:52224
	ds_read_b128 v[236:239], v187 offset:53248
	ds_read_b128 v[240:243], v187 offset:54272
	ds_read_b128 v[244:247], v187 offset:55296
	ds_read_b128 v[248:251], v187 offset:56320
	s_nop 15
	s_nop 15
	s_waitcnt lgkmcnt(0)
	s_barrier
	s_setprio 1
	v_mfma_f32_16x16x32_bf16 v[72:75], v[144:147], v[176:179], v[72:75]
	v_mfma_f32_16x16x32_bf16 v[76:79], v[152:155], v[176:179], v[76:79]
	v_mfma_f32_16x16x32_bf16 v[96:99], v[144:147], v[194:197], v[96:99]
	v_mfma_f32_16x16x32_bf16 v[100:103], v[152:155], v[194:197], v[100:103]
	v_mfma_f32_16x16x32_bf16 v[120:123], v[144:147], v[202:205], v[120:123]
	v_mfma_f32_16x16x32_bf16 v[124:127], v[152:155], v[202:205], v[124:127]
	v_mfma_f32_16x16x32_bf16 v[92:95], v[144:147], v[210:213], v[92:95]
	v_mfma_f32_16x16x32_bf16 v[84:87], v[152:155], v[210:213], v[84:87]
	v_mfma_f32_16x16x32_bf16 v[72:75], v[148:151], v[190:193], v[72:75]
	v_mfma_f32_16x16x32_bf16 v[76:79], v[156:159], v[190:193], v[76:79]
	v_mfma_f32_16x16x32_bf16 v[96:99], v[148:151], v[198:201], v[96:99]
	v_mfma_f32_16x16x32_bf16 v[100:103], v[156:159], v[198:201], v[100:103]
	v_mfma_f32_16x16x32_bf16 v[120:123], v[148:151], v[206:209], v[120:123]
	v_mfma_f32_16x16x32_bf16 v[124:127], v[156:159], v[206:209], v[124:127]
	v_mfma_f32_16x16x32_bf16 v[92:95], v[148:151], v[214:217], v[92:95]
	v_mfma_f32_16x16x32_bf16 v[84:87], v[156:159], v[214:217], v[84:87]
	s_setprio 0
	s_setprio 1
	v_mfma_f32_16x16x32_bf16 v[80:83], v[160:163], v[176:179], v[80:83]
	v_mfma_f32_16x16x32_bf16 v[88:91], v[168:171], v[176:179], v[88:91]
	v_mfma_f32_16x16x32_bf16 v[108:111], v[160:163], v[194:197], v[108:111]
	v_mfma_f32_16x16x32_bf16 v[112:115], v[168:171], v[194:197], v[112:115]
	v_mfma_f32_16x16x32_bf16 v[116:119], v[160:163], v[202:205], v[116:119]
	v_mfma_f32_16x16x32_bf16 v[104:107], v[168:171], v[202:205], v[104:107]
	v_mfma_f32_16x16x32_bf16 v[68:71], v[160:163], v[210:213], v[68:71]
	v_mfma_f32_16x16x32_bf16 v[64:67], v[168:171], v[210:213], v[64:67]
	v_mfma_f32_16x16x32_bf16 v[80:83], v[164:167], v[190:193], v[80:83]
	v_mfma_f32_16x16x32_bf16 v[88:91], v[172:175], v[190:193], v[88:91]
	v_mfma_f32_16x16x32_bf16 v[108:111], v[164:167], v[198:201], v[108:111]
	v_mfma_f32_16x16x32_bf16 v[112:115], v[172:175], v[198:201], v[112:115]
	v_mfma_f32_16x16x32_bf16 v[116:119], v[164:167], v[206:209], v[116:119]
	v_mfma_f32_16x16x32_bf16 v[104:107], v[172:175], v[206:209], v[104:107]
	v_mfma_f32_16x16x32_bf16 v[68:71], v[164:167], v[214:217], v[68:71]
	v_mfma_f32_16x16x32_bf16 v[64:67], v[172:175], v[214:217], v[64:67]
	s_setprio 0
	s_setprio 1
	v_mfma_f32_16x16x32_bf16 v[60:63], v[144:147], v[220:223], v[60:63]
	v_mfma_f32_16x16x32_bf16 v[56:59], v[152:155], v[220:223], v[56:59]
	v_mfma_f32_16x16x32_bf16 v[44:47], v[144:147], v[228:231], v[44:47]
	v_mfma_f32_16x16x32_bf16 v[40:43], v[152:155], v[228:231], v[40:43]
	v_mfma_f32_16x16x32_bf16 v[28:31], v[144:147], v[236:239], v[28:31]
	v_mfma_f32_16x16x32_bf16 v[24:27], v[152:155], v[236:239], v[24:27]
	v_mfma_f32_16x16x32_bf16 v[12:15], v[144:147], v[244:247], v[12:15]
	v_mfma_f32_16x16x32_bf16 v[8:11], v[152:155], v[244:247], v[8:11]
	v_mfma_f32_16x16x32_bf16 v[60:63], v[148:151], v[224:227], v[60:63]
	v_mfma_f32_16x16x32_bf16 v[56:59], v[156:159], v[224:227], v[56:59]
	v_mfma_f32_16x16x32_bf16 v[44:47], v[148:151], v[232:235], v[44:47]
	v_mfma_f32_16x16x32_bf16 v[40:43], v[156:159], v[232:235], v[40:43]
	v_mfma_f32_16x16x32_bf16 v[28:31], v[148:151], v[240:243], v[28:31]
	v_mfma_f32_16x16x32_bf16 v[24:27], v[156:159], v[240:243], v[24:27]
	v_mfma_f32_16x16x32_bf16 v[12:15], v[148:151], v[248:251], v[12:15]
	v_mfma_f32_16x16x32_bf16 v[8:11], v[156:159], v[248:251], v[8:11]
	s_setprio 0
	s_setprio 1
	v_mfma_f32_16x16x32_bf16 v[52:55], v[160:163], v[220:223], v[52:55]
	v_mfma_f32_16x16x32_bf16 v[48:51], v[168:171], v[220:223], v[48:51]
	v_mfma_f32_16x16x32_bf16 v[36:39], v[160:163], v[228:231], v[36:39]
	v_mfma_f32_16x16x32_bf16 v[32:35], v[168:171], v[228:231], v[32:35]
	v_mfma_f32_16x16x32_bf16 v[20:23], v[160:163], v[236:239], v[20:23]
	v_mfma_f32_16x16x32_bf16 v[16:19], v[168:171], v[236:239], v[16:19]
	v_mfma_f32_16x16x32_bf16 v[4:7], v[160:163], v[244:247], v[4:7]
	v_mfma_f32_16x16x32_bf16 v[0:3], v[168:171], v[244:247], v[0:3]
	v_mfma_f32_16x16x32_bf16 v[52:55], v[164:167], v[224:227], v[52:55]
	v_mfma_f32_16x16x32_bf16 v[48:51], v[172:175], v[224:227], v[48:51]
	v_mfma_f32_16x16x32_bf16 v[36:39], v[164:167], v[232:235], v[36:39]
	v_mfma_f32_16x16x32_bf16 v[32:35], v[172:175], v[232:235], v[32:35]
	v_mfma_f32_16x16x32_bf16 v[20:23], v[164:167], v[240:243], v[20:23]
	v_mfma_f32_16x16x32_bf16 v[16:19], v[172:175], v[240:243], v[16:19]
	v_mfma_f32_16x16x32_bf16 v[4:7], v[164:167], v[248:251], v[4:7]
	v_mfma_f32_16x16x32_bf16 v[0:3], v[172:175], v[248:251], v[0:3]
	s_setprio 0
	s_add_i32 s56, s56, 2
	s_add_u32 s46, s46, 0x100
	s_addc_u32 s47, s47, 0
	s_mov_b64 s[22:23], s[24:25]
	s_add_u32 s24, s22, 0x100
	s_addc_u32 s25, s23, 0
	s_cmpk_eq_i32 s56, 0x54
	s_cselect_b32 s29, s19, s25
	s_cselect_b32 s28, s18, s24
	s_cselect_b32 s27, s21, s47
	s_cselect_b32 s26, s20, s46
	s_cmpk_gt_u32 s56, 0x55
	s_waitcnt vmcnt(0)
	s_barrier
	s_cbranch_scc0 .Lk64_lead_p7
	s_branch .Lk64_done_p7
.Lk64_trail_p7:
	s_add_u32 vcc_lo, s22, 0x80
	s_addc_u32 vcc_hi, s23, 0
	s_add_i32 m0, s30, 0xa000
	s_nop 0
	global_load_lds_dwordx4 v132, vcc
	s_add_u32 vcc_lo, vcc_lo, 0x58000
	s_addc_u32 vcc_hi, vcc_hi, 0
	s_add_i32 m0, s30, 0x9000
	s_nop 0
	global_load_lds_dwordx4 v128, vcc
	s_add_u32 vcc_lo, vcc_lo, 0x108000
	s_addc_u32 vcc_hi, vcc_hi, 0
	s_add_i32 m0, s30, 0xe000
	s_nop 0
	global_load_lds_dwordx4 v132, vcc
	s_add_u32 vcc_lo, vcc_lo, 0x58000
	s_addc_u32 vcc_hi, vcc_hi, 0
	s_add_i32 m0, s30, 0xd000
	s_nop 0
	global_load_lds_dwordx4 v128, vcc
	s_add_u32 vcc_lo, s28, 0x0
	s_addc_u32 vcc_hi, s29, 0
	s_mov_b32 m0, s30
	s_nop 0
	global_load_lds_dwordx4 v128, vcc
	s_sub_u32 vcc_lo, vcc_lo, 0x58000
	s_subb_u32 vcc_hi, vcc_hi, 0
	s_sub_i32 m0, s30, 0x1000
	s_nop 0
	global_load_lds_dwordx4 v128, vcc
	s_add_u32 vcc_lo, vcc_lo, 0x1b8000
	s_addc_u32 vcc_hi, vcc_hi, 0
	s_add_i32 m0, s30, 0x4000
	s_nop 0
	global_load_lds_dwordx4 v128, vcc
	s_sub_u32 vcc_lo, vcc_lo, 0x58000
	s_subb_u32 vcc_hi, vcc_hi, 0
	s_add_i32 m0, s30, 0x3000
	s_nop 0
	global_load_lds_dwordx4 v128, vcc
	ds_read_b128 v[144:147], v185 offset:0
	ds_read_b128 v[148:151], v185 offset:1024
	ds_read_b128 v[152:155], v185 offset:2048
	ds_read_b128 v[156:159], v185 offset:3072
	ds_read_b128 v[160:163], v186 offset:0
	ds_read_b128 v[164:167], v186 offset:1024
	ds_read_b128 v[168:171], v186 offset:2048
	ds_read_b128 v[172:175], v186 offset:3072
	ds_read_b128 v[176:179], v187 offset:0
	ds_read_b128 v[190:193], v187 offset:1024
	ds_read_b128 v[194:197], v187 offset:2048
	ds_read_b128 v[198:201], v187 offset:3072
	ds_read_b128 v[202:205], v187 offset:4096
	ds_read_b128 v[206:209], v187 offset:5120
	ds_read_b128 v[210:213], v187 offset:6144
	ds_read_b128 v[214:217], v187 offset:7168
	ds_read_b128 v[220:223], v187 offset:16384
	ds_read_b128 v[224:227], v187 offset:17408
	ds_read_b128 v[228:231], v187 offset:18432
	ds_read_b128 v[232:235], v187 offset:19456
	ds_read_b128 v[236:239], v187 offset:20480
	ds_read_b128 v[240:243], v187 offset:21504
	ds_read_b128 v[244:247], v187 offset:22528
	ds_read_b128 v[248:251], v187 offset:23552
	s_nop 15
	s_nop 15
	s_waitcnt lgkmcnt(0)
	s_barrier
	s_setprio 1
	v_mfma_f32_16x16x32_bf16 v[72:75], v[144:147], v[176:179], v[72:75]
	v_mfma_f32_16x16x32_bf16 v[76:79], v[152:155], v[176:179], v[76:79]
	v_mfma_f32_16x16x32_bf16 v[96:99], v[144:147], v[194:197], v[96:99]
	v_mfma_f32_16x16x32_bf16 v[100:103], v[152:155], v[194:197], v[100:103]
	v_mfma_f32_16x16x32_bf16 v[120:123], v[144:147], v[202:205], v[120:123]
	v_mfma_f32_16x16x32_bf16 v[124:127], v[152:155], v[202:205], v[124:127]
	v_mfma_f32_16x16x32_bf16 v[92:95], v[144:147], v[210:213], v[92:95]
	v_mfma_f32_16x16x32_bf16 v[84:87], v[152:155], v[210:213], v[84:87]
	v_mfma_f32_16x16x32_bf16 v[72:75], v[148:151], v[190:193], v[72:75]
	v_mfma_f32_16x16x32_bf16 v[76:79], v[156:159], v[190:193], v[76:79]
	v_mfma_f32_16x16x32_bf16 v[96:99], v[148:151], v[198:201], v[96:99]
	v_mfma_f32_16x16x32_bf16 v[100:103], v[156:159], v[198:201], v[100:103]
	v_mfma_f32_16x16x32_bf16 v[120:123], v[148:151], v[206:209], v[120:123]
	v_mfma_f32_16x16x32_bf16 v[124:127], v[156:159], v[206:209], v[124:127]
	v_mfma_f32_16x16x32_bf16 v[92:95], v[148:151], v[214:217], v[92:95]
	v_mfma_f32_16x16x32_bf16 v[84:87], v[156:159], v[214:217], v[84:87]
	s_setprio 0
	s_setprio 1
	v_mfma_f32_16x16x32_bf16 v[80:83], v[160:163], v[176:179], v[80:83]
	v_mfma_f32_16x16x32_bf16 v[88:91], v[168:171], v[176:179], v[88:91]
	v_mfma_f32_16x16x32_bf16 v[108:111], v[160:163], v[194:197], v[108:111]
	v_mfma_f32_16x16x32_bf16 v[112:115], v[168:171], v[194:197], v[112:115]
	v_mfma_f32_16x16x32_bf16 v[116:119], v[160:163], v[202:205], v[116:119]
	v_mfma_f32_16x16x32_bf16 v[104:107], v[168:171], v[202:205], v[104:107]
	v_mfma_f32_16x16x32_bf16 v[68:71], v[160:163], v[210:213], v[68:71]
	v_mfma_f32_16x16x32_bf16 v[64:67], v[168:171], v[210:213], v[64:67]
	v_mfma_f32_16x16x32_bf16 v[80:83], v[164:167], v[190:193], v[80:83]
	v_mfma_f32_16x16x32_bf16 v[88:91], v[172:175], v[190:193], v[88:91]
	v_mfma_f32_16x16x32_bf16 v[108:111], v[164:167], v[198:201], v[108:111]
	v_mfma_f32_16x16x32_bf16 v[112:115], v[172:175], v[198:201], v[112:115]
	v_mfma_f32_16x16x32_bf16 v[116:119], v[164:167], v[206:209], v[116:119]
	v_mfma_f32_16x16x32_bf16 v[104:107], v[172:175], v[206:209], v[104:107]
	v_mfma_f32_16x16x32_bf16 v[68:71], v[164:167], v[214:217], v[68:71]
	v_mfma_f32_16x16x32_bf16 v[64:67], v[172:175], v[214:217], v[64:67]
	s_setprio 0
	s_setprio 1
	v_mfma_f32_16x16x32_bf16 v[60:63], v[144:147], v[220:223], v[60:63]
	v_mfma_f32_16x16x32_bf16 v[56:59], v[152:155], v[220:223], v[56:59]
	v_mfma_f32_16x16x32_bf16 v[44:47], v[144:147], v[228:231], v[44:47]
	v_mfma_f32_16x16x32_bf16 v[40:43], v[152:155], v[228:231], v[40:43]
	v_mfma_f32_16x16x32_bf16 v[28:31], v[144:147], v[236:239], v[28:31]
	v_mfma_f32_16x16x32_bf16 v[24:27], v[152:155], v[236:239], v[24:27]
	v_mfma_f32_16x16x32_bf16 v[12:15], v[144:147], v[244:247], v[12:15]
	v_mfma_f32_16x16x32_bf16 v[8:11], v[152:155], v[244:247], v[8:11]
	v_mfma_f32_16x16x32_bf16 v[60:63], v[148:151], v[224:227], v[60:63]
	v_mfma_f32_16x16x32_bf16 v[56:59], v[156:159], v[224:227], v[56:59]
	v_mfma_f32_16x16x32_bf16 v[44:47], v[148:151], v[232:235], v[44:47]
	v_mfma_f32_16x16x32_bf16 v[40:43], v[156:159], v[232:235], v[40:43]
	v_mfma_f32_16x16x32_bf16 v[28:31], v[148:151], v[240:243], v[28:31]
	v_mfma_f32_16x16x32_bf16 v[24:27], v[156:159], v[240:243], v[24:27]
	v_mfma_f32_16x16x32_bf16 v[12:15], v[148:151], v[248:251], v[12:15]
	v_mfma_f32_16x16x32_bf16 v[8:11], v[156:159], v[248:251], v[8:11]
	s_setprio 0
	s_setprio 1
	v_mfma_f32_16x16x32_bf16 v[52:55], v[160:163], v[220:223], v[52:55]
	v_mfma_f32_16x16x32_bf16 v[48:51], v[168:171], v[220:223], v[48:51]
	v_mfma_f32_16x16x32_bf16 v[36:39], v[160:163], v[228:231], v[36:39]
	v_mfma_f32_16x16x32_bf16 v[32:35], v[168:171], v[228:231], v[32:35]
	v_mfma_f32_16x16x32_bf16 v[20:23], v[160:163], v[236:239], v[20:23]
	v_mfma_f32_16x16x32_bf16 v[16:19], v[168:171], v[236:239], v[16:19]
	v_mfma_f32_16x16x32_bf16 v[4:7], v[160:163], v[244:247], v[4:7]
	v_mfma_f32_16x16x32_bf16 v[0:3], v[168:171], v[244:247], v[0:3]
	v_mfma_f32_16x16x32_bf16 v[52:55], v[164:167], v[224:227], v[52:55]
	v_mfma_f32_16x16x32_bf16 v[48:51], v[172:175], v[224:227], v[48:51]
	v_mfma_f32_16x16x32_bf16 v[36:39], v[164:167], v[232:235], v[36:39]
	v_mfma_f32_16x16x32_bf16 v[32:35], v[172:175], v[232:235], v[32:35]
	v_mfma_f32_16x16x32_bf16 v[20:23], v[164:167], v[240:243], v[20:23]
	v_mfma_f32_16x16x32_bf16 v[16:19], v[172:175], v[240:243], v[16:19]
	v_mfma_f32_16x16x32_bf16 v[4:7], v[164:167], v[248:251], v[4:7]
	v_mfma_f32_16x16x32_bf16 v[0:3], v[172:175], v[248:251], v[0:3]
	s_setprio 0
	s_waitcnt vmcnt(0)
	s_barrier
	s_add_u32 vcc_lo, s28, 0x0
	s_addc_u32 vcc_hi, s29, 0
	s_add_i32 m0, s30, 0x2000
	s_nop 0
	global_load_lds_dwordx4 v132, vcc
	s_add_u32 vcc_lo, vcc_lo, 0x58000
	s_addc_u32 vcc_hi, vcc_hi, 0
	s_add_i32 m0, s30, 0x1000
	s_nop 0
	global_load_lds_dwordx4 v128, vcc
	s_add_u32 vcc_lo, vcc_lo, 0x108000
	s_addc_u32 vcc_hi, vcc_hi, 0
	s_add_i32 m0, s30, 0x6000
	s_nop 0
	global_load_lds_dwordx4 v132, vcc
	s_add_u32 vcc_lo, vcc_lo, 0x58000
	s_addc_u32 vcc_hi, vcc_hi, 0
	s_add_i32 m0, s30, 0x5000
	s_nop 0
	global_load_lds_dwordx4 v128, vcc
	s_add_u32 vcc_lo, s28, 0x80
	s_addc_u32 vcc_hi, s29, 0
	s_add_i32 m0, s30, 0x8000
	s_nop 0
	global_load_lds_dwordx4 v128, vcc
	s_sub_u32 vcc_lo, vcc_lo, 0x58000
	s_subb_u32 vcc_hi, vcc_hi, 0
	s_add_i32 m0, s30, 0x7000
	s_nop 0
	global_load_lds_dwordx4 v128, vcc
	s_add_u32 vcc_lo, vcc_lo, 0x1b8000
	s_addc_u32 vcc_hi, vcc_hi, 0
	s_add_i32 m0, s30, 0xc000
	s_nop 0
	global_load_lds_dwordx4 v128, vcc
	s_sub_u32 vcc_lo, vcc_lo, 0x58000
	s_subb_u32 vcc_hi, vcc_hi, 0
	s_add_i32 m0, s30, 0xb000
	s_nop 0
	global_load_lds_dwordx4 v128, vcc
	ds_read_b128 v[144:147], v185 offset:32768
	ds_read_b128 v[148:151], v185 offset:33792
	ds_read_b128 v[152:155], v185 offset:34816
	ds_read_b128 v[156:159], v185 offset:35840
	ds_read_b128 v[160:163], v186 offset:32768
	ds_read_b128 v[164:167], v186 offset:33792
	ds_read_b128 v[168:171], v186 offset:34816
	ds_read_b128 v[172:175], v186 offset:35840
	ds_read_b128 v[176:179], v187 offset:32768
	ds_read_b128 v[190:193], v187 offset:33792
	ds_read_b128 v[194:197], v187 offset:34816
	ds_read_b128 v[198:201], v187 offset:35840
	ds_read_b128 v[202:205], v187 offset:36864
	ds_read_b128 v[206:209], v187 offset:37888
	ds_read_b128 v[210:213], v187 offset:38912
	ds_read_b128 v[214:217], v187 offset:39936
	ds_read_b128 v[220:223], v187 offset:49152
	ds_read_b128 v[224:227], v187 offset:50176
	ds_read_b128 v[228:231], v187 offset:51200
	ds_read_b128 v[232:235], v187 offset:52224
	ds_read_b128 v[236:239], v187 offset:53248
	ds_read_b128 v[240:243], v187 offset:54272
	ds_read_b128 v[244:247], v187 offset:55296
	ds_read_b128 v[248:251], v187 offset:56320
	s_nop 15
	s_nop 15
	s_waitcnt lgkmcnt(0)
	s_barrier
	s_setprio 1
	v_mfma_f32_16x16x32_bf16 v[72:75], v[144:147], v[176:179], v[72:75]
	v_mfma_f32_16x16x32_bf16 v[76:79], v[152:155], v[176:179], v[76:79]
	v_mfma_f32_16x16x32_bf16 v[96:99], v[144:147], v[194:197], v[96:99]
	v_mfma_f32_16x16x32_bf16 v[100:103], v[152:155], v[194:197], v[100:103]
	v_mfma_f32_16x16x32_bf16 v[120:123], v[144:147], v[202:205], v[120:123]
	v_mfma_f32_16x16x32_bf16 v[124:127], v[152:155], v[202:205], v[124:127]
	v_mfma_f32_16x16x32_bf16 v[92:95], v[144:147], v[210:213], v[92:95]
	v_mfma_f32_16x16x32_bf16 v[84:87], v[152:155], v[210:213], v[84:87]
	v_mfma_f32_16x16x32_bf16 v[72:75], v[148:151], v[190:193], v[72:75]
	v_mfma_f32_16x16x32_bf16 v[76:79], v[156:159], v[190:193], v[76:79]
	v_mfma_f32_16x16x32_bf16 v[96:99], v[148:151], v[198:201], v[96:99]
	v_mfma_f32_16x16x32_bf16 v[100:103], v[156:159], v[198:201], v[100:103]
	v_mfma_f32_16x16x32_bf16 v[120:123], v[148:151], v[206:209], v[120:123]
	v_mfma_f32_16x16x32_bf16 v[124:127], v[156:159], v[206:209], v[124:127]
	v_mfma_f32_16x16x32_bf16 v[92:95], v[148:151], v[214:217], v[92:95]
	v_mfma_f32_16x16x32_bf16 v[84:87], v[156:159], v[214:217], v[84:87]
	s_setprio 0
	s_setprio 1
	v_mfma_f32_16x16x32_bf16 v[80:83], v[160:163], v[176:179], v[80:83]
	v_mfma_f32_16x16x32_bf16 v[88:91], v[168:171], v[176:179], v[88:91]
	v_mfma_f32_16x16x32_bf16 v[108:111], v[160:163], v[194:197], v[108:111]
	v_mfma_f32_16x16x32_bf16 v[112:115], v[168:171], v[194:197], v[112:115]
	v_mfma_f32_16x16x32_bf16 v[116:119], v[160:163], v[202:205], v[116:119]
	v_mfma_f32_16x16x32_bf16 v[104:107], v[168:171], v[202:205], v[104:107]
	v_mfma_f32_16x16x32_bf16 v[68:71], v[160:163], v[210:213], v[68:71]
	v_mfma_f32_16x16x32_bf16 v[64:67], v[168:171], v[210:213], v[64:67]
	v_mfma_f32_16x16x32_bf16 v[80:83], v[164:167], v[190:193], v[80:83]
	v_mfma_f32_16x16x32_bf16 v[88:91], v[172:175], v[190:193], v[88:91]
	v_mfma_f32_16x16x32_bf16 v[108:111], v[164:167], v[198:201], v[108:111]
	v_mfma_f32_16x16x32_bf16 v[112:115], v[172:175], v[198:201], v[112:115]
	v_mfma_f32_16x16x32_bf16 v[116:119], v[164:167], v[206:209], v[116:119]
	v_mfma_f32_16x16x32_bf16 v[104:107], v[172:175], v[206:209], v[104:107]
	v_mfma_f32_16x16x32_bf16 v[68:71], v[164:167], v[214:217], v[68:71]
	v_mfma_f32_16x16x32_bf16 v[64:67], v[172:175], v[214:217], v[64:67]
	s_setprio 0
	s_setprio 1
	v_mfma_f32_16x16x32_bf16 v[60:63], v[144:147], v[220:223], v[60:63]
	v_mfma_f32_16x16x32_bf16 v[56:59], v[152:155], v[220:223], v[56:59]
	v_mfma_f32_16x16x32_bf16 v[44:47], v[144:147], v[228:231], v[44:47]
	v_mfma_f32_16x16x32_bf16 v[40:43], v[152:155], v[228:231], v[40:43]
	v_mfma_f32_16x16x32_bf16 v[28:31], v[144:147], v[236:239], v[28:31]
	v_mfma_f32_16x16x32_bf16 v[24:27], v[152:155], v[236:239], v[24:27]
	v_mfma_f32_16x16x32_bf16 v[12:15], v[144:147], v[244:247], v[12:15]
	v_mfma_f32_16x16x32_bf16 v[8:11], v[152:155], v[244:247], v[8:11]
	v_mfma_f32_16x16x32_bf16 v[60:63], v[148:151], v[224:227], v[60:63]
	v_mfma_f32_16x16x32_bf16 v[56:59], v[156:159], v[224:227], v[56:59]
	v_mfma_f32_16x16x32_bf16 v[44:47], v[148:151], v[232:235], v[44:47]
	v_mfma_f32_16x16x32_bf16 v[40:43], v[156:159], v[232:235], v[40:43]
	v_mfma_f32_16x16x32_bf16 v[28:31], v[148:151], v[240:243], v[28:31]
	v_mfma_f32_16x16x32_bf16 v[24:27], v[156:159], v[240:243], v[24:27]
	v_mfma_f32_16x16x32_bf16 v[12:15], v[148:151], v[248:251], v[12:15]
	v_mfma_f32_16x16x32_bf16 v[8:11], v[156:159], v[248:251], v[8:11]
	s_setprio 0
	s_setprio 1
	v_mfma_f32_16x16x32_bf16 v[52:55], v[160:163], v[220:223], v[52:55]
	v_mfma_f32_16x16x32_bf16 v[48:51], v[168:171], v[220:223], v[48:51]
	v_mfma_f32_16x16x32_bf16 v[36:39], v[160:163], v[228:231], v[36:39]
	v_mfma_f32_16x16x32_bf16 v[32:35], v[168:171], v[228:231], v[32:35]
	v_mfma_f32_16x16x32_bf16 v[20:23], v[160:163], v[236:239], v[20:23]
	v_mfma_f32_16x16x32_bf16 v[16:19], v[168:171], v[236:239], v[16:19]
	v_mfma_f32_16x16x32_bf16 v[4:7], v[160:163], v[244:247], v[4:7]
	v_mfma_f32_16x16x32_bf16 v[0:3], v[168:171], v[244:247], v[0:3]
	v_mfma_f32_16x16x32_bf16 v[52:55], v[164:167], v[224:227], v[52:55]
	v_mfma_f32_16x16x32_bf16 v[48:51], v[172:175], v[224:227], v[48:51]
	v_mfma_f32_16x16x32_bf16 v[36:39], v[164:167], v[232:235], v[36:39]
	v_mfma_f32_16x16x32_bf16 v[32:35], v[172:175], v[232:235], v[32:35]
	v_mfma_f32_16x16x32_bf16 v[20:23], v[164:167], v[240:243], v[20:23]
	v_mfma_f32_16x16x32_bf16 v[16:19], v[172:175], v[240:243], v[16:19]
	v_mfma_f32_16x16x32_bf16 v[4:7], v[164:167], v[248:251], v[4:7]
	v_mfma_f32_16x16x32_bf16 v[0:3], v[172:175], v[248:251], v[0:3]
	s_setprio 0
	s_add_i32 s56, s56, 2
	s_add_u32 s46, s46, 0x100
	s_addc_u32 s47, s47, 0
	s_mov_b64 s[22:23], s[24:25]
	s_add_u32 s24, s22, 0x100
	s_addc_u32 s25, s23, 0
	s_cmpk_eq_i32 s56, 0x54
	s_cselect_b32 s29, s19, s25
	s_cselect_b32 s28, s18, s24
	s_cselect_b32 s27, s21, s47
	s_cselect_b32 s26, s20, s46
	s_cmpk_gt_u32 s56, 0x55
	s_waitcnt vmcnt(0)
	s_barrier
	s_cbranch_scc0 .Lk64_trail_p7
